# v10: v9 + removed 48 duplicate s_waitcnt lgkmcnt(0) (hipcc repeats the inline-asm wait after s_setprio 1) in the 8 GEMM K-loops
# speedup vs baseline: 1.0135x; 1.0135x over previous
.LBB0_237:
	ds_read_b128 v[128:131], v169
	ds_read_b128 v[152:155], v169 offset:1024
	ds_read_b128 v[156:159], v169 offset:2048
	ds_read_b128 v[160:163], v169 offset:3072
	s_add_u32 s20, s8, 0xfff80080
	s_addc_u32 s21, s9, -1
	s_cmp_eq_u32 s35, 28
	s_cselect_b32 s21, s1, s21
	s_cselect_b32 s20, s7, s20
	s_cselect_b32 s79, s22, s34
	s_cselect_b32 s78, s23, s33
	v_lshl_add_u64 v[164:165], s[8:9], 0, v[142:143]
	s_add_i32 m0, s12, 0xc000
	ds_read_b128 v[172:175], v170
	ds_read_b128 v[176:179], v170 offset:1024
	ds_read_b128 v[180:183], v170 offset:2048
	ds_read_b128 v[184:187], v170 offset:3072
	ds_read_b128 v[188:191], v170 offset:4096
	ds_read_b128 v[194:197], v170 offset:5120
	ds_read_b128 v[198:201], v170 offset:6144
	ds_read_b128 v[202:205], v170 offset:7168
	global_load_lds_dwordx4 v[164:165], off
	v_lshl_add_u64 v[164:165], s[8:9], 0, v[146:147]
	s_add_i32 m0, s12, 0xe000
	s_nop 0
	global_load_lds_dwordx4 v[164:165], off
	s_waitcnt lgkmcnt(8)
	s_barrier
	s_waitcnt lgkmcnt(0)
	s_setprio 1
	v_mfma_f32_16x16x32_bf16 v[124:127], v[128:131], v[172:175], v[124:127]
	v_mfma_f32_16x16x32_bf16 v[120:123], v[156:159], v[172:175], v[120:123]
	v_mfma_f32_16x16x32_bf16 v[108:111], v[128:131], v[180:183], v[108:111]
	v_mfma_f32_16x16x32_bf16 v[104:107], v[156:159], v[180:183], v[104:107]
	v_mfma_f32_16x16x32_bf16 v[92:95], v[128:131], v[188:191], v[92:95]
	v_mfma_f32_16x16x32_bf16 v[88:91], v[156:159], v[188:191], v[88:91]
	v_mfma_f32_16x16x32_bf16 v[76:79], v[128:131], v[198:201], v[76:79]
	v_mfma_f32_16x16x32_bf16 v[72:75], v[156:159], v[198:201], v[72:75]
	v_mfma_f32_16x16x32_bf16 v[124:127], v[152:155], v[176:179], v[124:127]
	v_mfma_f32_16x16x32_bf16 v[120:123], v[160:163], v[176:179], v[120:123]
	v_mfma_f32_16x16x32_bf16 v[108:111], v[152:155], v[184:187], v[108:111]
	v_mfma_f32_16x16x32_bf16 v[104:107], v[160:163], v[184:187], v[104:107]
	v_mfma_f32_16x16x32_bf16 v[92:95], v[152:155], v[194:197], v[92:95]
	v_mfma_f32_16x16x32_bf16 v[88:91], v[160:163], v[194:197], v[88:91]
	v_mfma_f32_16x16x32_bf16 v[76:79], v[152:155], v[202:205], v[76:79]
	v_mfma_f32_16x16x32_bf16 v[72:75], v[160:163], v[202:205], v[72:75]
	s_setprio 0
	s_barrier
	s_add_i32 s50, s82, s11
	v_lshl_add_u64 v[164:165], s[78:79], 0, v[134:135]
	s_mov_b32 m0, s50
	ds_read_b128 v[206:209], v171
	ds_read_b128 v[210:213], v171 offset:1024
	ds_read_b128 v[214:217], v171 offset:2048
	ds_read_b128 v[218:221], v171 offset:3072
	global_load_lds_dwordx4 v[164:165], off
	v_lshl_add_u64 v[222:223], s[78:79], 0, v[138:139]
	s_add_i32 m0, s50, 0x2000
	s_nop 0
	global_load_lds_dwordx4 v[222:223], off
	s_barrier
	s_waitcnt lgkmcnt(0)
	s_setprio 1
	v_mfma_f32_16x16x32_bf16 v[116:119], v[206:209], v[172:175], v[116:119]
	v_mfma_f32_16x16x32_bf16 v[112:115], v[214:217], v[172:175], v[112:115]
	v_mfma_f32_16x16x32_bf16 v[100:103], v[206:209], v[180:183], v[100:103]
	v_mfma_f32_16x16x32_bf16 v[96:99], v[214:217], v[180:183], v[96:99]
	v_mfma_f32_16x16x32_bf16 v[84:87], v[206:209], v[188:191], v[84:87]
	v_mfma_f32_16x16x32_bf16 v[80:83], v[214:217], v[188:191], v[80:83]
	v_mfma_f32_16x16x32_bf16 v[68:71], v[206:209], v[198:201], v[68:71]
	v_mfma_f32_16x16x32_bf16 v[64:67], v[214:217], v[198:201], v[64:67]
	v_mfma_f32_16x16x32_bf16 v[116:119], v[210:213], v[176:179], v[116:119]
	v_mfma_f32_16x16x32_bf16 v[112:115], v[218:221], v[176:179], v[112:115]
	v_mfma_f32_16x16x32_bf16 v[100:103], v[210:213], v[184:187], v[100:103]
	v_mfma_f32_16x16x32_bf16 v[96:99], v[218:221], v[184:187], v[96:99]
	v_mfma_f32_16x16x32_bf16 v[84:87], v[210:213], v[194:197], v[84:87]
	v_mfma_f32_16x16x32_bf16 v[80:83], v[218:221], v[194:197], v[80:83]
	v_mfma_f32_16x16x32_bf16 v[68:71], v[210:213], v[202:205], v[68:71]
	v_mfma_f32_16x16x32_bf16 v[64:67], v[218:221], v[202:205], v[64:67]
	s_setprio 0
	s_mov_b32 m0, s12
	v_lshl_add_u64 v[224:225], s[20:21], 0, v[132:133]
	s_barrier
	ds_read_b128 v[172:175], v170 offset:16384
	ds_read_b128 v[176:179], v170 offset:17408
	ds_read_b128 v[180:183], v170 offset:18432
	ds_read_b128 v[184:187], v170 offset:19456
	ds_read_b128 v[188:191], v170 offset:20480
	ds_read_b128 v[194:197], v170 offset:21504
	ds_read_b128 v[198:201], v170 offset:22528
	ds_read_b128 v[202:205], v170 offset:23552
	global_load_lds_dwordx4 v[224:225], off
	v_lshl_add_u64 v[226:227], s[20:21], 0, v[136:137]
	s_mov_b32 m0, s36
	s_nop 0
	global_load_lds_dwordx4 v[226:227], off
	s_barrier
	s_waitcnt lgkmcnt(0)
	s_setprio 1
	v_mfma_f32_16x16x32_bf16 v[60:63], v[128:131], v[172:175], v[60:63]
	v_mfma_f32_16x16x32_bf16 v[56:59], v[156:159], v[172:175], v[56:59]
	v_mfma_f32_16x16x32_bf16 v[44:47], v[128:131], v[180:183], v[44:47]
	v_mfma_f32_16x16x32_bf16 v[40:43], v[156:159], v[180:183], v[40:43]
	v_mfma_f32_16x16x32_bf16 v[28:31], v[128:131], v[188:191], v[28:31]
	v_mfma_f32_16x16x32_bf16 v[24:27], v[156:159], v[188:191], v[24:27]
	v_mfma_f32_16x16x32_bf16 v[12:15], v[128:131], v[198:201], v[12:15]
	v_mfma_f32_16x16x32_bf16 v[8:11], v[156:159], v[198:201], v[8:11]
	v_mfma_f32_16x16x32_bf16 v[60:63], v[152:155], v[176:179], v[60:63]
	v_mfma_f32_16x16x32_bf16 v[56:59], v[160:163], v[176:179], v[56:59]
	v_mfma_f32_16x16x32_bf16 v[44:47], v[152:155], v[184:187], v[44:47]
	v_mfma_f32_16x16x32_bf16 v[40:43], v[160:163], v[184:187], v[40:43]
	v_mfma_f32_16x16x32_bf16 v[28:31], v[152:155], v[194:197], v[28:31]
	v_mfma_f32_16x16x32_bf16 v[24:27], v[160:163], v[194:197], v[24:27]
	v_mfma_f32_16x16x32_bf16 v[12:15], v[152:155], v[202:205], v[12:15]
	v_mfma_f32_16x16x32_bf16 v[8:11], v[160:163], v[202:205], v[8:11]
	s_setprio 0
	s_barrier
	s_add_u32 s50, s78, 0x80000
	s_addc_u32 s51, s79, 0
	s_add_i32 s58, s84, s11
	v_lshl_add_u64 v[128:129], s[50:51], 0, v[134:135]
	s_mov_b32 m0, s58
	s_nop 0
	global_load_lds_dwordx4 v[128:129], off
	v_lshl_add_u64 v[128:129], s[50:51], 0, v[138:139]
	s_add_i32 m0, s58, 0x2000
	s_nop 0
	global_load_lds_dwordx4 v[128:129], off
	s_waitcnt vmcnt(6)
	s_barrier
	s_setprio 1
	v_mfma_f32_16x16x32_bf16 v[52:55], v[206:209], v[172:175], v[52:55]
	v_mfma_f32_16x16x32_bf16 v[48:51], v[214:217], v[172:175], v[48:51]
	v_mfma_f32_16x16x32_bf16 v[36:39], v[206:209], v[180:183], v[36:39]
	v_mfma_f32_16x16x32_bf16 v[32:35], v[214:217], v[180:183], v[32:35]
	v_mfma_f32_16x16x32_bf16 v[20:23], v[206:209], v[188:191], v[20:23]
	v_mfma_f32_16x16x32_bf16 v[16:19], v[214:217], v[188:191], v[16:19]
	v_mfma_f32_16x16x32_bf16 v[4:7], v[206:209], v[198:201], v[4:7]
	v_mfma_f32_16x16x32_bf16 v[0:3], v[214:217], v[198:201], v[0:3]
	v_mfma_f32_16x16x32_bf16 v[52:55], v[210:213], v[176:179], v[52:55]
	v_mfma_f32_16x16x32_bf16 v[48:51], v[218:221], v[176:179], v[48:51]
	v_mfma_f32_16x16x32_bf16 v[36:39], v[210:213], v[184:187], v[36:39]
	v_mfma_f32_16x16x32_bf16 v[32:35], v[218:221], v[184:187], v[32:35]
	v_mfma_f32_16x16x32_bf16 v[20:23], v[210:213], v[194:197], v[20:23]
	v_mfma_f32_16x16x32_bf16 v[16:19], v[218:221], v[194:197], v[16:19]
	v_mfma_f32_16x16x32_bf16 v[4:7], v[210:213], v[202:205], v[4:7]
	v_mfma_f32_16x16x32_bf16 v[0:3], v[218:221], v[202:205], v[0:3]
	s_setprio 0
	s_add_i32 s50, 0, 0x18000
	v_add_u32_e32 v140, s50, v167
	s_barrier
	ds_read_b128 v[128:131], v140
	ds_read_b128 v[152:155], v140 offset:1024
	ds_read_b128 v[156:159], v140 offset:2048
	ds_read_b128 v[160:163], v140 offset:3072
	s_add_u32 s20, s20, 0x80000
	s_addc_u32 s21, s21, 0
	s_mov_b32 m0, s37
	v_lshl_add_u64 v[206:207], s[20:21], 0, v[132:133]
	ds_read_b128 v[172:175], v170 offset:32768
	ds_read_b128 v[176:179], v170 offset:33792
	ds_read_b128 v[180:183], v170 offset:34816
	ds_read_b128 v[184:187], v170 offset:35840
	ds_read_b128 v[188:191], v170 offset:36864
	ds_read_b128 v[194:197], v170 offset:37888
	ds_read_b128 v[198:201], v170 offset:38912
	ds_read_b128 v[202:205], v170 offset:39936
	global_load_lds_dwordx4 v[206:207], off
	v_lshl_add_u64 v[206:207], s[20:21], 0, v[136:137]
	s_mov_b32 m0, s38
	s_nop 0
	global_load_lds_dwordx4 v[206:207], off
	s_waitcnt lgkmcnt(8)
	s_barrier
	s_waitcnt lgkmcnt(0)
	s_setprio 1
	v_mfma_f32_16x16x32_bf16 v[124:127], v[128:131], v[172:175], v[124:127]
	v_mfma_f32_16x16x32_bf16 v[120:123], v[156:159], v[172:175], v[120:123]
	v_mfma_f32_16x16x32_bf16 v[108:111], v[128:131], v[180:183], v[108:111]
	v_mfma_f32_16x16x32_bf16 v[104:107], v[156:159], v[180:183], v[104:107]
	v_mfma_f32_16x16x32_bf16 v[92:95], v[128:131], v[188:191], v[92:95]
	v_mfma_f32_16x16x32_bf16 v[88:91], v[156:159], v[188:191], v[88:91]
	v_mfma_f32_16x16x32_bf16 v[76:79], v[128:131], v[198:201], v[76:79]
	v_mfma_f32_16x16x32_bf16 v[72:75], v[156:159], v[198:201], v[72:75]
	v_mfma_f32_16x16x32_bf16 v[124:127], v[152:155], v[176:179], v[124:127]
	v_mfma_f32_16x16x32_bf16 v[120:123], v[160:163], v[176:179], v[120:123]
	v_mfma_f32_16x16x32_bf16 v[108:111], v[152:155], v[184:187], v[108:111]
	v_mfma_f32_16x16x32_bf16 v[104:107], v[160:163], v[184:187], v[104:107]
	v_mfma_f32_16x16x32_bf16 v[92:95], v[152:155], v[194:197], v[92:95]
	v_mfma_f32_16x16x32_bf16 v[88:91], v[160:163], v[194:197], v[88:91]
	v_mfma_f32_16x16x32_bf16 v[76:79], v[152:155], v[202:205], v[76:79]
	v_mfma_f32_16x16x32_bf16 v[72:75], v[160:163], v[202:205], v[72:75]
	s_setprio 0
	s_barrier
	s_add_i32 s51, 0, 0x1c000
	s_add_i32 s20, s50, s11
	v_add_u32_e32 v140, s51, v167
	v_lshl_add_u64 v[164:165], v[164:165], 0, s[18:19]
	s_mov_b32 m0, s20
	ds_read_b128 v[206:209], v140
	ds_read_b128 v[210:213], v140 offset:1024
	ds_read_b128 v[214:217], v140 offset:2048
	ds_read_b128 v[218:221], v140 offset:3072
	global_load_lds_dwordx4 v[164:165], off
	v_lshl_add_u64 v[164:165], v[222:223], 0, s[18:19]
	s_add_i32 m0, s20, 0x2000
	s_nop 0
	global_load_lds_dwordx4 v[164:165], off
	s_barrier
	s_waitcnt lgkmcnt(0)
	s_setprio 1
	v_mfma_f32_16x16x32_bf16 v[116:119], v[206:209], v[172:175], v[116:119]
	v_mfma_f32_16x16x32_bf16 v[112:115], v[214:217], v[172:175], v[112:115]
	v_mfma_f32_16x16x32_bf16 v[100:103], v[206:209], v[180:183], v[100:103]
	v_mfma_f32_16x16x32_bf16 v[96:99], v[214:217], v[180:183], v[96:99]
	v_mfma_f32_16x16x32_bf16 v[84:87], v[206:209], v[188:191], v[84:87]
	v_mfma_f32_16x16x32_bf16 v[80:83], v[214:217], v[188:191], v[80:83]
	v_mfma_f32_16x16x32_bf16 v[68:71], v[206:209], v[198:201], v[68:71]
	v_mfma_f32_16x16x32_bf16 v[64:67], v[214:217], v[198:201], v[64:67]
	v_mfma_f32_16x16x32_bf16 v[116:119], v[210:213], v[176:179], v[116:119]
	v_mfma_f32_16x16x32_bf16 v[112:115], v[218:221], v[176:179], v[112:115]
	v_mfma_f32_16x16x32_bf16 v[100:103], v[210:213], v[184:187], v[100:103]
	v_mfma_f32_16x16x32_bf16 v[96:99], v[218:221], v[184:187], v[96:99]
	v_mfma_f32_16x16x32_bf16 v[84:87], v[210:213], v[194:197], v[84:87]
	v_mfma_f32_16x16x32_bf16 v[80:83], v[218:221], v[194:197], v[80:83]
	v_mfma_f32_16x16x32_bf16 v[68:71], v[210:213], v[202:205], v[68:71]
	v_mfma_f32_16x16x32_bf16 v[64:67], v[218:221], v[202:205], v[64:67]
	s_setprio 0
	s_mov_b32 m0, s57
	v_lshl_add_u64 v[164:165], v[224:225], 0, s[18:19]
	s_barrier
	ds_read_b128 v[172:175], v170 offset:49152
	ds_read_b128 v[176:179], v170 offset:50176
	ds_read_b128 v[180:183], v170 offset:51200
	ds_read_b128 v[184:187], v170 offset:52224
	ds_read_b128 v[188:191], v170 offset:53248
	ds_read_b128 v[194:197], v170 offset:54272
	ds_read_b128 v[198:201], v170 offset:55296
	ds_read_b128 v[202:205], v170 offset:56320
	global_load_lds_dwordx4 v[164:165], off
	v_lshl_add_u64 v[164:165], v[226:227], 0, s[18:19]
	s_mov_b32 m0, s80
	s_nop 0
	global_load_lds_dwordx4 v[164:165], off
	s_barrier
	s_waitcnt lgkmcnt(0)
	s_setprio 1
	v_mfma_f32_16x16x32_bf16 v[60:63], v[128:131], v[172:175], v[60:63]
	v_mfma_f32_16x16x32_bf16 v[56:59], v[156:159], v[172:175], v[56:59]
	v_mfma_f32_16x16x32_bf16 v[44:47], v[128:131], v[180:183], v[44:47]
	v_mfma_f32_16x16x32_bf16 v[40:43], v[156:159], v[180:183], v[40:43]
	v_mfma_f32_16x16x32_bf16 v[28:31], v[128:131], v[188:191], v[28:31]
	v_mfma_f32_16x16x32_bf16 v[24:27], v[156:159], v[188:191], v[24:27]
	v_mfma_f32_16x16x32_bf16 v[12:15], v[128:131], v[198:201], v[12:15]
	v_mfma_f32_16x16x32_bf16 v[8:11], v[156:159], v[198:201], v[8:11]
	v_mfma_f32_16x16x32_bf16 v[60:63], v[152:155], v[176:179], v[60:63]
	v_mfma_f32_16x16x32_bf16 v[56:59], v[160:163], v[176:179], v[56:59]
	v_mfma_f32_16x16x32_bf16 v[44:47], v[152:155], v[184:187], v[44:47]
	v_mfma_f32_16x16x32_bf16 v[40:43], v[160:163], v[184:187], v[40:43]
	v_mfma_f32_16x16x32_bf16 v[28:31], v[152:155], v[194:197], v[28:31]
	v_mfma_f32_16x16x32_bf16 v[24:27], v[160:163], v[194:197], v[24:27]
	v_mfma_f32_16x16x32_bf16 v[12:15], v[152:155], v[202:205], v[12:15]
	v_mfma_f32_16x16x32_bf16 v[8:11], v[160:163], v[202:205], v[8:11]
	s_setprio 0
	s_barrier
	s_add_u32 s20, s78, 0x80080
	s_addc_u32 s21, s79, 0
	s_add_i32 s50, s51, s11
	v_lshl_add_u64 v[128:129], s[20:21], 0, v[134:135]
	s_mov_b32 m0, s50
	s_nop 0
	global_load_lds_dwordx4 v[128:129], off
	v_lshl_add_u64 v[128:129], s[20:21], 0, v[138:139]
	s_add_i32 m0, s50, 0x2000
	s_nop 0
	global_load_lds_dwordx4 v[128:129], off
	s_waitcnt vmcnt(6)
	s_barrier
	s_setprio 1
	v_mfma_f32_16x16x32_bf16 v[52:55], v[206:209], v[172:175], v[52:55]
	v_mfma_f32_16x16x32_bf16 v[48:51], v[214:217], v[172:175], v[48:51]
	v_mfma_f32_16x16x32_bf16 v[36:39], v[206:209], v[180:183], v[36:39]
	v_mfma_f32_16x16x32_bf16 v[32:35], v[214:217], v[180:183], v[32:35]
	v_mfma_f32_16x16x32_bf16 v[20:23], v[206:209], v[188:191], v[20:23]
	v_mfma_f32_16x16x32_bf16 v[16:19], v[214:217], v[188:191], v[16:19]
	v_mfma_f32_16x16x32_bf16 v[4:7], v[206:209], v[198:201], v[4:7]
	v_mfma_f32_16x16x32_bf16 v[0:3], v[214:217], v[198:201], v[0:3]
	v_mfma_f32_16x16x32_bf16 v[52:55], v[210:213], v[176:179], v[52:55]
	v_mfma_f32_16x16x32_bf16 v[48:51], v[218:221], v[176:179], v[48:51]
	v_mfma_f32_16x16x32_bf16 v[36:39], v[210:213], v[184:187], v[36:39]
	v_mfma_f32_16x16x32_bf16 v[32:35], v[218:221], v[184:187], v[32:35]
	v_mfma_f32_16x16x32_bf16 v[20:23], v[210:213], v[194:197], v[20:23]
	v_mfma_f32_16x16x32_bf16 v[16:19], v[218:221], v[194:197], v[16:19]
	v_mfma_f32_16x16x32_bf16 v[4:7], v[210:213], v[202:205], v[4:7]
	v_mfma_f32_16x16x32_bf16 v[0:3], v[218:221], v[202:205], v[0:3]
	s_setprio 0
	s_add_i32 s35, s35, 2
	s_add_u32 s8, s8, 0x100
	s_addc_u32 s9, s9, 0
	s_add_u32 s33, s33, 0x100
	s_addc_u32 s34, s34, 0
	s_cmp_gt_u32 s35, 29
	s_barrier
	s_cbranch_scc0 .LBB0_237
	s_lshl_b32 s65, s6, 8
	v_lshl_add_u32 v154, s0, 8, v166
	v_or_b32_e32 v152, s65, v168
	v_ashrrev_i32_e32 v155, 31, v154
	v_lshlrev_b64 v[162:163], 7, v[154:155]
	v_lshlrev_b64 v[160:161], 11, v[154:155]
	v_mad_i64_i32 v[158:159], s[0:1], v154, s85, 0
	v_cmp_gt_i32_e64 s[8:9], s39, v154
	v_lshlrev_b64 v[156:157], 12, v[154:155]
	v_cvt_pk_bf16_f32 v128, v124, v125
	v_cvt_pk_bf16_f32 v129, v126, v127
	v_cvt_pk_bf16_f32 v130, v120, v121
	v_cvt_pk_bf16_f32 v131, v122, v123
	v_cmp_lt_i32_e64 s[6:7], s86, v152
	s_and_saveexec_b64 s[0:1], s[6:7]
	s_xor_b64 s[0:1], exec, s[0:1]
	s_cbranch_execz .LBB0_255
	s_cmpk_gt_u32 s65, 0xbff
	s_mov_b64 s[20:21], -1
	s_cbranch_scc0 .LBB0_251
	s_cmpk_gt_u32 s65, 0x17ff
	s_cbranch_scc0 .LBB0_248
	s_cmpk_gt_u32 s65, 0x1bff
	s_cbranch_scc0 .LBB0_245
	v_cmp_gt_u32_e32 vcc, s87, v152
	s_and_saveexec_b64 s[20:21], vcc
	s_cbranch_execz .LBB0_244
	v_readlane_b32 s22, v254, 24
	v_readlane_b32 s23, v254, 25
	v_mov_b32_e32 v153, v141
	s_nop 0
	v_lshl_add_u64 v[164:165], s[22:23], 0, v[162:163]
	v_lshl_add_u64 v[164:165], v[152:153], 2, v[164:165]
	v_add_co_u32_e32 v172, vcc, 0xffff9000, v164
	s_nop 1
	v_addc_co_u32_e32 v173, vcc, -1, v165, vcc
	v_add_co_u32_e32 v164, vcc, 0xffffa000, v164
	global_store_dwordx4 v[172:173], v[124:127], off
	s_nop 0
	v_addc_co_u32_e32 v165, vcc, -1, v165, vcc
	global_store_dwordx4 v[164:165], v[120:123], off offset:-4080

.LBB0_912:
	ds_read_b128 v[150:153], v161
	ds_read_b128 v[154:157], v161 offset:1024
	ds_read_b128 v[164:167], v161 offset:2048
	ds_read_b128 v[168:171], v161 offset:3072
	s_add_u32 s20, s48, 0xfff80080
	s_addc_u32 s21, s49, -1
	s_cmp_eq_u32 s47, 28
	s_cselect_b32 s21, s17, s21
	s_cselect_b32 s20, s33, s20
	s_cselect_b32 s51, s15, s45
	s_cselect_b32 s50, s34, s35
	v_lshl_add_u64 v[208:209], s[48:49], 0, v[138:139]
	s_add_i32 m0, s36, 0xc000
	ds_read_b128 v[172:175], v162
	ds_read_b128 v[176:179], v162 offset:1024
	ds_read_b128 v[180:183], v162 offset:2048
	ds_read_b128 v[184:187], v162 offset:3072
	ds_read_b128 v[188:191], v162 offset:4096
	ds_read_b128 v[196:199], v162 offset:5120
	ds_read_b128 v[200:203], v162 offset:6144
	ds_read_b128 v[204:207], v162 offset:7168
	global_load_lds_dwordx4 v[208:209], off
	v_lshl_add_u64 v[208:209], s[48:49], 0, v[140:141]
	s_add_i32 m0, s36, 0xe000
	s_nop 0
	global_load_lds_dwordx4 v[208:209], off
	s_waitcnt lgkmcnt(8)
	s_barrier
	s_waitcnt lgkmcnt(0)
	s_setprio 1
	v_mfma_f32_16x16x32_bf16 v[124:127], v[150:153], v[172:175], v[124:127]
	v_mfma_f32_16x16x32_bf16 v[120:123], v[164:167], v[172:175], v[120:123]
	v_mfma_f32_16x16x32_bf16 v[108:111], v[150:153], v[180:183], v[108:111]
	v_mfma_f32_16x16x32_bf16 v[104:107], v[164:167], v[180:183], v[104:107]
	v_mfma_f32_16x16x32_bf16 v[92:95], v[150:153], v[188:191], v[92:95]
	v_mfma_f32_16x16x32_bf16 v[88:91], v[164:167], v[188:191], v[88:91]
	v_mfma_f32_16x16x32_bf16 v[76:79], v[150:153], v[200:203], v[76:79]
	v_mfma_f32_16x16x32_bf16 v[72:75], v[164:167], v[200:203], v[72:75]
	v_mfma_f32_16x16x32_bf16 v[124:127], v[154:157], v[176:179], v[124:127]
	v_mfma_f32_16x16x32_bf16 v[120:123], v[168:171], v[176:179], v[120:123]
	v_mfma_f32_16x16x32_bf16 v[108:111], v[154:157], v[184:187], v[108:111]
	v_mfma_f32_16x16x32_bf16 v[104:107], v[168:171], v[184:187], v[104:107]
	v_mfma_f32_16x16x32_bf16 v[92:95], v[154:157], v[196:199], v[92:95]
	v_mfma_f32_16x16x32_bf16 v[88:91], v[168:171], v[196:199], v[88:91]
	v_mfma_f32_16x16x32_bf16 v[76:79], v[154:157], v[204:207], v[76:79]
	v_mfma_f32_16x16x32_bf16 v[72:75], v[168:171], v[204:207], v[72:75]
	s_setprio 0
	s_barrier
	s_add_i32 s65, s62, s23
	v_lshl_add_u64 v[224:225], s[50:51], 0, v[130:131]
	s_mov_b32 m0, s65
	ds_read_b128 v[208:211], v163
	ds_read_b128 v[212:215], v163 offset:1024
	ds_read_b128 v[216:219], v163 offset:2048
	ds_read_b128 v[220:223], v163 offset:3072
	global_load_lds_dwordx4 v[224:225], off
	v_lshl_add_u64 v[226:227], s[50:51], 0, v[134:135]
	s_add_i32 m0, s65, 0x2000
	s_nop 0
	global_load_lds_dwordx4 v[226:227], off
	s_barrier
	s_waitcnt lgkmcnt(0)
	s_setprio 1
	v_mfma_f32_16x16x32_bf16 v[116:119], v[208:211], v[172:175], v[116:119]
	v_mfma_f32_16x16x32_bf16 v[112:115], v[216:219], v[172:175], v[112:115]
	v_mfma_f32_16x16x32_bf16 v[100:103], v[208:211], v[180:183], v[100:103]
	v_mfma_f32_16x16x32_bf16 v[96:99], v[216:219], v[180:183], v[96:99]
	v_mfma_f32_16x16x32_bf16 v[84:87], v[208:211], v[188:191], v[84:87]
	v_mfma_f32_16x16x32_bf16 v[80:83], v[216:219], v[188:191], v[80:83]
	v_mfma_f32_16x16x32_bf16 v[68:71], v[208:211], v[200:203], v[68:71]
	v_mfma_f32_16x16x32_bf16 v[64:67], v[216:219], v[200:203], v[64:67]
	v_mfma_f32_16x16x32_bf16 v[116:119], v[212:215], v[176:179], v[116:119]
	v_mfma_f32_16x16x32_bf16 v[112:115], v[220:223], v[176:179], v[112:115]
	v_mfma_f32_16x16x32_bf16 v[100:103], v[212:215], v[184:187], v[100:103]
	v_mfma_f32_16x16x32_bf16 v[96:99], v[220:223], v[184:187], v[96:99]
	v_mfma_f32_16x16x32_bf16 v[84:87], v[212:215], v[196:199], v[84:87]
	v_mfma_f32_16x16x32_bf16 v[80:83], v[220:223], v[196:199], v[80:83]
	v_mfma_f32_16x16x32_bf16 v[68:71], v[212:215], v[204:207], v[68:71]
	v_mfma_f32_16x16x32_bf16 v[64:67], v[220:223], v[204:207], v[64:67]
	s_setprio 0
	s_mov_b32 m0, s36
	v_lshl_add_u64 v[228:229], s[20:21], 0, v[128:129]
	s_barrier
	ds_read_b128 v[172:175], v162 offset:16384
	ds_read_b128 v[176:179], v162 offset:17408
	ds_read_b128 v[180:183], v162 offset:18432
	ds_read_b128 v[184:187], v162 offset:19456
	ds_read_b128 v[188:191], v162 offset:20480
	ds_read_b128 v[196:199], v162 offset:21504
	ds_read_b128 v[200:203], v162 offset:22528
	ds_read_b128 v[204:207], v162 offset:23552
	global_load_lds_dwordx4 v[228:229], off
	v_lshl_add_u64 v[230:231], s[20:21], 0, v[132:133]
	s_mov_b32 m0, s37
	s_nop 0
	global_load_lds_dwordx4 v[230:231], off
	s_barrier
	s_waitcnt lgkmcnt(0)
	s_setprio 1
	v_mfma_f32_16x16x32_bf16 v[60:63], v[150:153], v[172:175], v[60:63]
	v_mfma_f32_16x16x32_bf16 v[56:59], v[164:167], v[172:175], v[56:59]
	v_mfma_f32_16x16x32_bf16 v[44:47], v[150:153], v[180:183], v[44:47]
	v_mfma_f32_16x16x32_bf16 v[40:43], v[164:167], v[180:183], v[40:43]
	v_mfma_f32_16x16x32_bf16 v[28:31], v[150:153], v[188:191], v[28:31]
	v_mfma_f32_16x16x32_bf16 v[24:27], v[164:167], v[188:191], v[24:27]
	v_mfma_f32_16x16x32_bf16 v[12:15], v[150:153], v[200:203], v[12:15]
	v_mfma_f32_16x16x32_bf16 v[8:11], v[164:167], v[200:203], v[8:11]
	v_mfma_f32_16x16x32_bf16 v[60:63], v[154:157], v[176:179], v[60:63]
	v_mfma_f32_16x16x32_bf16 v[56:59], v[168:171], v[176:179], v[56:59]
	v_mfma_f32_16x16x32_bf16 v[44:47], v[154:157], v[184:187], v[44:47]
	v_mfma_f32_16x16x32_bf16 v[40:43], v[168:171], v[184:187], v[40:43]
	v_mfma_f32_16x16x32_bf16 v[28:31], v[154:157], v[196:199], v[28:31]
	v_mfma_f32_16x16x32_bf16 v[24:27], v[168:171], v[196:199], v[24:27]
	v_mfma_f32_16x16x32_bf16 v[12:15], v[154:157], v[204:207], v[12:15]
	v_mfma_f32_16x16x32_bf16 v[8:11], v[168:171], v[204:207], v[8:11]
	s_setprio 0
	s_barrier
	s_add_u32 s66, s50, 0x80000
	s_addc_u32 s67, s51, 0
	s_add_i32 s65, s63, s23
	v_lshl_add_u64 v[150:151], s[66:67], 0, v[130:131]
	s_mov_b32 m0, s65
	s_nop 0
	global_load_lds_dwordx4 v[150:151], off
	v_lshl_add_u64 v[150:151], s[66:67], 0, v[134:135]
	s_add_i32 m0, s65, 0x2000
	s_nop 0
	global_load_lds_dwordx4 v[150:151], off
	s_waitcnt vmcnt(6)
	s_barrier
	s_setprio 1
	v_mfma_f32_16x16x32_bf16 v[52:55], v[208:211], v[172:175], v[52:55]
	v_mfma_f32_16x16x32_bf16 v[48:51], v[216:219], v[172:175], v[48:51]
	v_mfma_f32_16x16x32_bf16 v[36:39], v[208:211], v[180:183], v[36:39]
	v_mfma_f32_16x16x32_bf16 v[32:35], v[216:219], v[180:183], v[32:35]
	v_mfma_f32_16x16x32_bf16 v[20:23], v[208:211], v[188:191], v[20:23]
	v_mfma_f32_16x16x32_bf16 v[16:19], v[216:219], v[188:191], v[16:19]
	v_mfma_f32_16x16x32_bf16 v[4:7], v[208:211], v[200:203], v[4:7]
	v_mfma_f32_16x16x32_bf16 v[0:3], v[216:219], v[200:203], v[0:3]
	v_mfma_f32_16x16x32_bf16 v[52:55], v[212:215], v[176:179], v[52:55]
	v_mfma_f32_16x16x32_bf16 v[48:51], v[220:223], v[176:179], v[48:51]
	v_mfma_f32_16x16x32_bf16 v[36:39], v[212:215], v[184:187], v[36:39]
	v_mfma_f32_16x16x32_bf16 v[32:35], v[220:223], v[184:187], v[32:35]
	v_mfma_f32_16x16x32_bf16 v[20:23], v[212:215], v[196:199], v[20:23]
	v_mfma_f32_16x16x32_bf16 v[16:19], v[220:223], v[196:199], v[16:19]
	v_mfma_f32_16x16x32_bf16 v[4:7], v[212:215], v[204:207], v[4:7]
	v_mfma_f32_16x16x32_bf16 v[0:3], v[220:223], v[204:207], v[0:3]
	s_setprio 0
	s_add_i32 s65, 0, 0x18000
	v_add_u32_e32 v136, s65, v158
	s_barrier
	ds_read_b128 v[150:153], v136
	ds_read_b128 v[154:157], v136 offset:1024
	ds_read_b128 v[164:167], v136 offset:2048
	ds_read_b128 v[168:171], v136 offset:3072
	s_add_u32 s20, s20, 0x80000
	s_addc_u32 s21, s21, 0
	s_mov_b32 m0, s38
	v_lshl_add_u64 v[208:209], s[20:21], 0, v[128:129]
	ds_read_b128 v[172:175], v162 offset:32768
	ds_read_b128 v[176:179], v162 offset:33792
	ds_read_b128 v[180:183], v162 offset:34816
	ds_read_b128 v[184:187], v162 offset:35840
	ds_read_b128 v[188:191], v162 offset:36864
	ds_read_b128 v[196:199], v162 offset:37888
	ds_read_b128 v[200:203], v162 offset:38912
	ds_read_b128 v[204:207], v162 offset:39936
	global_load_lds_dwordx4 v[208:209], off
	v_lshl_add_u64 v[208:209], s[20:21], 0, v[132:133]
	s_mov_b32 m0, s39
	s_nop 0
	global_load_lds_dwordx4 v[208:209], off
	s_waitcnt lgkmcnt(8)
	s_barrier
	s_waitcnt lgkmcnt(0)
	s_setprio 1
	v_mfma_f32_16x16x32_bf16 v[124:127], v[150:153], v[172:175], v[124:127]
	v_mfma_f32_16x16x32_bf16 v[120:123], v[164:167], v[172:175], v[120:123]
	v_mfma_f32_16x16x32_bf16 v[108:111], v[150:153], v[180:183], v[108:111]
	v_mfma_f32_16x16x32_bf16 v[104:107], v[164:167], v[180:183], v[104:107]
	v_mfma_f32_16x16x32_bf16 v[92:95], v[150:153], v[188:191], v[92:95]
	v_mfma_f32_16x16x32_bf16 v[88:91], v[164:167], v[188:191], v[88:91]
	v_mfma_f32_16x16x32_bf16 v[76:79], v[150:153], v[200:203], v[76:79]
	v_mfma_f32_16x16x32_bf16 v[72:75], v[164:167], v[200:203], v[72:75]
	v_mfma_f32_16x16x32_bf16 v[124:127], v[154:157], v[176:179], v[124:127]
	v_mfma_f32_16x16x32_bf16 v[120:123], v[168:171], v[176:179], v[120:123]
	v_mfma_f32_16x16x32_bf16 v[108:111], v[154:157], v[184:187], v[108:111]
	v_mfma_f32_16x16x32_bf16 v[104:107], v[168:171], v[184:187], v[104:107]
	v_mfma_f32_16x16x32_bf16 v[92:95], v[154:157], v[196:199], v[92:95]
	v_mfma_f32_16x16x32_bf16 v[88:91], v[168:171], v[196:199], v[88:91]
	v_mfma_f32_16x16x32_bf16 v[76:79], v[154:157], v[204:207], v[76:79]
	v_mfma_f32_16x16x32_bf16 v[72:75], v[168:171], v[204:207], v[72:75]
	s_setprio 0
	s_barrier
	s_add_i32 s66, 0, 0x1c000
	s_add_i32 s20, s65, s23
	v_add_u32_e32 v136, s66, v158
	v_lshl_add_u64 v[224:225], v[224:225], 0, s[10:11]
	s_mov_b32 m0, s20
	ds_read_b128 v[208:211], v136
	ds_read_b128 v[212:215], v136 offset:1024
	ds_read_b128 v[216:219], v136 offset:2048
	ds_read_b128 v[220:223], v136 offset:3072
	global_load_lds_dwordx4 v[224:225], off
	v_lshl_add_u64 v[224:225], v[226:227], 0, s[10:11]
	s_add_i32 m0, s20, 0x2000
	s_nop 0
	global_load_lds_dwordx4 v[224:225], off
	s_barrier
	s_waitcnt lgkmcnt(0)
	s_setprio 1
	v_mfma_f32_16x16x32_bf16 v[116:119], v[208:211], v[172:175], v[116:119]
	v_mfma_f32_16x16x32_bf16 v[112:115], v[216:219], v[172:175], v[112:115]
	v_mfma_f32_16x16x32_bf16 v[100:103], v[208:211], v[180:183], v[100:103]
	v_mfma_f32_16x16x32_bf16 v[96:99], v[216:219], v[180:183], v[96:99]
	v_mfma_f32_16x16x32_bf16 v[84:87], v[208:211], v[188:191], v[84:87]
	v_mfma_f32_16x16x32_bf16 v[80:83], v[216:219], v[188:191], v[80:83]
	v_mfma_f32_16x16x32_bf16 v[68:71], v[208:211], v[200:203], v[68:71]
	v_mfma_f32_16x16x32_bf16 v[64:67], v[216:219], v[200:203], v[64:67]
	v_mfma_f32_16x16x32_bf16 v[116:119], v[212:215], v[176:179], v[116:119]
	v_mfma_f32_16x16x32_bf16 v[112:115], v[220:223], v[176:179], v[112:115]
	v_mfma_f32_16x16x32_bf16 v[100:103], v[212:215], v[184:187], v[100:103]
	v_mfma_f32_16x16x32_bf16 v[96:99], v[220:223], v[184:187], v[96:99]
	v_mfma_f32_16x16x32_bf16 v[84:87], v[212:215], v[196:199], v[84:87]
	v_mfma_f32_16x16x32_bf16 v[80:83], v[220:223], v[196:199], v[80:83]
	v_mfma_f32_16x16x32_bf16 v[68:71], v[212:215], v[204:207], v[68:71]
	v_mfma_f32_16x16x32_bf16 v[64:67], v[220:223], v[204:207], v[64:67]
	s_setprio 0
	s_mov_b32 m0, s58
	v_lshl_add_u64 v[224:225], v[228:229], 0, s[10:11]
	s_barrier
	ds_read_b128 v[172:175], v162 offset:49152
	ds_read_b128 v[176:179], v162 offset:50176
	ds_read_b128 v[180:183], v162 offset:51200
	ds_read_b128 v[184:187], v162 offset:52224
	ds_read_b128 v[188:191], v162 offset:53248
	ds_read_b128 v[196:199], v162 offset:54272
	ds_read_b128 v[200:203], v162 offset:55296
	ds_read_b128 v[204:207], v162 offset:56320
	global_load_lds_dwordx4 v[224:225], off
	v_lshl_add_u64 v[224:225], v[230:231], 0, s[10:11]
	s_mov_b32 m0, s59
	s_nop 0
	global_load_lds_dwordx4 v[224:225], off
	s_barrier
	s_waitcnt lgkmcnt(0)
	s_setprio 1
	v_mfma_f32_16x16x32_bf16 v[60:63], v[150:153], v[172:175], v[60:63]
	v_mfma_f32_16x16x32_bf16 v[56:59], v[164:167], v[172:175], v[56:59]
	v_mfma_f32_16x16x32_bf16 v[44:47], v[150:153], v[180:183], v[44:47]
	v_mfma_f32_16x16x32_bf16 v[40:43], v[164:167], v[180:183], v[40:43]
	v_mfma_f32_16x16x32_bf16 v[28:31], v[150:153], v[188:191], v[28:31]
	v_mfma_f32_16x16x32_bf16 v[24:27], v[164:167], v[188:191], v[24:27]
	v_mfma_f32_16x16x32_bf16 v[12:15], v[150:153], v[200:203], v[12:15]
	v_mfma_f32_16x16x32_bf16 v[8:11], v[164:167], v[200:203], v[8:11]
	v_mfma_f32_16x16x32_bf16 v[60:63], v[154:157], v[176:179], v[60:63]
	v_mfma_f32_16x16x32_bf16 v[56:59], v[168:171], v[176:179], v[56:59]
	v_mfma_f32_16x16x32_bf16 v[44:47], v[154:157], v[184:187], v[44:47]
	v_mfma_f32_16x16x32_bf16 v[40:43], v[168:171], v[184:187], v[40:43]
	v_mfma_f32_16x16x32_bf16 v[28:31], v[154:157], v[196:199], v[28:31]
	v_mfma_f32_16x16x32_bf16 v[24:27], v[168:171], v[196:199], v[24:27]
	v_mfma_f32_16x16x32_bf16 v[12:15], v[154:157], v[204:207], v[12:15]
	v_mfma_f32_16x16x32_bf16 v[8:11], v[168:171], v[204:207], v[8:11]
	s_setprio 0
	s_barrier
	s_add_u32 s20, s50, 0x80080
	s_addc_u32 s21, s51, 0
	s_add_i32 s50, s66, s23
	v_lshl_add_u64 v[150:151], s[20:21], 0, v[130:131]
	s_mov_b32 m0, s50
	s_nop 0
	global_load_lds_dwordx4 v[150:151], off
	v_lshl_add_u64 v[150:151], s[20:21], 0, v[134:135]
	s_add_i32 m0, s50, 0x2000
	s_nop 0
	global_load_lds_dwordx4 v[150:151], off
	s_waitcnt vmcnt(6)
	s_barrier
	s_setprio 1
	v_mfma_f32_16x16x32_bf16 v[52:55], v[208:211], v[172:175], v[52:55]
	v_mfma_f32_16x16x32_bf16 v[48:51], v[216:219], v[172:175], v[48:51]
	v_mfma_f32_16x16x32_bf16 v[36:39], v[208:211], v[180:183], v[36:39]
	v_mfma_f32_16x16x32_bf16 v[32:35], v[216:219], v[180:183], v[32:35]
	v_mfma_f32_16x16x32_bf16 v[20:23], v[208:211], v[188:191], v[20:23]
	v_mfma_f32_16x16x32_bf16 v[16:19], v[216:219], v[188:191], v[16:19]
	v_mfma_f32_16x16x32_bf16 v[4:7], v[208:211], v[200:203], v[4:7]
	v_mfma_f32_16x16x32_bf16 v[0:3], v[216:219], v[200:203], v[0:3]
	v_mfma_f32_16x16x32_bf16 v[52:55], v[212:215], v[176:179], v[52:55]
	v_mfma_f32_16x16x32_bf16 v[48:51], v[220:223], v[176:179], v[48:51]
	v_mfma_f32_16x16x32_bf16 v[36:39], v[212:215], v[184:187], v[36:39]
	v_mfma_f32_16x16x32_bf16 v[32:35], v[220:223], v[184:187], v[32:35]
	v_mfma_f32_16x16x32_bf16 v[20:23], v[212:215], v[196:199], v[20:23]
	v_mfma_f32_16x16x32_bf16 v[16:19], v[220:223], v[196:199], v[16:19]
	v_mfma_f32_16x16x32_bf16 v[4:7], v[212:215], v[204:207], v[4:7]
	v_mfma_f32_16x16x32_bf16 v[0:3], v[220:223], v[204:207], v[0:3]
	s_setprio 0
	s_add_i32 s47, s47, 2
	s_add_u32 s48, s48, 0x100
	s_addc_u32 s49, s49, 0
	s_add_u32 s35, s35, 0x100
	s_addc_u32 s45, s45, 0
	s_cmp_gt_u32 s47, 29
	s_cbranch_scc0 .Lepi_nl_about
	s_cmp_lg_u32 s57, 64
	s_cbranch_scc1 .Lepi_nl_about
	s_lshl_b32 s15, s46, 8
	s_add_i32 s15, s15, s57
	v_or_b32_e32 v154, s15, v147
	s_add_i32 s17, s15, 0xffffe000
	v_lshl_or_b32 v150, s44, 8, v160
	s_lshr_b32 s17, s17, 12
	v_lshlrev_b32_e32 v151, 13, v154
	s_add_i32 s17, s17, 1
	s_sub_u32 s34, s54, 0x4000000
	s_subb_u32 s35, s55, 0
	v_lshlrev_b32_e32 v152, 12, v154
	s_cmp_gt_i32 s15, s64
	s_cselect_b32 s34, s34, s52
	s_cselect_b32 s35, s35, s53
	s_cselect_b32 s17, s17, 0
	s_mul_i32 s17, s17, 0xc000
	v_lshl_add_u32 v151, v150, 2, v151
	s_add_u32 s20, s8, s17
	s_addc_u32 s21, s9, 0
	v_lshl_add_u32 v152, v150, 1, v152
	v_lshlrev_b32_e32 v153, 2, v150
	s_nop 0
	global_load_dwordx4 v[196:199], v153, s[20:21]
	global_load_dwordx4 v[200:203], v153, s[20:21] offset:16
	global_load_dwordx4 v[204:207], v153, s[20:21] offset:512
	global_load_dwordx4 v[208:211], v153, s[20:21] offset:528
	global_load_dwordx4 v[164:167], v151, s[34:35]
	global_load_dwordx4 v[168:171], v151, s[34:35] offset:16
	global_load_dwordx4 v[172:175], v151, s[34:35] offset:512
	global_load_dwordx4 v[176:179], v151, s[34:35] offset:528
	v_add_u32_e32 v155, 0x20000, v151
	global_load_dwordx4 v[180:183], v155, s[34:35]
	global_load_dwordx4 v[184:187], v155, s[34:35] offset:16
	global_load_dwordx4 v[188:191], v155, s[34:35] offset:512
	global_load_dwordx4 v[212:215], v155, s[34:35] offset:528
	v_add_u32_e32 v155, 0x40000, v151
	global_load_dwordx4 v[216:219], v155, s[34:35]
	global_load_dwordx4 v[220:223], v155, s[34:35] offset:16
	global_load_dwordx4 v[224:227], v155, s[34:35] offset:512
	global_load_dwordx4 v[228:231], v155, s[34:35] offset:528
	v_add_u32_e32 v155, 0x60000, v151
	global_load_dwordx4 v[236:239], v155, s[34:35]
	global_load_dwordx4 v[240:243], v155, s[34:35] offset:16
	global_load_dwordx4 v[244:247], v155, s[34:35] offset:512
	global_load_dwordx4 v[248:251], v155, s[34:35] offset:528
	s_waitcnt vmcnt(0)
	v_pk_fma_f32 v[124:125], v[124:125], v[196:197], v[164:165]
	v_pk_fma_f32 v[126:127], v[126:127], v[198:199], v[166:167]
	v_pk_fma_f32 v[120:121], v[120:121], v[200:201], v[168:169]
	v_pk_fma_f32 v[122:123], v[122:123], v[202:203], v[170:171]
	v_cvt_pk_bf16_f32 v123, v122, v123
	v_cvt_pk_bf16_f32 v122, v120, v121
	v_cvt_pk_bf16_f32 v121, v126, v127
	v_cvt_pk_bf16_f32 v120, v124, v125
	global_store_dwordx4 v152, v[120:123], s[74:75]
	v_pk_fma_f32 v[116:117], v[116:117], v[204:205], v[172:173]
	v_pk_fma_f32 v[118:119], v[118:119], v[206:207], v[174:175]
	v_pk_fma_f32 v[112:113], v[112:113], v[208:209], v[176:177]
	v_pk_fma_f32 v[114:115], v[114:115], v[210:211], v[178:179]
	v_cvt_pk_bf16_f32 v115, v114, v115
	v_cvt_pk_bf16_f32 v114, v112, v113
	v_cvt_pk_bf16_f32 v113, v118, v119
	v_cvt_pk_bf16_f32 v112, v116, v117
	global_store_dwordx4 v152, v[112:115], s[74:75] offset:256
	v_pk_fma_f32 v[108:109], v[108:109], v[196:197], v[180:181]
	v_pk_fma_f32 v[110:111], v[110:111], v[198:199], v[182:183]
	v_pk_fma_f32 v[104:105], v[104:105], v[200:201], v[184:185]
	v_pk_fma_f32 v[106:107], v[106:107], v[202:203], v[186:187]
	v_cvt_pk_bf16_f32 v107, v106, v107
	v_cvt_pk_bf16_f32 v106, v104, v105
	v_cvt_pk_bf16_f32 v105, v110, v111
	v_cvt_pk_bf16_f32 v104, v108, v109
	v_add_u32_e32 v156, 0x10000, v152
	global_store_dwordx4 v156, v[104:107], s[74:75]
	v_pk_fma_f32 v[100:101], v[100:101], v[204:205], v[188:189]
	v_pk_fma_f32 v[102:103], v[102:103], v[206:207], v[190:191]
	v_pk_fma_f32 v[96:97], v[96:97], v[208:209], v[212:213]
	v_pk_fma_f32 v[98:99], v[98:99], v[210:211], v[214:215]
	v_cvt_pk_bf16_f32 v99, v98, v99
	v_cvt_pk_bf16_f32 v98, v96, v97
	v_cvt_pk_bf16_f32 v97, v102, v103
	v_cvt_pk_bf16_f32 v96, v100, v101
	v_add_u32_e32 v156, 0x10000, v152
	global_store_dwordx4 v156, v[96:99], s[74:75] offset:256
	v_add_u32_e32 v155, 0x100000, v151
	global_load_dwordx4 v[164:167], v155, s[34:35]
	global_load_dwordx4 v[168:171], v155, s[34:35] offset:16
	global_load_dwordx4 v[172:175], v155, s[34:35] offset:512
	global_load_dwordx4 v[176:179], v155, s[34:35] offset:528
	v_add_u32_e32 v155, 0x120000, v151
	global_load_dwordx4 v[180:183], v155, s[34:35]
	global_load_dwordx4 v[184:187], v155, s[34:35] offset:16
	global_load_dwordx4 v[188:191], v155, s[34:35] offset:512
	global_load_dwordx4 v[212:215], v155, s[34:35] offset:528
	v_pk_fma_f32 v[92:93], v[92:93], v[196:197], v[216:217]
	v_pk_fma_f32 v[94:95], v[94:95], v[198:199], v[218:219]
	v_pk_fma_f32 v[88:89], v[88:89], v[200:201], v[220:221]
	v_pk_fma_f32 v[90:91], v[90:91], v[202:203], v[222:223]
	v_cvt_pk_bf16_f32 v91, v90, v91
	v_cvt_pk_bf16_f32 v90, v88, v89
	v_cvt_pk_bf16_f32 v89, v94, v95
	v_cvt_pk_bf16_f32 v88, v92, v93
	v_add_u32_e32 v156, 0x20000, v152
	global_store_dwordx4 v156, v[88:91], s[74:75]
	v_pk_fma_f32 v[84:85], v[84:85], v[204:205], v[224:225]
	v_pk_fma_f32 v[86:87], v[86:87], v[206:207], v[226:227]
	v_pk_fma_f32 v[80:81], v[80:81], v[208:209], v[228:229]
	v_pk_fma_f32 v[82:83], v[82:83], v[210:211], v[230:231]
	v_cvt_pk_bf16_f32 v83, v82, v83
	v_cvt_pk_bf16_f32 v82, v80, v81
	v_cvt_pk_bf16_f32 v81, v86, v87
	v_cvt_pk_bf16_f32 v80, v84, v85
	v_add_u32_e32 v156, 0x20000, v152
	global_store_dwordx4 v156, v[80:83], s[74:75] offset:256
	v_pk_fma_f32 v[76:77], v[76:77], v[196:197], v[236:237]
	v_pk_fma_f32 v[78:79], v[78:79], v[198:199], v[238:239]
	v_pk_fma_f32 v[72:73], v[72:73], v[200:201], v[240:241]
	v_pk_fma_f32 v[74:75], v[74:75], v[202:203], v[242:243]
	v_cvt_pk_bf16_f32 v75, v74, v75
	v_cvt_pk_bf16_f32 v74, v72, v73
	v_cvt_pk_bf16_f32 v73, v78, v79
	v_cvt_pk_bf16_f32 v72, v76, v77
	v_add_u32_e32 v156, 0x30000, v152
	global_store_dwordx4 v156, v[72:75], s[74:75]
	v_pk_fma_f32 v[68:69], v[68:69], v[204:205], v[244:245]
	v_pk_fma_f32 v[70:71], v[70:71], v[206:207], v[246:247]
	v_pk_fma_f32 v[64:65], v[64:65], v[208:209], v[248:249]
	v_pk_fma_f32 v[66:67], v[66:67], v[210:211], v[250:251]
	v_cvt_pk_bf16_f32 v67, v66, v67
	v_cvt_pk_bf16_f32 v66, v64, v65
	v_cvt_pk_bf16_f32 v65, v70, v71
	v_cvt_pk_bf16_f32 v64, v68, v69
	v_add_u32_e32 v156, 0x30000, v152
	global_store_dwordx4 v156, v[64:67], s[74:75] offset:256
	v_add_u32_e32 v155, 0x140000, v151
	global_load_dwordx4 v[216:219], v155, s[34:35]
	global_load_dwordx4 v[220:223], v155, s[34:35] offset:16
	global_load_dwordx4 v[224:227], v155, s[34:35] offset:512
	global_load_dwordx4 v[228:231], v155, s[34:35] offset:528
	v_add_u32_e32 v155, 0x160000, v151
	global_load_dwordx4 v[236:239], v155, s[34:35]
	global_load_dwordx4 v[240:243], v155, s[34:35] offset:16
	global_load_dwordx4 v[244:247], v155, s[34:35] offset:512
	global_load_dwordx4 v[248:251], v155, s[34:35] offset:528
	s_waitcnt vmcnt(0)
	v_pk_fma_f32 v[60:61], v[60:61], v[196:197], v[164:165]
	v_pk_fma_f32 v[62:63], v[62:63], v[198:199], v[166:167]
	v_pk_fma_f32 v[56:57], v[56:57], v[200:201], v[168:169]
	v_pk_fma_f32 v[58:59], v[58:59], v[202:203], v[170:171]
	v_cvt_pk_bf16_f32 v59, v58, v59
	v_cvt_pk_bf16_f32 v58, v56, v57
	v_cvt_pk_bf16_f32 v57, v62, v63
	v_cvt_pk_bf16_f32 v56, v60, v61
	v_add_u32_e32 v156, 0x80000, v152
	global_store_dwordx4 v156, v[56:59], s[74:75]
	v_pk_fma_f32 v[52:53], v[52:53], v[204:205], v[172:173]
	v_pk_fma_f32 v[54:55], v[54:55], v[206:207], v[174:175]
	v_pk_fma_f32 v[48:49], v[48:49], v[208:209], v[176:177]
	v_pk_fma_f32 v[50:51], v[50:51], v[210:211], v[178:179]
	v_cvt_pk_bf16_f32 v51, v50, v51
	v_cvt_pk_bf16_f32 v50, v48, v49
	v_cvt_pk_bf16_f32 v49, v54, v55
	v_cvt_pk_bf16_f32 v48, v52, v53
	v_add_u32_e32 v156, 0x80000, v152
	global_store_dwordx4 v156, v[48:51], s[74:75] offset:256
	v_pk_fma_f32 v[44:45], v[44:45], v[196:197], v[180:181]
	v_pk_fma_f32 v[46:47], v[46:47], v[198:199], v[182:183]
	v_pk_fma_f32 v[40:41], v[40:41], v[200:201], v[184:185]
	v_pk_fma_f32 v[42:43], v[42:43], v[202:203], v[186:187]
	v_cvt_pk_bf16_f32 v43, v42, v43
	v_cvt_pk_bf16_f32 v42, v40, v41
	v_cvt_pk_bf16_f32 v41, v46, v47
	v_cvt_pk_bf16_f32 v40, v44, v45
	v_add_u32_e32 v156, 0x90000, v152
	global_store_dwordx4 v156, v[40:43], s[74:75]
	v_pk_fma_f32 v[36:37], v[36:37], v[204:205], v[188:189]
	v_pk_fma_f32 v[38:39], v[38:39], v[206:207], v[190:191]
	v_pk_fma_f32 v[32:33], v[32:33], v[208:209], v[212:213]
	v_pk_fma_f32 v[34:35], v[34:35], v[210:211], v[214:215]
	v_cvt_pk_bf16_f32 v35, v34, v35
	v_cvt_pk_bf16_f32 v34, v32, v33
	v_cvt_pk_bf16_f32 v33, v38, v39
	v_cvt_pk_bf16_f32 v32, v36, v37
	v_add_u32_e32 v156, 0x90000, v152
	global_store_dwordx4 v156, v[32:35], s[74:75] offset:256
	v_pk_fma_f32 v[28:29], v[28:29], v[196:197], v[216:217]
	v_pk_fma_f32 v[30:31], v[30:31], v[198:199], v[218:219]
	v_pk_fma_f32 v[24:25], v[24:25], v[200:201], v[220:221]
	v_pk_fma_f32 v[26:27], v[26:27], v[202:203], v[222:223]
	v_cvt_pk_bf16_f32 v27, v26, v27
	v_cvt_pk_bf16_f32 v26, v24, v25
	v_cvt_pk_bf16_f32 v25, v30, v31
	v_cvt_pk_bf16_f32 v24, v28, v29
	v_add_u32_e32 v156, 0xa0000, v152
	global_store_dwordx4 v156, v[24:27], s[74:75]
	v_pk_fma_f32 v[20:21], v[20:21], v[204:205], v[224:225]
	v_pk_fma_f32 v[22:23], v[22:23], v[206:207], v[226:227]
	v_pk_fma_f32 v[16:17], v[16:17], v[208:209], v[228:229]
	v_pk_fma_f32 v[18:19], v[18:19], v[210:211], v[230:231]
	v_cvt_pk_bf16_f32 v19, v18, v19
	v_cvt_pk_bf16_f32 v18, v16, v17
	v_cvt_pk_bf16_f32 v17, v22, v23
	v_cvt_pk_bf16_f32 v16, v20, v21
	v_add_u32_e32 v156, 0xa0000, v152
	global_store_dwordx4 v156, v[16:19], s[74:75] offset:256
	v_pk_fma_f32 v[12:13], v[12:13], v[196:197], v[236:237]
	v_pk_fma_f32 v[14:15], v[14:15], v[198:199], v[238:239]
	v_pk_fma_f32 v[8:9], v[8:9], v[200:201], v[240:241]
	v_pk_fma_f32 v[10:11], v[10:11], v[202:203], v[242:243]
	v_cvt_pk_bf16_f32 v11, v10, v11
	v_cvt_pk_bf16_f32 v10, v8, v9
	v_cvt_pk_bf16_f32 v9, v14, v15
	v_cvt_pk_bf16_f32 v8, v12, v13
	v_add_u32_e32 v156, 0xb0000, v152
	global_store_dwordx4 v156, v[8:11], s[74:75]
	v_pk_fma_f32 v[4:5], v[4:5], v[204:205], v[244:245]
	v_pk_fma_f32 v[6:7], v[6:7], v[206:207], v[246:247]
	v_pk_fma_f32 v[0:1], v[0:1], v[208:209], v[248:249]
	v_pk_fma_f32 v[2:3], v[2:3], v[210:211], v[250:251]
	v_cvt_pk_bf16_f32 v3, v2, v3
	v_cvt_pk_bf16_f32 v2, v0, v1
	v_cvt_pk_bf16_f32 v1, v6, v7
	v_cvt_pk_bf16_f32 v0, v4, v5
	v_add_u32_e32 v156, 0xb0000, v152
	global_store_dwordx4 v156, v[0:3], s[74:75] offset:256

.LBB0_999:
	ds_read_b128 v[156:159], v152
	ds_read_b128 v[160:163], v152 offset:1024
	ds_read_b128 v[164:167], v152 offset:2048
	ds_read_b128 v[168:171], v152 offset:3072
	s_add_u32 s20, s46, 0xfff80080
	s_addc_u32 s21, s47, -1
	s_cmp_eq_u32 s58, 28
	s_cselect_b32 s21, s15, s21
	s_cselect_b32 s20, s54, s20
	s_cselect_b32 s49, s11, s57
	s_cselect_b32 s48, s55, s56
	v_lshl_add_u64 v[148:149], s[46:47], 0, v[136:137]
	s_add_i32 m0, s35, 0xc000
	ds_read_b128 v[172:175], v153
	ds_read_b128 v[176:179], v153 offset:1024
	ds_read_b128 v[180:183], v153 offset:2048
	ds_read_b128 v[184:187], v153 offset:3072
	ds_read_b128 v[188:191], v153 offset:4096
	ds_read_b128 v[196:199], v153 offset:5120
	ds_read_b128 v[200:203], v153 offset:6144
	ds_read_b128 v[204:207], v153 offset:7168
	global_load_lds_dwordx4 v[148:149], off
	v_lshl_add_u64 v[148:149], s[46:47], 0, v[138:139]
	s_add_i32 m0, s35, 0xe000
	s_nop 0
	global_load_lds_dwordx4 v[148:149], off
	s_waitcnt lgkmcnt(8)
	s_barrier
	s_waitcnt lgkmcnt(0)
	s_setprio 1
	v_mfma_f32_16x16x32_bf16 v[124:127], v[156:159], v[172:175], v[124:127]
	v_mfma_f32_16x16x32_bf16 v[120:123], v[164:167], v[172:175], v[120:123]
	v_mfma_f32_16x16x32_bf16 v[108:111], v[156:159], v[180:183], v[108:111]
	v_mfma_f32_16x16x32_bf16 v[104:107], v[164:167], v[180:183], v[104:107]
	v_mfma_f32_16x16x32_bf16 v[92:95], v[156:159], v[188:191], v[92:95]
	v_mfma_f32_16x16x32_bf16 v[88:91], v[164:167], v[188:191], v[88:91]
	v_mfma_f32_16x16x32_bf16 v[76:79], v[156:159], v[200:203], v[76:79]
	v_mfma_f32_16x16x32_bf16 v[72:75], v[164:167], v[200:203], v[72:75]
	v_mfma_f32_16x16x32_bf16 v[124:127], v[160:163], v[176:179], v[124:127]
	v_mfma_f32_16x16x32_bf16 v[120:123], v[168:171], v[176:179], v[120:123]
	v_mfma_f32_16x16x32_bf16 v[108:111], v[160:163], v[184:187], v[108:111]
	v_mfma_f32_16x16x32_bf16 v[104:107], v[168:171], v[184:187], v[104:107]
	v_mfma_f32_16x16x32_bf16 v[92:95], v[160:163], v[196:199], v[92:95]
	v_mfma_f32_16x16x32_bf16 v[88:91], v[168:171], v[196:199], v[88:91]
	v_mfma_f32_16x16x32_bf16 v[76:79], v[160:163], v[204:207], v[76:79]
	v_mfma_f32_16x16x32_bf16 v[72:75], v[168:171], v[204:207], v[72:75]
	s_setprio 0
	s_barrier
	s_add_i32 s59, s52, s23
	v_lshl_add_u64 v[148:149], s[48:49], 0, v[132:133]
	s_mov_b32 m0, s59
	ds_read_b128 v[208:211], v154
	ds_read_b128 v[212:215], v154 offset:1024
	ds_read_b128 v[216:219], v154 offset:2048
	ds_read_b128 v[220:223], v154 offset:3072
	global_load_lds_dwordx4 v[148:149], off
	v_lshl_add_u64 v[224:225], s[48:49], 0, v[128:129]
	s_add_i32 m0, s59, 0x2000
	s_nop 0
	global_load_lds_dwordx4 v[224:225], off
	s_barrier
	s_waitcnt lgkmcnt(0)
	s_setprio 1
	v_mfma_f32_16x16x32_bf16 v[116:119], v[208:211], v[172:175], v[116:119]
	v_mfma_f32_16x16x32_bf16 v[112:115], v[216:219], v[172:175], v[112:115]
	v_mfma_f32_16x16x32_bf16 v[100:103], v[208:211], v[180:183], v[100:103]
	v_mfma_f32_16x16x32_bf16 v[96:99], v[216:219], v[180:183], v[96:99]
	v_mfma_f32_16x16x32_bf16 v[84:87], v[208:211], v[188:191], v[84:87]
	v_mfma_f32_16x16x32_bf16 v[80:83], v[216:219], v[188:191], v[80:83]
	v_mfma_f32_16x16x32_bf16 v[68:71], v[208:211], v[200:203], v[68:71]
	v_mfma_f32_16x16x32_bf16 v[64:67], v[216:219], v[200:203], v[64:67]
	v_mfma_f32_16x16x32_bf16 v[116:119], v[212:215], v[176:179], v[116:119]
	v_mfma_f32_16x16x32_bf16 v[112:115], v[220:223], v[176:179], v[112:115]
	v_mfma_f32_16x16x32_bf16 v[100:103], v[212:215], v[184:187], v[100:103]
	v_mfma_f32_16x16x32_bf16 v[96:99], v[220:223], v[184:187], v[96:99]
	v_mfma_f32_16x16x32_bf16 v[84:87], v[212:215], v[196:199], v[84:87]
	v_mfma_f32_16x16x32_bf16 v[80:83], v[220:223], v[196:199], v[80:83]
	v_mfma_f32_16x16x32_bf16 v[68:71], v[212:215], v[204:207], v[68:71]
	v_mfma_f32_16x16x32_bf16 v[64:67], v[220:223], v[204:207], v[64:67]
	s_setprio 0
	s_mov_b32 m0, s35
	v_lshl_add_u64 v[226:227], s[20:21], 0, v[134:135]
	s_barrier
	ds_read_b128 v[172:175], v153 offset:16384
	ds_read_b128 v[176:179], v153 offset:17408
	ds_read_b128 v[180:183], v153 offset:18432
	ds_read_b128 v[184:187], v153 offset:19456
	ds_read_b128 v[188:191], v153 offset:20480
	ds_read_b128 v[196:199], v153 offset:21504
	ds_read_b128 v[200:203], v153 offset:22528
	ds_read_b128 v[204:207], v153 offset:23552
	global_load_lds_dwordx4 v[226:227], off
	v_lshl_add_u64 v[228:229], s[20:21], 0, v[130:131]
	s_mov_b32 m0, s36
	s_nop 0
	global_load_lds_dwordx4 v[228:229], off
	s_barrier
	s_waitcnt lgkmcnt(0)
	s_setprio 1
	v_mfma_f32_16x16x32_bf16 v[60:63], v[156:159], v[172:175], v[60:63]
	v_mfma_f32_16x16x32_bf16 v[56:59], v[164:167], v[172:175], v[56:59]
	v_mfma_f32_16x16x32_bf16 v[44:47], v[156:159], v[180:183], v[44:47]
	v_mfma_f32_16x16x32_bf16 v[40:43], v[164:167], v[180:183], v[40:43]
	v_mfma_f32_16x16x32_bf16 v[28:31], v[156:159], v[188:191], v[28:31]
	v_mfma_f32_16x16x32_bf16 v[24:27], v[164:167], v[188:191], v[24:27]
	v_mfma_f32_16x16x32_bf16 v[12:15], v[156:159], v[200:203], v[12:15]
	v_mfma_f32_16x16x32_bf16 v[8:11], v[164:167], v[200:203], v[8:11]
	v_mfma_f32_16x16x32_bf16 v[60:63], v[160:163], v[176:179], v[60:63]
	v_mfma_f32_16x16x32_bf16 v[56:59], v[168:171], v[176:179], v[56:59]
	v_mfma_f32_16x16x32_bf16 v[44:47], v[160:163], v[184:187], v[44:47]
	v_mfma_f32_16x16x32_bf16 v[40:43], v[168:171], v[184:187], v[40:43]
	v_mfma_f32_16x16x32_bf16 v[28:31], v[160:163], v[196:199], v[28:31]
	v_mfma_f32_16x16x32_bf16 v[24:27], v[168:171], v[196:199], v[24:27]
	v_mfma_f32_16x16x32_bf16 v[12:15], v[160:163], v[204:207], v[12:15]
	v_mfma_f32_16x16x32_bf16 v[8:11], v[168:171], v[204:207], v[8:11]
	s_setprio 0
	s_barrier
	s_add_u32 s60, s48, 0x80000
	s_addc_u32 s61, s49, 0
	s_add_i32 s59, s53, s23
	v_lshl_add_u64 v[156:157], s[60:61], 0, v[132:133]
	s_mov_b32 m0, s59
	s_nop 0
	global_load_lds_dwordx4 v[156:157], off
	v_lshl_add_u64 v[156:157], s[60:61], 0, v[128:129]
	s_add_i32 m0, s59, 0x2000
	s_nop 0
	global_load_lds_dwordx4 v[156:157], off
	s_waitcnt vmcnt(6)
	s_barrier
	s_setprio 1
	v_mfma_f32_16x16x32_bf16 v[52:55], v[208:211], v[172:175], v[52:55]
	v_mfma_f32_16x16x32_bf16 v[48:51], v[216:219], v[172:175], v[48:51]
	v_mfma_f32_16x16x32_bf16 v[36:39], v[208:211], v[180:183], v[36:39]
	v_mfma_f32_16x16x32_bf16 v[32:35], v[216:219], v[180:183], v[32:35]
	v_mfma_f32_16x16x32_bf16 v[20:23], v[208:211], v[188:191], v[20:23]
	v_mfma_f32_16x16x32_bf16 v[16:19], v[216:219], v[188:191], v[16:19]
	v_mfma_f32_16x16x32_bf16 v[4:7], v[208:211], v[200:203], v[4:7]
	v_mfma_f32_16x16x32_bf16 v[0:3], v[216:219], v[200:203], v[0:3]
	v_mfma_f32_16x16x32_bf16 v[52:55], v[212:215], v[176:179], v[52:55]
	v_mfma_f32_16x16x32_bf16 v[48:51], v[220:223], v[176:179], v[48:51]
	v_mfma_f32_16x16x32_bf16 v[36:39], v[212:215], v[184:187], v[36:39]
	v_mfma_f32_16x16x32_bf16 v[32:35], v[220:223], v[184:187], v[32:35]
	v_mfma_f32_16x16x32_bf16 v[20:23], v[212:215], v[196:199], v[20:23]
	v_mfma_f32_16x16x32_bf16 v[16:19], v[220:223], v[196:199], v[16:19]
	v_mfma_f32_16x16x32_bf16 v[4:7], v[212:215], v[204:207], v[4:7]
	v_mfma_f32_16x16x32_bf16 v[0:3], v[220:223], v[204:207], v[0:3]
	s_setprio 0
	s_add_i32 s59, 0, 0x18000
	v_add_u32_e32 v155, s59, v150
	s_barrier
	ds_read_b128 v[156:159], v155
	ds_read_b128 v[160:163], v155 offset:1024
	ds_read_b128 v[164:167], v155 offset:2048
	ds_read_b128 v[168:171], v155 offset:3072
	s_add_u32 s20, s20, 0x80000
	s_addc_u32 s21, s21, 0
	s_mov_b32 m0, s37
	v_lshl_add_u64 v[208:209], s[20:21], 0, v[134:135]
	ds_read_b128 v[172:175], v153 offset:32768
	ds_read_b128 v[176:179], v153 offset:33792
	ds_read_b128 v[180:183], v153 offset:34816
	ds_read_b128 v[184:187], v153 offset:35840
	ds_read_b128 v[188:191], v153 offset:36864
	ds_read_b128 v[196:199], v153 offset:37888
	ds_read_b128 v[200:203], v153 offset:38912
	ds_read_b128 v[204:207], v153 offset:39936
	global_load_lds_dwordx4 v[208:209], off
	v_lshl_add_u64 v[208:209], s[20:21], 0, v[130:131]
	s_mov_b32 m0, s38
	s_nop 0
	global_load_lds_dwordx4 v[208:209], off
	s_waitcnt lgkmcnt(8)
	s_barrier
	s_waitcnt lgkmcnt(0)
	s_setprio 1
	v_mfma_f32_16x16x32_bf16 v[124:127], v[156:159], v[172:175], v[124:127]
	v_mfma_f32_16x16x32_bf16 v[120:123], v[164:167], v[172:175], v[120:123]
	v_mfma_f32_16x16x32_bf16 v[108:111], v[156:159], v[180:183], v[108:111]
	v_mfma_f32_16x16x32_bf16 v[104:107], v[164:167], v[180:183], v[104:107]
	v_mfma_f32_16x16x32_bf16 v[92:95], v[156:159], v[188:191], v[92:95]
	v_mfma_f32_16x16x32_bf16 v[88:91], v[164:167], v[188:191], v[88:91]
	v_mfma_f32_16x16x32_bf16 v[76:79], v[156:159], v[200:203], v[76:79]
	v_mfma_f32_16x16x32_bf16 v[72:75], v[164:167], v[200:203], v[72:75]
	v_mfma_f32_16x16x32_bf16 v[124:127], v[160:163], v[176:179], v[124:127]
	v_mfma_f32_16x16x32_bf16 v[120:123], v[168:171], v[176:179], v[120:123]
	v_mfma_f32_16x16x32_bf16 v[108:111], v[160:163], v[184:187], v[108:111]
	v_mfma_f32_16x16x32_bf16 v[104:107], v[168:171], v[184:187], v[104:107]
	v_mfma_f32_16x16x32_bf16 v[92:95], v[160:163], v[196:199], v[92:95]
	v_mfma_f32_16x16x32_bf16 v[88:91], v[168:171], v[196:199], v[88:91]
	v_mfma_f32_16x16x32_bf16 v[76:79], v[160:163], v[204:207], v[76:79]
	v_mfma_f32_16x16x32_bf16 v[72:75], v[168:171], v[204:207], v[72:75]
	s_setprio 0
	s_barrier
	s_add_i32 s60, 0, 0x1c000
	s_add_i32 s20, s59, s23
	v_add_u32_e32 v155, s60, v150
	v_lshl_add_u64 v[148:149], v[148:149], 0, s[8:9]
	s_mov_b32 m0, s20
	ds_read_b128 v[208:211], v155
	ds_read_b128 v[212:215], v155 offset:1024
	ds_read_b128 v[216:219], v155 offset:2048
	ds_read_b128 v[220:223], v155 offset:3072
	global_load_lds_dwordx4 v[148:149], off
	v_lshl_add_u64 v[148:149], v[224:225], 0, s[8:9]
	s_add_i32 m0, s20, 0x2000
	s_nop 0
	global_load_lds_dwordx4 v[148:149], off
	s_barrier
	s_waitcnt lgkmcnt(0)
	s_setprio 1
	v_mfma_f32_16x16x32_bf16 v[116:119], v[208:211], v[172:175], v[116:119]
	v_mfma_f32_16x16x32_bf16 v[112:115], v[216:219], v[172:175], v[112:115]
	v_mfma_f32_16x16x32_bf16 v[100:103], v[208:211], v[180:183], v[100:103]
	v_mfma_f32_16x16x32_bf16 v[96:99], v[216:219], v[180:183], v[96:99]
	v_mfma_f32_16x16x32_bf16 v[84:87], v[208:211], v[188:191], v[84:87]
	v_mfma_f32_16x16x32_bf16 v[80:83], v[216:219], v[188:191], v[80:83]
	v_mfma_f32_16x16x32_bf16 v[68:71], v[208:211], v[200:203], v[68:71]
	v_mfma_f32_16x16x32_bf16 v[64:67], v[216:219], v[200:203], v[64:67]
	v_mfma_f32_16x16x32_bf16 v[116:119], v[212:215], v[176:179], v[116:119]
	v_mfma_f32_16x16x32_bf16 v[112:115], v[220:223], v[176:179], v[112:115]
	v_mfma_f32_16x16x32_bf16 v[100:103], v[212:215], v[184:187], v[100:103]
	v_mfma_f32_16x16x32_bf16 v[96:99], v[220:223], v[184:187], v[96:99]
	v_mfma_f32_16x16x32_bf16 v[84:87], v[212:215], v[196:199], v[84:87]
	v_mfma_f32_16x16x32_bf16 v[80:83], v[220:223], v[196:199], v[80:83]
	v_mfma_f32_16x16x32_bf16 v[68:71], v[212:215], v[204:207], v[68:71]
	v_mfma_f32_16x16x32_bf16 v[64:67], v[220:223], v[204:207], v[64:67]
	s_setprio 0
	s_mov_b32 m0, s45
	v_lshl_add_u64 v[148:149], v[226:227], 0, s[8:9]
	s_barrier
	ds_read_b128 v[172:175], v153 offset:49152
	ds_read_b128 v[176:179], v153 offset:50176
	ds_read_b128 v[180:183], v153 offset:51200
	ds_read_b128 v[184:187], v153 offset:52224
	ds_read_b128 v[188:191], v153 offset:53248
	ds_read_b128 v[196:199], v153 offset:54272
	ds_read_b128 v[200:203], v153 offset:55296
	ds_read_b128 v[204:207], v153 offset:56320
	global_load_lds_dwordx4 v[148:149], off
	v_lshl_add_u64 v[148:149], v[228:229], 0, s[8:9]
	s_mov_b32 m0, s50
	s_nop 0
	global_load_lds_dwordx4 v[148:149], off
	s_barrier
	s_waitcnt lgkmcnt(0)
	s_setprio 1
	v_mfma_f32_16x16x32_bf16 v[60:63], v[156:159], v[172:175], v[60:63]
	v_mfma_f32_16x16x32_bf16 v[56:59], v[164:167], v[172:175], v[56:59]
	v_mfma_f32_16x16x32_bf16 v[44:47], v[156:159], v[180:183], v[44:47]
	v_mfma_f32_16x16x32_bf16 v[40:43], v[164:167], v[180:183], v[40:43]
	v_mfma_f32_16x16x32_bf16 v[28:31], v[156:159], v[188:191], v[28:31]
	v_mfma_f32_16x16x32_bf16 v[24:27], v[164:167], v[188:191], v[24:27]
	v_mfma_f32_16x16x32_bf16 v[12:15], v[156:159], v[200:203], v[12:15]
	v_mfma_f32_16x16x32_bf16 v[8:11], v[164:167], v[200:203], v[8:11]
	v_mfma_f32_16x16x32_bf16 v[60:63], v[160:163], v[176:179], v[60:63]
	v_mfma_f32_16x16x32_bf16 v[56:59], v[168:171], v[176:179], v[56:59]
	v_mfma_f32_16x16x32_bf16 v[44:47], v[160:163], v[184:187], v[44:47]
	v_mfma_f32_16x16x32_bf16 v[40:43], v[168:171], v[184:187], v[40:43]
	v_mfma_f32_16x16x32_bf16 v[28:31], v[160:163], v[196:199], v[28:31]
	v_mfma_f32_16x16x32_bf16 v[24:27], v[168:171], v[196:199], v[24:27]
	v_mfma_f32_16x16x32_bf16 v[12:15], v[160:163], v[204:207], v[12:15]
	v_mfma_f32_16x16x32_bf16 v[8:11], v[168:171], v[204:207], v[8:11]
	s_setprio 0
	s_barrier
	s_add_u32 s20, s48, 0x80080
	s_addc_u32 s21, s49, 0
	s_add_i32 s48, s60, s23
	v_lshl_add_u64 v[148:149], s[20:21], 0, v[132:133]
	s_mov_b32 m0, s48
	s_nop 0
	global_load_lds_dwordx4 v[148:149], off
	v_lshl_add_u64 v[148:149], s[20:21], 0, v[128:129]
	s_add_i32 m0, s48, 0x2000
	s_nop 0
	global_load_lds_dwordx4 v[148:149], off
	s_waitcnt vmcnt(6)
	s_barrier
	s_setprio 1
	v_mfma_f32_16x16x32_bf16 v[52:55], v[208:211], v[172:175], v[52:55]
	v_mfma_f32_16x16x32_bf16 v[48:51], v[216:219], v[172:175], v[48:51]
	v_mfma_f32_16x16x32_bf16 v[36:39], v[208:211], v[180:183], v[36:39]
	v_mfma_f32_16x16x32_bf16 v[32:35], v[216:219], v[180:183], v[32:35]
	v_mfma_f32_16x16x32_bf16 v[20:23], v[208:211], v[188:191], v[20:23]
	v_mfma_f32_16x16x32_bf16 v[16:19], v[216:219], v[188:191], v[16:19]
	v_mfma_f32_16x16x32_bf16 v[4:7], v[208:211], v[200:203], v[4:7]
	v_mfma_f32_16x16x32_bf16 v[0:3], v[216:219], v[200:203], v[0:3]
	v_mfma_f32_16x16x32_bf16 v[52:55], v[212:215], v[176:179], v[52:55]
	v_mfma_f32_16x16x32_bf16 v[48:51], v[220:223], v[176:179], v[48:51]
	v_mfma_f32_16x16x32_bf16 v[36:39], v[212:215], v[184:187], v[36:39]
	v_mfma_f32_16x16x32_bf16 v[32:35], v[220:223], v[184:187], v[32:35]
	v_mfma_f32_16x16x32_bf16 v[20:23], v[212:215], v[196:199], v[20:23]
	v_mfma_f32_16x16x32_bf16 v[16:19], v[220:223], v[196:199], v[16:19]
	v_mfma_f32_16x16x32_bf16 v[4:7], v[212:215], v[204:207], v[4:7]
	v_mfma_f32_16x16x32_bf16 v[0:3], v[220:223], v[204:207], v[0:3]
	s_setprio 0
	s_add_i32 s58, s58, 2
	s_add_u32 s46, s46, 0x100
	s_addc_u32 s47, s47, 0
	s_add_u32 s56, s56, 0x100
	s_addc_u32 s57, s57, 0
	s_cmp_gt_u32 s58, 29
	s_cbranch_scc0 .Ldup_nl_mlpin0
	s_cmpk_gt_u32 s12, 0xff
	s_cbranch_scc0 .Ldup_nl_mlpin0
	v_lshl_add_u32 v148, s44, 8, v147
	v_max_f32_e32 v124, v124, v124
	v_max_f32_e32 v120, v120, v120
	v_ashrrev_i32_e32 v149, 31, v148
	v_max_f32_e32 v124, 0, v124
	v_max_f32_e32 v120, 0, v120
	v_lshlrev_b64 v[158:159], 14, v[148:149]
	v_mul_f32_e32 v149, v124, v124
	v_mul_f32_e32 v124, v120, v120
	v_max_f32_e32 v120, v125, v125
	v_max_f32_e32 v121, v121, v121
	v_max_f32_e32 v120, 0, v120
	v_max_f32_e32 v121, 0, v121
	v_mul_f32_e32 v155, v120, v120
	v_mul_f32_e32 v160, v121, v121
	v_max_f32_e32 v120, v126, v126
	v_max_f32_e32 v121, v122, v122
	v_max_f32_e32 v120, 0, v120
	v_max_f32_e32 v121, 0, v121
	v_lshl_or_b32 v156, s33, 8, v151
	v_mul_f32_e32 v161, v120, v120
	v_mul_f32_e32 v125, v121, v121
	v_max_f32_e32 v120, v127, v127
	v_max_f32_e32 v121, v123, v123
	v_max_f32_e32 v116, v116, v116
	v_max_f32_e32 v112, v112, v112
	v_max_f32_e32 v117, v117, v117
	v_max_f32_e32 v113, v113, v113
	v_max_f32_e32 v118, v118, v118
	v_max_f32_e32 v114, v114, v114
	v_max_f32_e32 v119, v119, v119
	v_max_f32_e32 v115, v115, v115
	v_ashrrev_i32_e32 v157, 31, v156
	v_max_f32_e32 v120, 0, v120
	v_max_f32_e32 v121, 0, v121
	v_max_f32_e32 v116, 0, v116
	v_max_f32_e32 v112, 0, v112
	v_max_f32_e32 v117, 0, v117
	v_max_f32_e32 v113, 0, v113
	v_max_f32_e32 v118, 0, v118
	v_max_f32_e32 v114, 0, v114
	v_max_f32_e32 v119, 0, v119
	v_max_f32_e32 v115, 0, v115
	v_mul_f32_e32 v162, v120, v120
	v_mul_f32_e32 v163, v121, v121
	v_lshl_add_u64 v[122:123], s[28:29], 0, v[158:159]
	v_lshlrev_b64 v[120:121], 1, v[156:157]
	v_mul_f32_e32 v116, v116, v116
	v_mul_f32_e32 v112, v112, v112
	v_mul_f32_e32 v117, v117, v117
	v_mul_f32_e32 v113, v113, v113
	v_mul_f32_e32 v118, v118, v118
	v_mul_f32_e32 v114, v114, v114
	v_mul_f32_e32 v119, v119, v119
	v_mul_f32_e32 v115, v115, v115
	v_max_f32_e32 v104, v104, v104
	v_lshl_add_u64 v[126:127], v[122:123], 0, v[120:121]
	v_cvt_pk_bf16_f32 v115, v114, v115
	v_cvt_pk_bf16_f32 v114, v112, v113
	v_cvt_pk_bf16_f32 v113, v118, v119
	v_cvt_pk_bf16_f32 v112, v116, v117
	v_max_f32_e32 v104, 0, v104
	global_store_dwordx4 v[126:127], v[112:115], off offset:256
	v_max_f32_e32 v105, v105, v105
	v_max_f32_e32 v105, 0, v105
	v_mul_f32_e32 v115, v104, v104
	v_max_f32_e32 v104, v109, v109
	v_max_f32_e32 v104, 0, v104
	v_mul_f32_e32 v116, v104, v104
	v_mul_f32_e32 v117, v105, v105
	v_max_f32_e32 v104, v110, v110
	v_max_f32_e32 v105, v106, v106
	v_or_b32_e32 v112, 16, v148
	v_max_f32_e32 v104, 0, v104
	v_max_f32_e32 v105, 0, v105
	v_ashrrev_i32_e32 v113, 31, v112
	v_mul_f32_e32 v110, v104, v104
	v_mul_f32_e32 v106, v105, v105
	v_max_f32_e32 v104, v111, v111
	v_max_f32_e32 v105, v107, v107
	v_max_f32_e32 v100, v100, v100
	v_max_f32_e32 v96, v96, v96
	v_max_f32_e32 v101, v101, v101
	v_max_f32_e32 v97, v97, v97
	v_max_f32_e32 v102, v102, v102
	v_max_f32_e32 v98, v98, v98
	v_max_f32_e32 v103, v103, v103
	v_max_f32_e32 v99, v99, v99
	v_lshlrev_b64 v[112:113], 14, v[112:113]
	v_max_f32_e32 v108, v108, v108
	v_max_f32_e32 v104, 0, v104
	v_max_f32_e32 v105, 0, v105
	v_max_f32_e32 v100, 0, v100
	v_max_f32_e32 v96, 0, v96
	v_max_f32_e32 v101, 0, v101
	v_max_f32_e32 v97, 0, v97
	v_max_f32_e32 v102, 0, v102
	v_max_f32_e32 v98, 0, v98
	v_max_f32_e32 v103, 0, v103
	v_max_f32_e32 v99, 0, v99
	v_max_f32_e32 v108, 0, v108
	v_mul_f32_e32 v111, v104, v104
	v_mul_f32_e32 v107, v105, v105
	v_lshl_add_u64 v[104:105], s[28:29], 0, v[112:113]
	v_mul_f32_e32 v100, v100, v100
	v_mul_f32_e32 v96, v96, v96
	v_mul_f32_e32 v101, v101, v101
	v_mul_f32_e32 v97, v97, v97
	v_mul_f32_e32 v102, v102, v102
	v_mul_f32_e32 v98, v98, v98
	v_mul_f32_e32 v103, v103, v103
	v_mul_f32_e32 v99, v99, v99
	v_max_f32_e32 v88, v88, v88
	v_mul_f32_e32 v114, v108, v108
	v_lshl_add_u64 v[108:109], v[104:105], 0, v[120:121]
	v_cvt_pk_bf16_f32 v99, v98, v99
	v_cvt_pk_bf16_f32 v98, v96, v97
	v_cvt_pk_bf16_f32 v97, v102, v103
	v_cvt_pk_bf16_f32 v96, v100, v101
	v_max_f32_e32 v88, 0, v88
	global_store_dwordx4 v[108:109], v[96:99], off offset:256
	v_max_f32_e32 v89, v89, v89
	v_max_f32_e32 v89, 0, v89
	v_mul_f32_e32 v99, v88, v88
	v_max_f32_e32 v88, v93, v93
	v_max_f32_e32 v88, 0, v88
	v_mul_f32_e32 v100, v88, v88
	v_mul_f32_e32 v101, v89, v89
	v_max_f32_e32 v88, v94, v94
	v_max_f32_e32 v89, v90, v90
	v_or_b32_e32 v96, 32, v148
	v_max_f32_e32 v88, 0, v88
	v_max_f32_e32 v89, 0, v89
	v_ashrrev_i32_e32 v97, 31, v96
	v_mul_f32_e32 v94, v88, v88
	v_mul_f32_e32 v90, v89, v89
	v_max_f32_e32 v88, v95, v95
	v_max_f32_e32 v89, v91, v91
	v_max_f32_e32 v84, v84, v84
	v_max_f32_e32 v80, v80, v80
	v_max_f32_e32 v85, v85, v85
	v_max_f32_e32 v81, v81, v81
	v_max_f32_e32 v86, v86, v86
	v_max_f32_e32 v82, v82, v82
	v_max_f32_e32 v87, v87, v87
	v_max_f32_e32 v83, v83, v83
	v_lshlrev_b64 v[96:97], 14, v[96:97]
	v_max_f32_e32 v92, v92, v92
	v_max_f32_e32 v88, 0, v88
	v_max_f32_e32 v89, 0, v89
	v_max_f32_e32 v84, 0, v84
	v_max_f32_e32 v80, 0, v80
	v_max_f32_e32 v85, 0, v85
	v_max_f32_e32 v81, 0, v81
	v_max_f32_e32 v86, 0, v86
	v_max_f32_e32 v82, 0, v82
	v_max_f32_e32 v87, 0, v87
	v_max_f32_e32 v83, 0, v83
	v_max_f32_e32 v92, 0, v92
	v_mul_f32_e32 v95, v88, v88
	v_mul_f32_e32 v91, v89, v89
	v_lshl_add_u64 v[88:89], s[28:29], 0, v[96:97]
	v_mul_f32_e32 v84, v84, v84
	v_mul_f32_e32 v80, v80, v80
	v_mul_f32_e32 v85, v85, v85
	v_mul_f32_e32 v81, v81, v81
	v_mul_f32_e32 v86, v86, v86
	v_mul_f32_e32 v82, v82, v82
	v_mul_f32_e32 v87, v87, v87
	v_mul_f32_e32 v83, v83, v83
	v_max_f32_e32 v72, v72, v72
	v_mul_f32_e32 v98, v92, v92
	v_lshl_add_u64 v[92:93], v[88:89], 0, v[120:121]
	v_cvt_pk_bf16_f32 v83, v82, v83
	v_cvt_pk_bf16_f32 v82, v80, v81
	v_cvt_pk_bf16_f32 v81, v86, v87
	v_cvt_pk_bf16_f32 v80, v84, v85
	v_max_f32_e32 v72, 0, v72
	global_store_dwordx4 v[92:93], v[80:83], off offset:256
	v_max_f32_e32 v73, v73, v73
	v_max_f32_e32 v73, 0, v73
	v_mul_f32_e32 v83, v72, v72
	v_max_f32_e32 v72, v77, v77
	v_max_f32_e32 v72, 0, v72
	v_mul_f32_e32 v84, v72, v72
	v_mul_f32_e32 v85, v73, v73
	v_max_f32_e32 v72, v78, v78
	v_max_f32_e32 v73, v74, v74
	v_or_b32_e32 v80, 48, v148
	v_max_f32_e32 v72, 0, v72
	v_max_f32_e32 v73, 0, v73
	v_ashrrev_i32_e32 v81, 31, v80
	v_mul_f32_e32 v78, v72, v72
	v_mul_f32_e32 v74, v73, v73
	v_max_f32_e32 v72, v79, v79
	v_max_f32_e32 v73, v75, v75
	v_max_f32_e32 v68, v68, v68
	v_max_f32_e32 v64, v64, v64
	v_max_f32_e32 v69, v69, v69
	v_max_f32_e32 v65, v65, v65
	v_max_f32_e32 v70, v70, v70
	v_max_f32_e32 v66, v66, v66
	v_max_f32_e32 v71, v71, v71
	v_max_f32_e32 v67, v67, v67
	v_lshlrev_b64 v[80:81], 14, v[80:81]
	v_max_f32_e32 v76, v76, v76
	v_max_f32_e32 v72, 0, v72
	v_max_f32_e32 v73, 0, v73
	v_max_f32_e32 v68, 0, v68
	v_max_f32_e32 v64, 0, v64
	v_max_f32_e32 v69, 0, v69
	v_max_f32_e32 v65, 0, v65
	v_max_f32_e32 v70, 0, v70
	v_max_f32_e32 v66, 0, v66
	v_max_f32_e32 v71, 0, v71
	v_max_f32_e32 v67, 0, v67
	v_max_f32_e32 v76, 0, v76
	v_mul_f32_e32 v79, v72, v72
	v_mul_f32_e32 v75, v73, v73
	v_lshl_add_u64 v[72:73], s[28:29], 0, v[80:81]
	v_mul_f32_e32 v68, v68, v68
	v_mul_f32_e32 v64, v64, v64
	v_mul_f32_e32 v69, v69, v69
	v_mul_f32_e32 v65, v65, v65
	v_mul_f32_e32 v70, v70, v70
	v_mul_f32_e32 v66, v66, v66
	v_mul_f32_e32 v71, v71, v71
	v_mul_f32_e32 v67, v67, v67
	v_max_f32_e32 v56, v56, v56
	v_mul_f32_e32 v82, v76, v76
	v_lshl_add_u64 v[76:77], v[72:73], 0, v[120:121]
	v_cvt_pk_bf16_f32 v67, v66, v67
	v_cvt_pk_bf16_f32 v66, v64, v65
	v_cvt_pk_bf16_f32 v65, v70, v71
	v_cvt_pk_bf16_f32 v64, v68, v69
	v_max_f32_e32 v56, 0, v56
	global_store_dwordx4 v[76:77], v[64:67], off offset:256
	v_max_f32_e32 v57, v57, v57
	v_max_f32_e32 v57, 0, v57
	v_mul_f32_e32 v67, v56, v56
	v_max_f32_e32 v56, v61, v61
	v_max_f32_e32 v56, 0, v56
	v_mul_f32_e32 v68, v56, v56
	v_mul_f32_e32 v69, v57, v57
	v_max_f32_e32 v56, v62, v62
	v_max_f32_e32 v57, v58, v58
	v_add_u32_e32 v64, 0x80, v148
	v_max_f32_e32 v56, 0, v56
	v_max_f32_e32 v57, 0, v57
	v_ashrrev_i32_e32 v65, 31, v64
	v_mul_f32_e32 v62, v56, v56
	v_mul_f32_e32 v58, v57, v57
	v_max_f32_e32 v56, v63, v63
	v_max_f32_e32 v57, v59, v59
	v_max_f32_e32 v52, v52, v52
	v_max_f32_e32 v48, v48, v48
	v_max_f32_e32 v53, v53, v53
	v_max_f32_e32 v49, v49, v49
	v_max_f32_e32 v54, v54, v54
	v_max_f32_e32 v50, v50, v50
	v_max_f32_e32 v55, v55, v55
	v_max_f32_e32 v51, v51, v51
	v_lshlrev_b64 v[64:65], 14, v[64:65]
	v_max_f32_e32 v60, v60, v60
	v_max_f32_e32 v56, 0, v56
	v_max_f32_e32 v57, 0, v57
	v_max_f32_e32 v52, 0, v52
	v_max_f32_e32 v48, 0, v48
	v_max_f32_e32 v53, 0, v53
	v_max_f32_e32 v49, 0, v49
	v_max_f32_e32 v54, 0, v54
	v_max_f32_e32 v50, 0, v50
	v_max_f32_e32 v55, 0, v55
	v_max_f32_e32 v51, 0, v51
	v_max_f32_e32 v60, 0, v60
	v_mul_f32_e32 v63, v56, v56
	v_mul_f32_e32 v59, v57, v57
	v_lshl_add_u64 v[56:57], s[28:29], 0, v[64:65]
	v_mul_f32_e32 v52, v52, v52
	v_mul_f32_e32 v48, v48, v48
	v_mul_f32_e32 v53, v53, v53
	v_mul_f32_e32 v49, v49, v49
	v_mul_f32_e32 v54, v54, v54
	v_mul_f32_e32 v50, v50, v50
	v_mul_f32_e32 v55, v55, v55
	v_mul_f32_e32 v51, v51, v51
	v_max_f32_e32 v40, v40, v40
	v_mul_f32_e32 v66, v60, v60
	v_lshl_add_u64 v[60:61], v[56:57], 0, v[120:121]
	v_cvt_pk_bf16_f32 v51, v50, v51
	v_cvt_pk_bf16_f32 v50, v48, v49
	v_cvt_pk_bf16_f32 v49, v54, v55
	v_cvt_pk_bf16_f32 v48, v52, v53
	v_max_f32_e32 v40, 0, v40
	global_store_dwordx4 v[60:61], v[48:51], off offset:256
	v_max_f32_e32 v41, v41, v41
	v_max_f32_e32 v41, 0, v41
	v_mul_f32_e32 v51, v40, v40
	v_max_f32_e32 v40, v45, v45
	v_max_f32_e32 v40, 0, v40
	v_mul_f32_e32 v52, v40, v40
	v_mul_f32_e32 v53, v41, v41
	v_max_f32_e32 v40, v46, v46
	v_max_f32_e32 v41, v42, v42
	v_add_u32_e32 v48, 0x90, v148
	v_max_f32_e32 v40, 0, v40
	v_max_f32_e32 v41, 0, v41
	v_ashrrev_i32_e32 v49, 31, v48
	v_mul_f32_e32 v46, v40, v40
	v_mul_f32_e32 v42, v41, v41
	v_max_f32_e32 v40, v47, v47
	v_max_f32_e32 v41, v43, v43
	v_max_f32_e32 v36, v36, v36
	v_max_f32_e32 v32, v32, v32
	v_max_f32_e32 v37, v37, v37
	v_max_f32_e32 v33, v33, v33
	v_max_f32_e32 v38, v38, v38
	v_max_f32_e32 v34, v34, v34
	v_max_f32_e32 v39, v39, v39
	v_max_f32_e32 v35, v35, v35
	v_lshlrev_b64 v[48:49], 14, v[48:49]
	v_max_f32_e32 v44, v44, v44
	v_max_f32_e32 v40, 0, v40
	v_max_f32_e32 v41, 0, v41
	v_max_f32_e32 v36, 0, v36
	v_max_f32_e32 v32, 0, v32
	v_max_f32_e32 v37, 0, v37
	v_max_f32_e32 v33, 0, v33
	v_max_f32_e32 v38, 0, v38
	v_max_f32_e32 v34, 0, v34
	v_max_f32_e32 v39, 0, v39
	v_max_f32_e32 v35, 0, v35
	v_max_f32_e32 v44, 0, v44
	v_mul_f32_e32 v47, v40, v40
	v_mul_f32_e32 v43, v41, v41
	v_lshl_add_u64 v[40:41], s[28:29], 0, v[48:49]
	v_mul_f32_e32 v36, v36, v36
	v_mul_f32_e32 v32, v32, v32
	v_mul_f32_e32 v37, v37, v37
	v_mul_f32_e32 v33, v33, v33
	v_mul_f32_e32 v38, v38, v38
	v_mul_f32_e32 v34, v34, v34
	v_mul_f32_e32 v39, v39, v39
	v_mul_f32_e32 v35, v35, v35
	v_max_f32_e32 v24, v24, v24
	v_mul_f32_e32 v50, v44, v44
	v_lshl_add_u64 v[44:45], v[40:41], 0, v[120:121]
	v_cvt_pk_bf16_f32 v35, v34, v35
	v_cvt_pk_bf16_f32 v34, v32, v33
	v_cvt_pk_bf16_f32 v33, v38, v39
	v_cvt_pk_bf16_f32 v32, v36, v37
	v_max_f32_e32 v24, 0, v24
	global_store_dwordx4 v[44:45], v[32:35], off offset:256
	v_max_f32_e32 v25, v25, v25
	v_max_f32_e32 v25, 0, v25
	v_mul_f32_e32 v35, v24, v24
	v_max_f32_e32 v24, v29, v29
	v_max_f32_e32 v24, 0, v24
	v_mul_f32_e32 v36, v24, v24
	v_mul_f32_e32 v37, v25, v25
	v_max_f32_e32 v24, v30, v30
	v_max_f32_e32 v25, v26, v26
	v_add_u32_e32 v32, 0xa0, v148
	v_max_f32_e32 v24, 0, v24
	v_max_f32_e32 v25, 0, v25
	v_ashrrev_i32_e32 v33, 31, v32
	v_mul_f32_e32 v30, v24, v24
	v_mul_f32_e32 v26, v25, v25
	v_max_f32_e32 v24, v31, v31
	v_max_f32_e32 v25, v27, v27
	v_max_f32_e32 v20, v20, v20
	v_max_f32_e32 v16, v16, v16
	v_max_f32_e32 v21, v21, v21
	v_max_f32_e32 v17, v17, v17
	v_max_f32_e32 v22, v22, v22
	v_max_f32_e32 v18, v18, v18
	v_max_f32_e32 v23, v23, v23
	v_max_f32_e32 v19, v19, v19
	v_lshlrev_b64 v[32:33], 14, v[32:33]
	v_max_f32_e32 v28, v28, v28
	v_max_f32_e32 v24, 0, v24
	v_max_f32_e32 v25, 0, v25
	v_max_f32_e32 v20, 0, v20
	v_max_f32_e32 v16, 0, v16
	v_max_f32_e32 v21, 0, v21
	v_max_f32_e32 v17, 0, v17
	v_max_f32_e32 v22, 0, v22
	v_max_f32_e32 v18, 0, v18
	v_max_f32_e32 v23, 0, v23
	v_max_f32_e32 v19, 0, v19
	v_max_f32_e32 v28, 0, v28
	v_mul_f32_e32 v31, v24, v24
	v_mul_f32_e32 v27, v25, v25
	v_lshl_add_u64 v[24:25], s[28:29], 0, v[32:33]
	v_mul_f32_e32 v20, v20, v20
	v_mul_f32_e32 v16, v16, v16
	v_mul_f32_e32 v21, v21, v21
	v_mul_f32_e32 v17, v17, v17
	v_mul_f32_e32 v22, v22, v22
	v_mul_f32_e32 v18, v18, v18
	v_mul_f32_e32 v23, v23, v23
	v_mul_f32_e32 v19, v19, v19
	v_max_f32_e32 v8, v8, v8
	v_mul_f32_e32 v34, v28, v28
	v_lshl_add_u64 v[28:29], v[24:25], 0, v[120:121]
	v_cvt_pk_bf16_f32 v19, v18, v19
	v_cvt_pk_bf16_f32 v18, v16, v17
	v_cvt_pk_bf16_f32 v17, v22, v23
	v_cvt_pk_bf16_f32 v16, v20, v21
	v_max_f32_e32 v8, 0, v8
	global_store_dwordx4 v[28:29], v[16:19], off offset:256
	v_max_f32_e32 v9, v9, v9
	v_max_f32_e32 v9, 0, v9
	v_mul_f32_e32 v19, v8, v8
	v_max_f32_e32 v8, v13, v13
	v_max_f32_e32 v8, 0, v8
	v_mul_f32_e32 v20, v8, v8
	v_mul_f32_e32 v21, v9, v9
	v_max_f32_e32 v8, v14, v14
	v_max_f32_e32 v9, v10, v10
	v_add_u32_e32 v16, 0xb0, v148
	v_max_f32_e32 v8, 0, v8
	v_max_f32_e32 v9, 0, v9
	v_ashrrev_i32_e32 v17, 31, v16
	v_max_f32_e32 v12, v12, v12
	v_mul_f32_e32 v14, v8, v8
	v_mul_f32_e32 v10, v9, v9
	v_max_f32_e32 v8, v15, v15
	v_max_f32_e32 v9, v11, v11
	v_max_f32_e32 v4, v4, v4
	v_max_f32_e32 v0, v0, v0
	v_max_f32_e32 v5, v5, v5
	v_max_f32_e32 v1, v1, v1
	v_max_f32_e32 v6, v6, v6
	v_max_f32_e32 v2, v2, v2
	v_max_f32_e32 v7, v7, v7
	v_max_f32_e32 v3, v3, v3
	v_lshlrev_b64 v[16:17], 14, v[16:17]
	v_max_f32_e32 v12, 0, v12
	v_max_f32_e32 v8, 0, v8
	v_max_f32_e32 v9, 0, v9
	v_max_f32_e32 v4, 0, v4
	v_max_f32_e32 v0, 0, v0
	v_max_f32_e32 v5, 0, v5
	v_max_f32_e32 v1, 0, v1
	v_max_f32_e32 v6, 0, v6
	v_max_f32_e32 v2, 0, v2
	v_max_f32_e32 v7, 0, v7
	v_max_f32_e32 v3, 0, v3
	v_mul_f32_e32 v18, v12, v12
	v_mul_f32_e32 v15, v8, v8
	v_mul_f32_e32 v11, v9, v9
	v_lshl_add_u64 v[8:9], s[28:29], 0, v[16:17]
	v_mul_f32_e32 v4, v4, v4
	v_mul_f32_e32 v0, v0, v0
	v_mul_f32_e32 v5, v5, v5
	v_mul_f32_e32 v1, v1, v1
	v_mul_f32_e32 v6, v6, v6
	v_mul_f32_e32 v2, v2, v2
	v_mul_f32_e32 v7, v7, v7
	v_mul_f32_e32 v3, v3, v3
	v_cvt_pk_bf16_f32 v125, v125, v163
	v_cvt_pk_bf16_f32 v124, v124, v160
	v_cvt_pk_bf16_f32 v123, v161, v162
	v_cvt_pk_bf16_f32 v122, v149, v155
	v_cvt_pk_bf16_f32 v107, v106, v107
	v_cvt_pk_bf16_f32 v106, v115, v117
	v_cvt_pk_bf16_f32 v105, v110, v111
	v_cvt_pk_bf16_f32 v104, v114, v116
	v_cvt_pk_bf16_f32 v91, v90, v91
	v_cvt_pk_bf16_f32 v90, v99, v101
	v_cvt_pk_bf16_f32 v89, v94, v95
	v_cvt_pk_bf16_f32 v88, v98, v100
	v_cvt_pk_bf16_f32 v75, v74, v75
	v_cvt_pk_bf16_f32 v74, v83, v85
	v_cvt_pk_bf16_f32 v73, v78, v79
	v_cvt_pk_bf16_f32 v72, v82, v84
	v_cvt_pk_bf16_f32 v59, v58, v59
	v_cvt_pk_bf16_f32 v58, v67, v69
	v_cvt_pk_bf16_f32 v57, v62, v63
	v_cvt_pk_bf16_f32 v56, v66, v68
	v_cvt_pk_bf16_f32 v43, v42, v43
	v_cvt_pk_bf16_f32 v42, v51, v53
	v_cvt_pk_bf16_f32 v41, v46, v47
	v_cvt_pk_bf16_f32 v40, v50, v52
	v_cvt_pk_bf16_f32 v27, v26, v27
	v_cvt_pk_bf16_f32 v26, v35, v37
	v_cvt_pk_bf16_f32 v25, v30, v31
	v_cvt_pk_bf16_f32 v24, v34, v36
	v_lshl_add_u64 v[12:13], v[8:9], 0, v[120:121]
	v_cvt_pk_bf16_f32 v11, v10, v11
	v_cvt_pk_bf16_f32 v10, v19, v21
	v_cvt_pk_bf16_f32 v9, v14, v15
	v_cvt_pk_bf16_f32 v8, v18, v20
	v_cvt_pk_bf16_f32 v3, v2, v3
	v_cvt_pk_bf16_f32 v2, v0, v1
	v_cvt_pk_bf16_f32 v1, v6, v7
	v_cvt_pk_bf16_f32 v0, v4, v5
	global_store_dwordx4 v[126:127], v[122:125], off
	global_store_dwordx4 v[108:109], v[104:107], off
	global_store_dwordx4 v[92:93], v[88:91], off
	global_store_dwordx4 v[76:77], v[72:75], off
	global_store_dwordx4 v[60:61], v[56:59], off
	global_store_dwordx4 v[44:45], v[40:43], off
	global_store_dwordx4 v[28:29], v[24:27], off
	global_store_dwordx4 v[12:13], v[8:11], off
	global_store_dwordx4 v[12:13], v[0:3], off offset:256

.LBB0_1030:
	ds_read_b128 v[148:151], v159
	ds_read_b128 v[152:155], v159 offset:1024
	ds_read_b128 v[162:165], v159 offset:2048
	ds_read_b128 v[166:169], v159 offset:3072
	s_add_u32 s20, s48, 0xffe00080
	s_addc_u32 s21, s49, -1
	s_cmpk_eq_i32 s63, 0x7c
	s_cselect_b32 s21, s17, s21
	s_cselect_b32 s20, s59, s20
	s_cselect_b32 s51, s15, s62
	s_cselect_b32 s50, s60, s61
	v_lshl_add_u64 v[190:191], s[48:49], 0, v[136:137]
	s_add_i32 m0, s37, 0xc000
	ds_read_b128 v[170:173], v160
	ds_read_b128 v[174:177], v160 offset:1024
	ds_read_b128 v[178:181], v160 offset:2048
	ds_read_b128 v[182:185], v160 offset:3072
	ds_read_b128 v[186:189], v160 offset:4096
	ds_read_b128 v[196:199], v160 offset:5120
	ds_read_b128 v[200:203], v160 offset:6144
	ds_read_b128 v[204:207], v160 offset:7168
	global_load_lds_dwordx4 v[190:191], off
	v_lshl_add_u64 v[190:191], s[48:49], 0, v[138:139]
	s_add_i32 m0, s37, 0xe000
	s_nop 0
	global_load_lds_dwordx4 v[190:191], off
	s_waitcnt lgkmcnt(8)
	s_barrier
	s_waitcnt lgkmcnt(0)
	s_setprio 1
	v_mfma_f32_16x16x32_bf16 v[124:127], v[148:151], v[170:173], v[124:127]
	v_mfma_f32_16x16x32_bf16 v[120:123], v[162:165], v[170:173], v[120:123]
	v_mfma_f32_16x16x32_bf16 v[108:111], v[148:151], v[178:181], v[108:111]
	v_mfma_f32_16x16x32_bf16 v[104:107], v[162:165], v[178:181], v[104:107]
	v_mfma_f32_16x16x32_bf16 v[92:95], v[148:151], v[186:189], v[92:95]
	v_mfma_f32_16x16x32_bf16 v[88:91], v[162:165], v[186:189], v[88:91]
	v_mfma_f32_16x16x32_bf16 v[76:79], v[148:151], v[200:203], v[76:79]
	v_mfma_f32_16x16x32_bf16 v[72:75], v[162:165], v[200:203], v[72:75]
	v_mfma_f32_16x16x32_bf16 v[124:127], v[152:155], v[174:177], v[124:127]
	v_mfma_f32_16x16x32_bf16 v[120:123], v[166:169], v[174:177], v[120:123]
	v_mfma_f32_16x16x32_bf16 v[108:111], v[152:155], v[182:185], v[108:111]
	v_mfma_f32_16x16x32_bf16 v[104:107], v[166:169], v[182:185], v[104:107]
	v_mfma_f32_16x16x32_bf16 v[92:95], v[152:155], v[196:199], v[92:95]
	v_mfma_f32_16x16x32_bf16 v[88:91], v[166:169], v[196:199], v[88:91]
	v_mfma_f32_16x16x32_bf16 v[76:79], v[152:155], v[204:207], v[76:79]
	v_mfma_f32_16x16x32_bf16 v[72:75], v[166:169], v[204:207], v[72:75]
	s_setprio 0
	s_barrier
	s_add_i32 s64, s55, s23
	v_lshl_add_u64 v[190:191], s[50:51], 0, v[132:133]
	s_mov_b32 m0, s64
	ds_read_b128 v[208:211], v161
	ds_read_b128 v[212:215], v161 offset:1024
	ds_read_b128 v[216:219], v161 offset:2048
	ds_read_b128 v[220:223], v161 offset:3072
	global_load_lds_dwordx4 v[190:191], off
	v_lshl_add_u64 v[224:225], s[50:51], 0, v[128:129]
	s_add_i32 m0, s64, 0x2000
	s_nop 0
	global_load_lds_dwordx4 v[224:225], off
	s_barrier
	s_waitcnt lgkmcnt(0)
	s_setprio 1
	v_mfma_f32_16x16x32_bf16 v[116:119], v[208:211], v[170:173], v[116:119]
	v_mfma_f32_16x16x32_bf16 v[112:115], v[216:219], v[170:173], v[112:115]
	v_mfma_f32_16x16x32_bf16 v[100:103], v[208:211], v[178:181], v[100:103]
	v_mfma_f32_16x16x32_bf16 v[96:99], v[216:219], v[178:181], v[96:99]
	v_mfma_f32_16x16x32_bf16 v[84:87], v[208:211], v[186:189], v[84:87]
	v_mfma_f32_16x16x32_bf16 v[80:83], v[216:219], v[186:189], v[80:83]
	v_mfma_f32_16x16x32_bf16 v[68:71], v[208:211], v[200:203], v[68:71]
	v_mfma_f32_16x16x32_bf16 v[64:67], v[216:219], v[200:203], v[64:67]
	v_mfma_f32_16x16x32_bf16 v[116:119], v[212:215], v[174:177], v[116:119]
	v_mfma_f32_16x16x32_bf16 v[112:115], v[220:223], v[174:177], v[112:115]
	v_mfma_f32_16x16x32_bf16 v[100:103], v[212:215], v[182:185], v[100:103]
	v_mfma_f32_16x16x32_bf16 v[96:99], v[220:223], v[182:185], v[96:99]
	v_mfma_f32_16x16x32_bf16 v[84:87], v[212:215], v[196:199], v[84:87]
	v_mfma_f32_16x16x32_bf16 v[80:83], v[220:223], v[196:199], v[80:83]
	v_mfma_f32_16x16x32_bf16 v[68:71], v[212:215], v[204:207], v[68:71]
	v_mfma_f32_16x16x32_bf16 v[64:67], v[220:223], v[204:207], v[64:67]
	s_setprio 0
	s_mov_b32 m0, s37
	v_lshl_add_u64 v[226:227], s[20:21], 0, v[134:135]
	s_barrier
	ds_read_b128 v[170:173], v160 offset:16384
	ds_read_b128 v[174:177], v160 offset:17408
	ds_read_b128 v[178:181], v160 offset:18432
	ds_read_b128 v[182:185], v160 offset:19456
	ds_read_b128 v[186:189], v160 offset:20480
	ds_read_b128 v[196:199], v160 offset:21504
	ds_read_b128 v[200:203], v160 offset:22528
	ds_read_b128 v[204:207], v160 offset:23552
	global_load_lds_dwordx4 v[226:227], off
	v_lshl_add_u64 v[228:229], s[20:21], 0, v[130:131]
	s_mov_b32 m0, s38
	s_nop 0
	global_load_lds_dwordx4 v[228:229], off
	s_barrier
	s_waitcnt lgkmcnt(0)
	s_setprio 1
	v_mfma_f32_16x16x32_bf16 v[60:63], v[148:151], v[170:173], v[60:63]
	v_mfma_f32_16x16x32_bf16 v[56:59], v[162:165], v[170:173], v[56:59]
	v_mfma_f32_16x16x32_bf16 v[44:47], v[148:151], v[178:181], v[44:47]
	v_mfma_f32_16x16x32_bf16 v[40:43], v[162:165], v[178:181], v[40:43]
	v_mfma_f32_16x16x32_bf16 v[28:31], v[148:151], v[186:189], v[28:31]
	v_mfma_f32_16x16x32_bf16 v[24:27], v[162:165], v[186:189], v[24:27]
	v_mfma_f32_16x16x32_bf16 v[12:15], v[148:151], v[200:203], v[12:15]
	v_mfma_f32_16x16x32_bf16 v[8:11], v[162:165], v[200:203], v[8:11]
	v_mfma_f32_16x16x32_bf16 v[60:63], v[152:155], v[174:177], v[60:63]
	v_mfma_f32_16x16x32_bf16 v[56:59], v[166:169], v[174:177], v[56:59]
	v_mfma_f32_16x16x32_bf16 v[44:47], v[152:155], v[182:185], v[44:47]
	v_mfma_f32_16x16x32_bf16 v[40:43], v[166:169], v[182:185], v[40:43]
	v_mfma_f32_16x16x32_bf16 v[28:31], v[152:155], v[196:199], v[28:31]
	v_mfma_f32_16x16x32_bf16 v[24:27], v[166:169], v[196:199], v[24:27]
	v_mfma_f32_16x16x32_bf16 v[12:15], v[152:155], v[204:207], v[12:15]
	v_mfma_f32_16x16x32_bf16 v[8:11], v[166:169], v[204:207], v[8:11]
	s_setprio 0
	s_barrier
	s_add_u32 s64, s50, 0x200000
	s_addc_u32 s65, s51, 0
	s_add_i32 s66, s57, s23
	v_lshl_add_u64 v[148:149], s[64:65], 0, v[132:133]
	s_mov_b32 m0, s66
	s_nop 0
	global_load_lds_dwordx4 v[148:149], off
	v_lshl_add_u64 v[148:149], s[64:65], 0, v[128:129]
	s_add_i32 m0, s66, 0x2000
	s_nop 0
	global_load_lds_dwordx4 v[148:149], off
	s_waitcnt vmcnt(6)
	s_barrier
	s_setprio 1
	v_mfma_f32_16x16x32_bf16 v[52:55], v[208:211], v[170:173], v[52:55]
	v_mfma_f32_16x16x32_bf16 v[48:51], v[216:219], v[170:173], v[48:51]
	v_mfma_f32_16x16x32_bf16 v[36:39], v[208:211], v[178:181], v[36:39]
	v_mfma_f32_16x16x32_bf16 v[32:35], v[216:219], v[178:181], v[32:35]
	v_mfma_f32_16x16x32_bf16 v[20:23], v[208:211], v[186:189], v[20:23]
	v_mfma_f32_16x16x32_bf16 v[16:19], v[216:219], v[186:189], v[16:19]
	v_mfma_f32_16x16x32_bf16 v[4:7], v[208:211], v[200:203], v[4:7]
	v_mfma_f32_16x16x32_bf16 v[0:3], v[216:219], v[200:203], v[0:3]
	v_mfma_f32_16x16x32_bf16 v[52:55], v[212:215], v[174:177], v[52:55]
	v_mfma_f32_16x16x32_bf16 v[48:51], v[220:223], v[174:177], v[48:51]
	v_mfma_f32_16x16x32_bf16 v[36:39], v[212:215], v[182:185], v[36:39]
	v_mfma_f32_16x16x32_bf16 v[32:35], v[220:223], v[182:185], v[32:35]
	v_mfma_f32_16x16x32_bf16 v[20:23], v[212:215], v[196:199], v[20:23]
	v_mfma_f32_16x16x32_bf16 v[16:19], v[220:223], v[196:199], v[16:19]
	v_mfma_f32_16x16x32_bf16 v[4:7], v[212:215], v[204:207], v[4:7]
	v_mfma_f32_16x16x32_bf16 v[0:3], v[220:223], v[204:207], v[0:3]
	s_setprio 0
	s_add_i32 s64, 0, 0x18000
	v_add_u32_e32 v166, s64, v156
	s_barrier
	ds_read_b128 v[148:151], v166
	ds_read_b128 v[152:155], v166 offset:1024
	ds_read_b128 v[162:165], v166 offset:2048
	ds_read_b128 v[166:169], v166 offset:3072
	s_add_u32 s20, s20, 0x200000
	s_addc_u32 s21, s21, 0
	s_mov_b32 m0, s39
	v_lshl_add_u64 v[208:209], s[20:21], 0, v[134:135]
	ds_read_b128 v[170:173], v160 offset:32768
	ds_read_b128 v[174:177], v160 offset:33792
	ds_read_b128 v[178:181], v160 offset:34816
	ds_read_b128 v[182:185], v160 offset:35840
	ds_read_b128 v[186:189], v160 offset:36864
	ds_read_b128 v[196:199], v160 offset:37888
	ds_read_b128 v[200:203], v160 offset:38912
	ds_read_b128 v[204:207], v160 offset:39936
	global_load_lds_dwordx4 v[208:209], off
	v_lshl_add_u64 v[208:209], s[20:21], 0, v[130:131]
	s_mov_b32 m0, s47
	s_nop 0
	global_load_lds_dwordx4 v[208:209], off
	s_waitcnt lgkmcnt(8)
	s_barrier
	s_waitcnt lgkmcnt(0)
	s_setprio 1
	v_mfma_f32_16x16x32_bf16 v[124:127], v[148:151], v[170:173], v[124:127]
	v_mfma_f32_16x16x32_bf16 v[120:123], v[162:165], v[170:173], v[120:123]
	v_mfma_f32_16x16x32_bf16 v[108:111], v[148:151], v[178:181], v[108:111]
	v_mfma_f32_16x16x32_bf16 v[104:107], v[162:165], v[178:181], v[104:107]
	v_mfma_f32_16x16x32_bf16 v[92:95], v[148:151], v[186:189], v[92:95]
	v_mfma_f32_16x16x32_bf16 v[88:91], v[162:165], v[186:189], v[88:91]
	v_mfma_f32_16x16x32_bf16 v[76:79], v[148:151], v[200:203], v[76:79]
	v_mfma_f32_16x16x32_bf16 v[72:75], v[162:165], v[200:203], v[72:75]
	v_mfma_f32_16x16x32_bf16 v[124:127], v[152:155], v[174:177], v[124:127]
	v_mfma_f32_16x16x32_bf16 v[120:123], v[166:169], v[174:177], v[120:123]
	v_mfma_f32_16x16x32_bf16 v[108:111], v[152:155], v[182:185], v[108:111]
	v_mfma_f32_16x16x32_bf16 v[104:107], v[166:169], v[182:185], v[104:107]
	v_mfma_f32_16x16x32_bf16 v[92:95], v[152:155], v[196:199], v[92:95]
	v_mfma_f32_16x16x32_bf16 v[88:91], v[166:169], v[196:199], v[88:91]
	v_mfma_f32_16x16x32_bf16 v[76:79], v[152:155], v[204:207], v[76:79]
	v_mfma_f32_16x16x32_bf16 v[72:75], v[166:169], v[204:207], v[72:75]
	s_setprio 0
	s_barrier
	s_add_i32 s65, 0, 0x1c000
	s_add_i32 s20, s64, s23
	v_add_u32_e32 v195, s65, v156
	v_lshl_add_u64 v[190:191], v[190:191], 0, s[10:11]
	s_mov_b32 m0, s20
	ds_read_b128 v[208:211], v195
	ds_read_b128 v[212:215], v195 offset:1024
	ds_read_b128 v[216:219], v195 offset:2048
	ds_read_b128 v[220:223], v195 offset:3072
	global_load_lds_dwordx4 v[190:191], off
	v_lshl_add_u64 v[190:191], v[224:225], 0, s[10:11]
	s_add_i32 m0, s20, 0x2000
	s_nop 0
	global_load_lds_dwordx4 v[190:191], off
	s_barrier
	s_waitcnt lgkmcnt(0)
	s_setprio 1
	v_mfma_f32_16x16x32_bf16 v[116:119], v[208:211], v[170:173], v[116:119]
	v_mfma_f32_16x16x32_bf16 v[112:115], v[216:219], v[170:173], v[112:115]
	v_mfma_f32_16x16x32_bf16 v[100:103], v[208:211], v[178:181], v[100:103]
	v_mfma_f32_16x16x32_bf16 v[96:99], v[216:219], v[178:181], v[96:99]
	v_mfma_f32_16x16x32_bf16 v[84:87], v[208:211], v[186:189], v[84:87]
	v_mfma_f32_16x16x32_bf16 v[80:83], v[216:219], v[186:189], v[80:83]
	v_mfma_f32_16x16x32_bf16 v[68:71], v[208:211], v[200:203], v[68:71]
	v_mfma_f32_16x16x32_bf16 v[64:67], v[216:219], v[200:203], v[64:67]
	v_mfma_f32_16x16x32_bf16 v[116:119], v[212:215], v[174:177], v[116:119]
	v_mfma_f32_16x16x32_bf16 v[112:115], v[220:223], v[174:177], v[112:115]
	v_mfma_f32_16x16x32_bf16 v[100:103], v[212:215], v[182:185], v[100:103]
	v_mfma_f32_16x16x32_bf16 v[96:99], v[220:223], v[182:185], v[96:99]
	v_mfma_f32_16x16x32_bf16 v[84:87], v[212:215], v[196:199], v[84:87]
	v_mfma_f32_16x16x32_bf16 v[80:83], v[220:223], v[196:199], v[80:83]
	v_mfma_f32_16x16x32_bf16 v[68:71], v[212:215], v[204:207], v[68:71]
	v_mfma_f32_16x16x32_bf16 v[64:67], v[220:223], v[204:207], v[64:67]
	s_setprio 0
	s_mov_b32 m0, s34
	v_lshl_add_u64 v[190:191], v[226:227], 0, s[10:11]
	s_barrier
	ds_read_b128 v[170:173], v160 offset:49152
	ds_read_b128 v[174:177], v160 offset:50176
	ds_read_b128 v[178:181], v160 offset:51200
	ds_read_b128 v[182:185], v160 offset:52224
	ds_read_b128 v[186:189], v160 offset:53248
	ds_read_b128 v[196:199], v160 offset:54272
	ds_read_b128 v[200:203], v160 offset:55296
	ds_read_b128 v[204:207], v160 offset:56320
	global_load_lds_dwordx4 v[190:191], off
	v_lshl_add_u64 v[190:191], v[228:229], 0, s[10:11]
	s_mov_b32 m0, s35
	s_nop 0
	global_load_lds_dwordx4 v[190:191], off
	s_barrier
	s_waitcnt lgkmcnt(0)
	s_setprio 1
	v_mfma_f32_16x16x32_bf16 v[60:63], v[148:151], v[170:173], v[60:63]
	v_mfma_f32_16x16x32_bf16 v[56:59], v[162:165], v[170:173], v[56:59]
	v_mfma_f32_16x16x32_bf16 v[44:47], v[148:151], v[178:181], v[44:47]
	v_mfma_f32_16x16x32_bf16 v[40:43], v[162:165], v[178:181], v[40:43]
	v_mfma_f32_16x16x32_bf16 v[28:31], v[148:151], v[186:189], v[28:31]
	v_mfma_f32_16x16x32_bf16 v[24:27], v[162:165], v[186:189], v[24:27]
	v_mfma_f32_16x16x32_bf16 v[12:15], v[148:151], v[200:203], v[12:15]
	v_mfma_f32_16x16x32_bf16 v[8:11], v[162:165], v[200:203], v[8:11]
	v_mfma_f32_16x16x32_bf16 v[60:63], v[152:155], v[174:177], v[60:63]
	v_mfma_f32_16x16x32_bf16 v[56:59], v[166:169], v[174:177], v[56:59]
	v_mfma_f32_16x16x32_bf16 v[44:47], v[152:155], v[182:185], v[44:47]
	v_mfma_f32_16x16x32_bf16 v[40:43], v[166:169], v[182:185], v[40:43]
	v_mfma_f32_16x16x32_bf16 v[28:31], v[152:155], v[196:199], v[28:31]
	v_mfma_f32_16x16x32_bf16 v[24:27], v[166:169], v[196:199], v[24:27]
	v_mfma_f32_16x16x32_bf16 v[12:15], v[152:155], v[204:207], v[12:15]
	v_mfma_f32_16x16x32_bf16 v[8:11], v[166:169], v[204:207], v[8:11]
	s_setprio 0
	s_barrier
	s_add_u32 s20, s50, 0x200080
	s_addc_u32 s21, s51, 0
	s_add_i32 s50, s65, s23
	v_lshl_add_u64 v[148:149], s[20:21], 0, v[132:133]
	s_mov_b32 m0, s50
	s_nop 0
	global_load_lds_dwordx4 v[148:149], off
	v_lshl_add_u64 v[148:149], s[20:21], 0, v[128:129]
	s_add_i32 m0, s50, 0x2000
	s_nop 0
	global_load_lds_dwordx4 v[148:149], off
	s_waitcnt vmcnt(6)
	s_barrier
	s_setprio 1
	v_mfma_f32_16x16x32_bf16 v[52:55], v[208:211], v[170:173], v[52:55]
	v_mfma_f32_16x16x32_bf16 v[48:51], v[216:219], v[170:173], v[48:51]
	v_mfma_f32_16x16x32_bf16 v[36:39], v[208:211], v[178:181], v[36:39]
	v_mfma_f32_16x16x32_bf16 v[32:35], v[216:219], v[178:181], v[32:35]
	v_mfma_f32_16x16x32_bf16 v[20:23], v[208:211], v[186:189], v[20:23]
	v_mfma_f32_16x16x32_bf16 v[16:19], v[216:219], v[186:189], v[16:19]
	v_mfma_f32_16x16x32_bf16 v[4:7], v[208:211], v[200:203], v[4:7]
	v_mfma_f32_16x16x32_bf16 v[0:3], v[216:219], v[200:203], v[0:3]
	v_mfma_f32_16x16x32_bf16 v[52:55], v[212:215], v[174:177], v[52:55]
	v_mfma_f32_16x16x32_bf16 v[48:51], v[220:223], v[174:177], v[48:51]
	v_mfma_f32_16x16x32_bf16 v[36:39], v[212:215], v[182:185], v[36:39]
	v_mfma_f32_16x16x32_bf16 v[32:35], v[220:223], v[182:185], v[32:35]
	v_mfma_f32_16x16x32_bf16 v[20:23], v[212:215], v[196:199], v[20:23]
	v_mfma_f32_16x16x32_bf16 v[16:19], v[220:223], v[196:199], v[16:19]
	v_mfma_f32_16x16x32_bf16 v[4:7], v[212:215], v[204:207], v[4:7]
	v_mfma_f32_16x16x32_bf16 v[0:3], v[220:223], v[204:207], v[0:3]
	s_setprio 0
	s_add_i32 s63, s63, 2
	s_add_u32 s48, s48, 0x100
	s_addc_u32 s49, s49, 0
	s_add_u32 s61, s61, 0x100
	s_addc_u32 s62, s62, 0
	s_cmpk_gt_u32 s63, 0x7d
	s_cbranch_scc0 .Lepi_nl_mlpout0
	s_cmp_lg_u32 s53, 64
	s_cbranch_scc1 .Lepi_nl_mlpout0
	s_lshl_b32 s15, s46, 8
	s_add_i32 s15, s15, s53
	v_or_b32_e32 v154, s15, v147
	s_add_i32 s17, s15, 0xffffe000
	v_lshl_or_b32 v150, s33, 8, v158
	s_lshr_b32 s17, s17, 12
	v_lshlrev_b32_e32 v148, 12, v154
	s_add_i32 s17, s17, 1
	s_cmp_gt_i32 s15, s58
	s_cselect_b32 s17, s17, 0
	s_mul_i32 s17, s17, s56
	v_lshl_add_u32 v148, v150, 1, v148
	s_add_u32 s20, s8, s17
	s_addc_u32 s21, s9, 0
	v_lshlrev_b32_e32 v149, 2, v150
	s_nop 0
	global_load_dwordx4 v[196:199], v149, s[20:21]
	global_load_dwordx4 v[200:203], v149, s[20:21] offset:16
	global_load_dwordx4 v[204:207], v149, s[20:21] offset:512
	global_load_dwordx4 v[208:211], v149, s[20:21] offset:528
	global_load_dwordx4 v[212:215], v148, s[74:75]
	global_load_dwordx4 v[216:219], v148, s[74:75] offset:256
	v_add_u32_e32 v151, 0x10000, v148
	global_load_dwordx4 v[220:223], v151, s[74:75]
	global_load_dwordx4 v[224:227], v151, s[74:75] offset:256
	v_add_u32_e32 v151, 0x20000, v148
	global_load_dwordx4 v[164:167], v151, s[74:75]
	global_load_dwordx4 v[168:171], v151, s[74:75] offset:256
	v_add_u32_e32 v151, 0x30000, v148
	global_load_dwordx4 v[172:175], v151, s[74:75]
	global_load_dwordx4 v[176:179], v151, s[74:75] offset:256
	s_waitcnt vmcnt(0)
	v_lshlrev_b32_e32 v180, 16, v212
	v_and_b32_e32 v181, 0xffff0000, v212
	v_lshlrev_b32_e32 v182, 16, v213
	v_and_b32_e32 v183, 0xffff0000, v213
	v_lshlrev_b32_e32 v184, 16, v214
	v_and_b32_e32 v185, 0xffff0000, v214
	v_lshlrev_b32_e32 v186, 16, v215
	v_and_b32_e32 v187, 0xffff0000, v215
	v_pk_fma_f32 v[124:125], v[124:125], v[196:197], v[180:181]
	v_pk_fma_f32 v[126:127], v[126:127], v[198:199], v[182:183]
	v_pk_fma_f32 v[120:121], v[120:121], v[200:201], v[184:185]
	v_pk_fma_f32 v[122:123], v[122:123], v[202:203], v[186:187]
	v_cvt_pk_bf16_f32 v123, v122, v123
	v_cvt_pk_bf16_f32 v122, v120, v121
	v_cvt_pk_bf16_f32 v121, v126, v127
	v_cvt_pk_bf16_f32 v120, v124, v125
	global_store_dwordx4 v148, v[120:123], s[74:75]
	v_lshlrev_b32_e32 v180, 16, v216
	v_and_b32_e32 v181, 0xffff0000, v216
	v_lshlrev_b32_e32 v182, 16, v217
	v_and_b32_e32 v183, 0xffff0000, v217
	v_lshlrev_b32_e32 v184, 16, v218
	v_and_b32_e32 v185, 0xffff0000, v218
	v_lshlrev_b32_e32 v186, 16, v219
	v_and_b32_e32 v187, 0xffff0000, v219
	v_pk_fma_f32 v[116:117], v[116:117], v[204:205], v[180:181]
	v_pk_fma_f32 v[118:119], v[118:119], v[206:207], v[182:183]
	v_pk_fma_f32 v[112:113], v[112:113], v[208:209], v[184:185]
	v_pk_fma_f32 v[114:115], v[114:115], v[210:211], v[186:187]
	v_cvt_pk_bf16_f32 v115, v114, v115
	v_cvt_pk_bf16_f32 v114, v112, v113
	v_cvt_pk_bf16_f32 v113, v118, v119
	v_cvt_pk_bf16_f32 v112, v116, v117
	global_store_dwordx4 v148, v[112:115], s[74:75] offset:256
	v_lshlrev_b32_e32 v180, 16, v220
	v_and_b32_e32 v181, 0xffff0000, v220
	v_lshlrev_b32_e32 v182, 16, v221
	v_and_b32_e32 v183, 0xffff0000, v221
	v_lshlrev_b32_e32 v184, 16, v222
	v_and_b32_e32 v185, 0xffff0000, v222
	v_lshlrev_b32_e32 v186, 16, v223
	v_and_b32_e32 v187, 0xffff0000, v223
	v_pk_fma_f32 v[108:109], v[108:109], v[196:197], v[180:181]
	v_pk_fma_f32 v[110:111], v[110:111], v[198:199], v[182:183]
	v_pk_fma_f32 v[104:105], v[104:105], v[200:201], v[184:185]
	v_pk_fma_f32 v[106:107], v[106:107], v[202:203], v[186:187]
	v_cvt_pk_bf16_f32 v107, v106, v107
	v_cvt_pk_bf16_f32 v106, v104, v105
	v_cvt_pk_bf16_f32 v105, v110, v111
	v_cvt_pk_bf16_f32 v104, v108, v109
	v_add_u32_e32 v151, 0x10000, v148
	global_store_dwordx4 v151, v[104:107], s[74:75]
	v_lshlrev_b32_e32 v180, 16, v224
	v_and_b32_e32 v181, 0xffff0000, v224
	v_lshlrev_b32_e32 v182, 16, v225
	v_and_b32_e32 v183, 0xffff0000, v225
	v_lshlrev_b32_e32 v184, 16, v226
	v_and_b32_e32 v185, 0xffff0000, v226
	v_lshlrev_b32_e32 v186, 16, v227
	v_and_b32_e32 v187, 0xffff0000, v227
	v_pk_fma_f32 v[100:101], v[100:101], v[204:205], v[180:181]
	v_pk_fma_f32 v[102:103], v[102:103], v[206:207], v[182:183]
	v_pk_fma_f32 v[96:97], v[96:97], v[208:209], v[184:185]
	v_pk_fma_f32 v[98:99], v[98:99], v[210:211], v[186:187]
	v_cvt_pk_bf16_f32 v99, v98, v99
	v_cvt_pk_bf16_f32 v98, v96, v97
	v_cvt_pk_bf16_f32 v97, v102, v103
	v_cvt_pk_bf16_f32 v96, v100, v101
	v_add_u32_e32 v151, 0x10000, v148
	global_store_dwordx4 v151, v[96:99], s[74:75] offset:256
	v_add_u32_e32 v151, 0x80000, v148
	global_load_dwordx4 v[212:215], v151, s[74:75]
	global_load_dwordx4 v[216:219], v151, s[74:75] offset:256
	v_add_u32_e32 v151, 0x90000, v148
	global_load_dwordx4 v[220:223], v151, s[74:75]
	global_load_dwordx4 v[224:227], v151, s[74:75] offset:256
	v_lshlrev_b32_e32 v180, 16, v164
	v_and_b32_e32 v181, 0xffff0000, v164
	v_lshlrev_b32_e32 v182, 16, v165
	v_and_b32_e32 v183, 0xffff0000, v165
	v_lshlrev_b32_e32 v184, 16, v166
	v_and_b32_e32 v185, 0xffff0000, v166
	v_lshlrev_b32_e32 v186, 16, v167
	v_and_b32_e32 v187, 0xffff0000, v167
	v_pk_fma_f32 v[92:93], v[92:93], v[196:197], v[180:181]
	v_pk_fma_f32 v[94:95], v[94:95], v[198:199], v[182:183]
	v_pk_fma_f32 v[88:89], v[88:89], v[200:201], v[184:185]
	v_pk_fma_f32 v[90:91], v[90:91], v[202:203], v[186:187]
	v_cvt_pk_bf16_f32 v91, v90, v91
	v_cvt_pk_bf16_f32 v90, v88, v89
	v_cvt_pk_bf16_f32 v89, v94, v95
	v_cvt_pk_bf16_f32 v88, v92, v93
	v_add_u32_e32 v151, 0x20000, v148
	global_store_dwordx4 v151, v[88:91], s[74:75]
	v_lshlrev_b32_e32 v180, 16, v168
	v_and_b32_e32 v181, 0xffff0000, v168
	v_lshlrev_b32_e32 v182, 16, v169
	v_and_b32_e32 v183, 0xffff0000, v169
	v_lshlrev_b32_e32 v184, 16, v170
	v_and_b32_e32 v185, 0xffff0000, v170
	v_lshlrev_b32_e32 v186, 16, v171
	v_and_b32_e32 v187, 0xffff0000, v171
	v_pk_fma_f32 v[84:85], v[84:85], v[204:205], v[180:181]
	v_pk_fma_f32 v[86:87], v[86:87], v[206:207], v[182:183]
	v_pk_fma_f32 v[80:81], v[80:81], v[208:209], v[184:185]
	v_pk_fma_f32 v[82:83], v[82:83], v[210:211], v[186:187]
	v_cvt_pk_bf16_f32 v83, v82, v83
	v_cvt_pk_bf16_f32 v82, v80, v81
	v_cvt_pk_bf16_f32 v81, v86, v87
	v_cvt_pk_bf16_f32 v80, v84, v85
	v_add_u32_e32 v151, 0x20000, v148
	global_store_dwordx4 v151, v[80:83], s[74:75] offset:256
	v_lshlrev_b32_e32 v180, 16, v172
	v_and_b32_e32 v181, 0xffff0000, v172
	v_lshlrev_b32_e32 v182, 16, v173
	v_and_b32_e32 v183, 0xffff0000, v173
	v_lshlrev_b32_e32 v184, 16, v174
	v_and_b32_e32 v185, 0xffff0000, v174
	v_lshlrev_b32_e32 v186, 16, v175
	v_and_b32_e32 v187, 0xffff0000, v175
	v_pk_fma_f32 v[76:77], v[76:77], v[196:197], v[180:181]
	v_pk_fma_f32 v[78:79], v[78:79], v[198:199], v[182:183]
	v_pk_fma_f32 v[72:73], v[72:73], v[200:201], v[184:185]
	v_pk_fma_f32 v[74:75], v[74:75], v[202:203], v[186:187]
	v_cvt_pk_bf16_f32 v75, v74, v75
	v_cvt_pk_bf16_f32 v74, v72, v73
	v_cvt_pk_bf16_f32 v73, v78, v79
	v_cvt_pk_bf16_f32 v72, v76, v77
	v_add_u32_e32 v151, 0x30000, v148
	global_store_dwordx4 v151, v[72:75], s[74:75]
	v_lshlrev_b32_e32 v180, 16, v176
	v_and_b32_e32 v181, 0xffff0000, v176
	v_lshlrev_b32_e32 v182, 16, v177
	v_and_b32_e32 v183, 0xffff0000, v177
	v_lshlrev_b32_e32 v184, 16, v178
	v_and_b32_e32 v185, 0xffff0000, v178
	v_lshlrev_b32_e32 v186, 16, v179
	v_and_b32_e32 v187, 0xffff0000, v179
	v_pk_fma_f32 v[68:69], v[68:69], v[204:205], v[180:181]
	v_pk_fma_f32 v[70:71], v[70:71], v[206:207], v[182:183]
	v_pk_fma_f32 v[64:65], v[64:65], v[208:209], v[184:185]
	v_pk_fma_f32 v[66:67], v[66:67], v[210:211], v[186:187]
	v_cvt_pk_bf16_f32 v67, v66, v67
	v_cvt_pk_bf16_f32 v66, v64, v65
	v_cvt_pk_bf16_f32 v65, v70, v71
	v_cvt_pk_bf16_f32 v64, v68, v69
	v_add_u32_e32 v151, 0x30000, v148
	global_store_dwordx4 v151, v[64:67], s[74:75] offset:256
	v_add_u32_e32 v151, 0xa0000, v148
	global_load_dwordx4 v[164:167], v151, s[74:75]
	global_load_dwordx4 v[168:171], v151, s[74:75] offset:256
	v_add_u32_e32 v151, 0xb0000, v148
	global_load_dwordx4 v[172:175], v151, s[74:75]
	global_load_dwordx4 v[176:179], v151, s[74:75] offset:256
	s_waitcnt vmcnt(0)
	v_lshlrev_b32_e32 v180, 16, v212
	v_and_b32_e32 v181, 0xffff0000, v212
	v_lshlrev_b32_e32 v182, 16, v213
	v_and_b32_e32 v183, 0xffff0000, v213
	v_lshlrev_b32_e32 v184, 16, v214
	v_and_b32_e32 v185, 0xffff0000, v214
	v_lshlrev_b32_e32 v186, 16, v215
	v_and_b32_e32 v187, 0xffff0000, v215
	v_pk_fma_f32 v[60:61], v[60:61], v[196:197], v[180:181]
	v_pk_fma_f32 v[62:63], v[62:63], v[198:199], v[182:183]
	v_pk_fma_f32 v[56:57], v[56:57], v[200:201], v[184:185]
	v_pk_fma_f32 v[58:59], v[58:59], v[202:203], v[186:187]
	v_cvt_pk_bf16_f32 v59, v58, v59
	v_cvt_pk_bf16_f32 v58, v56, v57
	v_cvt_pk_bf16_f32 v57, v62, v63
	v_cvt_pk_bf16_f32 v56, v60, v61
	v_add_u32_e32 v151, 0x80000, v148
	global_store_dwordx4 v151, v[56:59], s[74:75]
	v_lshlrev_b32_e32 v180, 16, v216
	v_and_b32_e32 v181, 0xffff0000, v216
	v_lshlrev_b32_e32 v182, 16, v217
	v_and_b32_e32 v183, 0xffff0000, v217
	v_lshlrev_b32_e32 v184, 16, v218
	v_and_b32_e32 v185, 0xffff0000, v218
	v_lshlrev_b32_e32 v186, 16, v219
	v_and_b32_e32 v187, 0xffff0000, v219
	v_pk_fma_f32 v[52:53], v[52:53], v[204:205], v[180:181]
	v_pk_fma_f32 v[54:55], v[54:55], v[206:207], v[182:183]
	v_pk_fma_f32 v[48:49], v[48:49], v[208:209], v[184:185]
	v_pk_fma_f32 v[50:51], v[50:51], v[210:211], v[186:187]
	v_cvt_pk_bf16_f32 v51, v50, v51
	v_cvt_pk_bf16_f32 v50, v48, v49
	v_cvt_pk_bf16_f32 v49, v54, v55
	v_cvt_pk_bf16_f32 v48, v52, v53
	v_add_u32_e32 v151, 0x80000, v148
	global_store_dwordx4 v151, v[48:51], s[74:75] offset:256
	v_lshlrev_b32_e32 v180, 16, v220
	v_and_b32_e32 v181, 0xffff0000, v220
	v_lshlrev_b32_e32 v182, 16, v221
	v_and_b32_e32 v183, 0xffff0000, v221
	v_lshlrev_b32_e32 v184, 16, v222
	v_and_b32_e32 v185, 0xffff0000, v222
	v_lshlrev_b32_e32 v186, 16, v223
	v_and_b32_e32 v187, 0xffff0000, v223
	v_pk_fma_f32 v[44:45], v[44:45], v[196:197], v[180:181]
	v_pk_fma_f32 v[46:47], v[46:47], v[198:199], v[182:183]
	v_pk_fma_f32 v[40:41], v[40:41], v[200:201], v[184:185]
	v_pk_fma_f32 v[42:43], v[42:43], v[202:203], v[186:187]
	v_cvt_pk_bf16_f32 v43, v42, v43
	v_cvt_pk_bf16_f32 v42, v40, v41
	v_cvt_pk_bf16_f32 v41, v46, v47
	v_cvt_pk_bf16_f32 v40, v44, v45
	v_add_u32_e32 v151, 0x90000, v148
	global_store_dwordx4 v151, v[40:43], s[74:75]
	v_lshlrev_b32_e32 v180, 16, v224
	v_and_b32_e32 v181, 0xffff0000, v224
	v_lshlrev_b32_e32 v182, 16, v225
	v_and_b32_e32 v183, 0xffff0000, v225
	v_lshlrev_b32_e32 v184, 16, v226
	v_and_b32_e32 v185, 0xffff0000, v226
	v_lshlrev_b32_e32 v186, 16, v227
	v_and_b32_e32 v187, 0xffff0000, v227
	v_pk_fma_f32 v[36:37], v[36:37], v[204:205], v[180:181]
	v_pk_fma_f32 v[38:39], v[38:39], v[206:207], v[182:183]
	v_pk_fma_f32 v[32:33], v[32:33], v[208:209], v[184:185]
	v_pk_fma_f32 v[34:35], v[34:35], v[210:211], v[186:187]
	v_cvt_pk_bf16_f32 v35, v34, v35
	v_cvt_pk_bf16_f32 v34, v32, v33
	v_cvt_pk_bf16_f32 v33, v38, v39
	v_cvt_pk_bf16_f32 v32, v36, v37
	v_add_u32_e32 v151, 0x90000, v148
	global_store_dwordx4 v151, v[32:35], s[74:75] offset:256
	v_lshlrev_b32_e32 v180, 16, v164
	v_and_b32_e32 v181, 0xffff0000, v164
	v_lshlrev_b32_e32 v182, 16, v165
	v_and_b32_e32 v183, 0xffff0000, v165
	v_lshlrev_b32_e32 v184, 16, v166
	v_and_b32_e32 v185, 0xffff0000, v166
	v_lshlrev_b32_e32 v186, 16, v167
	v_and_b32_e32 v187, 0xffff0000, v167
	v_pk_fma_f32 v[28:29], v[28:29], v[196:197], v[180:181]
	v_pk_fma_f32 v[30:31], v[30:31], v[198:199], v[182:183]
	v_pk_fma_f32 v[24:25], v[24:25], v[200:201], v[184:185]
	v_pk_fma_f32 v[26:27], v[26:27], v[202:203], v[186:187]
	v_cvt_pk_bf16_f32 v27, v26, v27
	v_cvt_pk_bf16_f32 v26, v24, v25
	v_cvt_pk_bf16_f32 v25, v30, v31
	v_cvt_pk_bf16_f32 v24, v28, v29
	v_add_u32_e32 v151, 0xa0000, v148
	global_store_dwordx4 v151, v[24:27], s[74:75]
	v_lshlrev_b32_e32 v180, 16, v168
	v_and_b32_e32 v181, 0xffff0000, v168
	v_lshlrev_b32_e32 v182, 16, v169
	v_and_b32_e32 v183, 0xffff0000, v169
	v_lshlrev_b32_e32 v184, 16, v170
	v_and_b32_e32 v185, 0xffff0000, v170
	v_lshlrev_b32_e32 v186, 16, v171
	v_and_b32_e32 v187, 0xffff0000, v171
	v_pk_fma_f32 v[20:21], v[20:21], v[204:205], v[180:181]
	v_pk_fma_f32 v[22:23], v[22:23], v[206:207], v[182:183]
	v_pk_fma_f32 v[16:17], v[16:17], v[208:209], v[184:185]
	v_pk_fma_f32 v[18:19], v[18:19], v[210:211], v[186:187]
	v_cvt_pk_bf16_f32 v19, v18, v19
	v_cvt_pk_bf16_f32 v18, v16, v17
	v_cvt_pk_bf16_f32 v17, v22, v23
	v_cvt_pk_bf16_f32 v16, v20, v21
	v_add_u32_e32 v151, 0xa0000, v148
	global_store_dwordx4 v151, v[16:19], s[74:75] offset:256
	v_lshlrev_b32_e32 v180, 16, v172
	v_and_b32_e32 v181, 0xffff0000, v172
	v_lshlrev_b32_e32 v182, 16, v173
	v_and_b32_e32 v183, 0xffff0000, v173
	v_lshlrev_b32_e32 v184, 16, v174
	v_and_b32_e32 v185, 0xffff0000, v174
	v_lshlrev_b32_e32 v186, 16, v175
	v_and_b32_e32 v187, 0xffff0000, v175
	v_pk_fma_f32 v[12:13], v[12:13], v[196:197], v[180:181]
	v_pk_fma_f32 v[14:15], v[14:15], v[198:199], v[182:183]
	v_pk_fma_f32 v[8:9], v[8:9], v[200:201], v[184:185]
	v_pk_fma_f32 v[10:11], v[10:11], v[202:203], v[186:187]
	v_cvt_pk_bf16_f32 v11, v10, v11
	v_cvt_pk_bf16_f32 v10, v8, v9
	v_cvt_pk_bf16_f32 v9, v14, v15
	v_cvt_pk_bf16_f32 v8, v12, v13
	v_add_u32_e32 v151, 0xb0000, v148
	global_store_dwordx4 v151, v[8:11], s[74:75]
	v_lshlrev_b32_e32 v180, 16, v176
	v_and_b32_e32 v181, 0xffff0000, v176
	v_lshlrev_b32_e32 v182, 16, v177
	v_and_b32_e32 v183, 0xffff0000, v177
	v_lshlrev_b32_e32 v184, 16, v178
	v_and_b32_e32 v185, 0xffff0000, v178
	v_lshlrev_b32_e32 v186, 16, v179
	v_and_b32_e32 v187, 0xffff0000, v179
	v_pk_fma_f32 v[4:5], v[4:5], v[204:205], v[180:181]
	v_pk_fma_f32 v[6:7], v[6:7], v[206:207], v[182:183]
	v_pk_fma_f32 v[0:1], v[0:1], v[208:209], v[184:185]
	v_pk_fma_f32 v[2:3], v[2:3], v[210:211], v[186:187]
	v_cvt_pk_bf16_f32 v3, v2, v3
	v_cvt_pk_bf16_f32 v2, v0, v1
	v_cvt_pk_bf16_f32 v1, v6, v7
	v_cvt_pk_bf16_f32 v0, v4, v5
	v_add_u32_e32 v151, 0xb0000, v148
	global_store_dwordx4 v151, v[0:3], s[74:75] offset:256

.LBB0_1090:
	ds_read_b128 v[148:151], v163
	ds_read_b128 v[166:169], v163 offset:1024
	ds_read_b128 v[170:173], v163 offset:2048
	ds_read_b128 v[174:177], v163 offset:3072
	s_add_u32 s18, s16, 0xfff80080
	s_addc_u32 s19, s17, -1
	s_cmp_eq_u32 s35, 28
	s_cselect_b32 s21, s1, s19
	s_cselect_b32 s20, s15, s18
	s_cselect_b32 s19, s22, s34
	s_cselect_b32 s18, s23, s33
	v_lshl_add_u64 v[142:143], s[16:17], 0, v[134:135]
	s_add_i32 m0, s38, 0xc000
	ds_read_b128 v[178:181], v164
	ds_read_b128 v[182:185], v164 offset:1024
	ds_read_b128 v[186:189], v164 offset:2048
	ds_read_b128 v[196:199], v164 offset:3072
	ds_read_b128 v[200:203], v164 offset:4096
	ds_read_b128 v[204:207], v164 offset:5120
	ds_read_b128 v[208:211], v164 offset:6144
	ds_read_b128 v[212:215], v164 offset:7168
	global_load_lds_dwordx4 v[142:143], off
	v_lshl_add_u64 v[142:143], s[16:17], 0, v[136:137]
	s_add_i32 m0, s38, 0xe000
	s_nop 0
	global_load_lds_dwordx4 v[142:143], off
	s_waitcnt lgkmcnt(8)
	s_barrier
	s_waitcnt lgkmcnt(0)
	s_setprio 1
	v_mfma_f32_16x16x32_bf16 v[124:127], v[148:151], v[178:181], v[124:127]
	v_mfma_f32_16x16x32_bf16 v[120:123], v[170:173], v[178:181], v[120:123]
	v_mfma_f32_16x16x32_bf16 v[108:111], v[148:151], v[186:189], v[108:111]
	v_mfma_f32_16x16x32_bf16 v[104:107], v[170:173], v[186:189], v[104:107]
	v_mfma_f32_16x16x32_bf16 v[92:95], v[148:151], v[200:203], v[92:95]
	v_mfma_f32_16x16x32_bf16 v[88:91], v[170:173], v[200:203], v[88:91]
	v_mfma_f32_16x16x32_bf16 v[76:79], v[148:151], v[208:211], v[76:79]
	v_mfma_f32_16x16x32_bf16 v[72:75], v[170:173], v[208:211], v[72:75]
	v_mfma_f32_16x16x32_bf16 v[124:127], v[166:169], v[182:185], v[124:127]
	v_mfma_f32_16x16x32_bf16 v[120:123], v[174:177], v[182:185], v[120:123]
	v_mfma_f32_16x16x32_bf16 v[108:111], v[166:169], v[196:199], v[108:111]
	v_mfma_f32_16x16x32_bf16 v[104:107], v[174:177], v[196:199], v[104:107]
	v_mfma_f32_16x16x32_bf16 v[92:95], v[166:169], v[204:207], v[92:95]
	v_mfma_f32_16x16x32_bf16 v[88:91], v[174:177], v[204:207], v[88:91]
	v_mfma_f32_16x16x32_bf16 v[76:79], v[166:169], v[212:215], v[76:79]
	v_mfma_f32_16x16x32_bf16 v[72:75], v[174:177], v[212:215], v[72:75]
	s_setprio 0
	s_barrier
	s_add_i32 s49, s65, s37
	v_lshl_add_u64 v[142:143], s[18:19], 0, v[128:129]
	s_mov_b32 m0, s49
	ds_read_b128 v[216:219], v165
	ds_read_b128 v[220:223], v165 offset:1024
	ds_read_b128 v[224:227], v165 offset:2048
	ds_read_b128 v[228:231], v165 offset:3072
	global_load_lds_dwordx4 v[142:143], off
	v_lshl_add_u64 v[152:153], s[18:19], 0, v[130:131]
	s_add_i32 m0, s49, 0x2000
	s_nop 0
	global_load_lds_dwordx4 v[152:153], off
	s_barrier
	s_waitcnt lgkmcnt(0)
	s_setprio 1
	v_mfma_f32_16x16x32_bf16 v[116:119], v[216:219], v[178:181], v[116:119]
	v_mfma_f32_16x16x32_bf16 v[112:115], v[224:227], v[178:181], v[112:115]
	v_mfma_f32_16x16x32_bf16 v[100:103], v[216:219], v[186:189], v[100:103]
	v_mfma_f32_16x16x32_bf16 v[96:99], v[224:227], v[186:189], v[96:99]
	v_mfma_f32_16x16x32_bf16 v[84:87], v[216:219], v[200:203], v[84:87]
	v_mfma_f32_16x16x32_bf16 v[80:83], v[224:227], v[200:203], v[80:83]
	v_mfma_f32_16x16x32_bf16 v[68:71], v[216:219], v[208:211], v[68:71]
	v_mfma_f32_16x16x32_bf16 v[64:67], v[224:227], v[208:211], v[64:67]
	v_mfma_f32_16x16x32_bf16 v[116:119], v[220:223], v[182:185], v[116:119]
	v_mfma_f32_16x16x32_bf16 v[112:115], v[228:231], v[182:185], v[112:115]
	v_mfma_f32_16x16x32_bf16 v[100:103], v[220:223], v[196:199], v[100:103]
	v_mfma_f32_16x16x32_bf16 v[96:99], v[228:231], v[196:199], v[96:99]
	v_mfma_f32_16x16x32_bf16 v[84:87], v[220:223], v[204:207], v[84:87]
	v_mfma_f32_16x16x32_bf16 v[80:83], v[228:231], v[204:207], v[80:83]
	v_mfma_f32_16x16x32_bf16 v[68:71], v[220:223], v[212:215], v[68:71]
	v_mfma_f32_16x16x32_bf16 v[64:67], v[228:231], v[212:215], v[64:67]
	s_setprio 0
	s_mov_b32 m0, s38
	v_lshl_add_u64 v[190:191], s[20:21], 0, v[128:129]
	s_barrier
	ds_read_b128 v[178:181], v164 offset:16384
	ds_read_b128 v[182:185], v164 offset:17408
	ds_read_b128 v[186:189], v164 offset:18432
	ds_read_b128 v[196:199], v164 offset:19456
	ds_read_b128 v[200:203], v164 offset:20480
	ds_read_b128 v[204:207], v164 offset:21504
	ds_read_b128 v[208:211], v164 offset:22528
	ds_read_b128 v[212:215], v164 offset:23552
	global_load_lds_dwordx4 v[190:191], off
	v_lshl_add_u64 v[232:233], s[20:21], 0, v[130:131]
	s_mov_b32 m0, s39
	s_nop 0
	global_load_lds_dwordx4 v[232:233], off
	s_barrier
	s_waitcnt lgkmcnt(0)
	s_setprio 1
	v_mfma_f32_16x16x32_bf16 v[60:63], v[148:151], v[178:181], v[60:63]
	v_mfma_f32_16x16x32_bf16 v[56:59], v[170:173], v[178:181], v[56:59]
	v_mfma_f32_16x16x32_bf16 v[44:47], v[148:151], v[186:189], v[44:47]
	v_mfma_f32_16x16x32_bf16 v[40:43], v[170:173], v[186:189], v[40:43]
	v_mfma_f32_16x16x32_bf16 v[28:31], v[148:151], v[200:203], v[28:31]
	v_mfma_f32_16x16x32_bf16 v[24:27], v[170:173], v[200:203], v[24:27]
	v_mfma_f32_16x16x32_bf16 v[12:15], v[148:151], v[208:211], v[12:15]
	v_mfma_f32_16x16x32_bf16 v[8:11], v[170:173], v[208:211], v[8:11]
	v_mfma_f32_16x16x32_bf16 v[60:63], v[166:169], v[182:185], v[60:63]
	v_mfma_f32_16x16x32_bf16 v[56:59], v[174:177], v[182:185], v[56:59]
	v_mfma_f32_16x16x32_bf16 v[44:47], v[166:169], v[196:199], v[44:47]
	v_mfma_f32_16x16x32_bf16 v[40:43], v[174:177], v[196:199], v[40:43]
	v_mfma_f32_16x16x32_bf16 v[28:31], v[166:169], v[204:207], v[28:31]
	v_mfma_f32_16x16x32_bf16 v[24:27], v[174:177], v[204:207], v[24:27]
	v_mfma_f32_16x16x32_bf16 v[12:15], v[166:169], v[212:215], v[12:15]
	v_mfma_f32_16x16x32_bf16 v[8:11], v[174:177], v[212:215], v[8:11]
	s_setprio 0
	s_barrier
	s_add_u32 s80, s18, 0x80000
	s_addc_u32 s81, s19, 0
	s_add_i32 s49, s67, s37
	v_lshl_add_u64 v[148:149], s[80:81], 0, v[128:129]
	s_mov_b32 m0, s49
	s_nop 0
	global_load_lds_dwordx4 v[148:149], off
	v_lshl_add_u64 v[148:149], s[80:81], 0, v[130:131]
	s_add_i32 m0, s49, 0x2000
	s_nop 0
	global_load_lds_dwordx4 v[148:149], off
	s_waitcnt vmcnt(6)
	s_barrier
	s_setprio 1
	v_mfma_f32_16x16x32_bf16 v[52:55], v[216:219], v[178:181], v[52:55]
	v_mfma_f32_16x16x32_bf16 v[48:51], v[224:227], v[178:181], v[48:51]
	v_mfma_f32_16x16x32_bf16 v[36:39], v[216:219], v[186:189], v[36:39]
	v_mfma_f32_16x16x32_bf16 v[32:35], v[224:227], v[186:189], v[32:35]
	v_mfma_f32_16x16x32_bf16 v[20:23], v[216:219], v[200:203], v[20:23]
	v_mfma_f32_16x16x32_bf16 v[16:19], v[224:227], v[200:203], v[16:19]
	v_mfma_f32_16x16x32_bf16 v[4:7], v[216:219], v[208:211], v[4:7]
	v_mfma_f32_16x16x32_bf16 v[0:3], v[224:227], v[208:211], v[0:3]
	v_mfma_f32_16x16x32_bf16 v[52:55], v[220:223], v[182:185], v[52:55]
	v_mfma_f32_16x16x32_bf16 v[48:51], v[228:231], v[182:185], v[48:51]
	v_mfma_f32_16x16x32_bf16 v[36:39], v[220:223], v[196:199], v[36:39]
	v_mfma_f32_16x16x32_bf16 v[32:35], v[228:231], v[196:199], v[32:35]
	v_mfma_f32_16x16x32_bf16 v[20:23], v[220:223], v[204:207], v[20:23]
	v_mfma_f32_16x16x32_bf16 v[16:19], v[228:231], v[204:207], v[16:19]
	v_mfma_f32_16x16x32_bf16 v[4:7], v[220:223], v[212:215], v[4:7]
	v_mfma_f32_16x16x32_bf16 v[0:3], v[228:231], v[212:215], v[0:3]
	s_setprio 0
	s_add_i32 s49, 0, 0x18000
	v_add_u32_e32 v132, s49, v154
	s_barrier
	ds_read_b128 v[148:151], v132
	ds_read_b128 v[166:169], v132 offset:1024
	ds_read_b128 v[170:173], v132 offset:2048
	ds_read_b128 v[174:177], v132 offset:3072
	s_add_u32 s20, s20, 0x80000
	s_addc_u32 s21, s21, 0
	s_mov_b32 m0, s56
	v_lshl_add_u64 v[216:217], s[20:21], 0, v[128:129]
	ds_read_b128 v[178:181], v164 offset:32768
	ds_read_b128 v[182:185], v164 offset:33792
	ds_read_b128 v[186:189], v164 offset:34816
	ds_read_b128 v[196:199], v164 offset:35840
	ds_read_b128 v[200:203], v164 offset:36864
	ds_read_b128 v[204:207], v164 offset:37888
	ds_read_b128 v[208:211], v164 offset:38912
	ds_read_b128 v[212:215], v164 offset:39936
	global_load_lds_dwordx4 v[216:217], off
	v_lshl_add_u64 v[216:217], s[20:21], 0, v[130:131]
	s_mov_b32 m0, s57
	s_nop 0
	global_load_lds_dwordx4 v[216:217], off
	s_waitcnt lgkmcnt(8)
	s_barrier
	s_waitcnt lgkmcnt(0)
	s_setprio 1
	v_mfma_f32_16x16x32_bf16 v[124:127], v[148:151], v[178:181], v[124:127]
	v_mfma_f32_16x16x32_bf16 v[120:123], v[170:173], v[178:181], v[120:123]
	v_mfma_f32_16x16x32_bf16 v[108:111], v[148:151], v[186:189], v[108:111]
	v_mfma_f32_16x16x32_bf16 v[104:107], v[170:173], v[186:189], v[104:107]
	v_mfma_f32_16x16x32_bf16 v[92:95], v[148:151], v[200:203], v[92:95]
	v_mfma_f32_16x16x32_bf16 v[88:91], v[170:173], v[200:203], v[88:91]
	v_mfma_f32_16x16x32_bf16 v[76:79], v[148:151], v[208:211], v[76:79]
	v_mfma_f32_16x16x32_bf16 v[72:75], v[170:173], v[208:211], v[72:75]
	v_mfma_f32_16x16x32_bf16 v[124:127], v[166:169], v[182:185], v[124:127]
	v_mfma_f32_16x16x32_bf16 v[120:123], v[174:177], v[182:185], v[120:123]
	v_mfma_f32_16x16x32_bf16 v[108:111], v[166:169], v[196:199], v[108:111]
	v_mfma_f32_16x16x32_bf16 v[104:107], v[174:177], v[196:199], v[104:107]
	v_mfma_f32_16x16x32_bf16 v[92:95], v[166:169], v[204:207], v[92:95]
	v_mfma_f32_16x16x32_bf16 v[88:91], v[174:177], v[204:207], v[88:91]
	v_mfma_f32_16x16x32_bf16 v[76:79], v[166:169], v[212:215], v[76:79]
	v_mfma_f32_16x16x32_bf16 v[72:75], v[174:177], v[212:215], v[72:75]
	s_setprio 0
	s_barrier
	s_add_i32 s20, 0, 0x1c000
	s_add_i32 s21, s49, s37
	v_add_u32_e32 v132, s20, v154
	v_lshl_add_u64 v[142:143], v[142:143], 0, s[46:47]
	s_mov_b32 m0, s21
	ds_read_b128 v[216:219], v132
	ds_read_b128 v[220:223], v132 offset:1024
	ds_read_b128 v[224:227], v132 offset:2048
	ds_read_b128 v[228:231], v132 offset:3072
	global_load_lds_dwordx4 v[142:143], off
	v_lshl_add_u64 v[142:143], v[152:153], 0, s[46:47]
	s_add_i32 m0, s21, 0x2000
	s_nop 0
	global_load_lds_dwordx4 v[142:143], off
	s_barrier
	s_waitcnt lgkmcnt(0)
	s_setprio 1
	v_mfma_f32_16x16x32_bf16 v[116:119], v[216:219], v[178:181], v[116:119]
	v_mfma_f32_16x16x32_bf16 v[112:115], v[224:227], v[178:181], v[112:115]
	v_mfma_f32_16x16x32_bf16 v[100:103], v[216:219], v[186:189], v[100:103]
	v_mfma_f32_16x16x32_bf16 v[96:99], v[224:227], v[186:189], v[96:99]
	v_mfma_f32_16x16x32_bf16 v[84:87], v[216:219], v[200:203], v[84:87]
	v_mfma_f32_16x16x32_bf16 v[80:83], v[224:227], v[200:203], v[80:83]
	v_mfma_f32_16x16x32_bf16 v[68:71], v[216:219], v[208:211], v[68:71]
	v_mfma_f32_16x16x32_bf16 v[64:67], v[224:227], v[208:211], v[64:67]
	v_mfma_f32_16x16x32_bf16 v[116:119], v[220:223], v[182:185], v[116:119]
	v_mfma_f32_16x16x32_bf16 v[112:115], v[228:231], v[182:185], v[112:115]
	v_mfma_f32_16x16x32_bf16 v[100:103], v[220:223], v[196:199], v[100:103]
	v_mfma_f32_16x16x32_bf16 v[96:99], v[228:231], v[196:199], v[96:99]
	v_mfma_f32_16x16x32_bf16 v[84:87], v[220:223], v[204:207], v[84:87]
	v_mfma_f32_16x16x32_bf16 v[80:83], v[228:231], v[204:207], v[80:83]
	v_mfma_f32_16x16x32_bf16 v[68:71], v[220:223], v[212:215], v[68:71]
	v_mfma_f32_16x16x32_bf16 v[64:67], v[228:231], v[212:215], v[64:67]
	s_setprio 0
	s_mov_b32 m0, s60
	v_lshl_add_u64 v[142:143], v[190:191], 0, s[46:47]
	s_barrier
	ds_read_b128 v[178:181], v164 offset:49152
	ds_read_b128 v[182:185], v164 offset:50176
	ds_read_b128 v[186:189], v164 offset:51200
	ds_read_b128 v[196:199], v164 offset:52224
	ds_read_b128 v[200:203], v164 offset:53248
	ds_read_b128 v[204:207], v164 offset:54272
	ds_read_b128 v[208:211], v164 offset:55296
	ds_read_b128 v[212:215], v164 offset:56320
	global_load_lds_dwordx4 v[142:143], off
	v_lshl_add_u64 v[142:143], v[232:233], 0, s[46:47]
	s_mov_b32 m0, s61
	s_nop 0
	global_load_lds_dwordx4 v[142:143], off
	s_barrier
	s_waitcnt lgkmcnt(0)
	s_setprio 1
	v_mfma_f32_16x16x32_bf16 v[60:63], v[148:151], v[178:181], v[60:63]
	v_mfma_f32_16x16x32_bf16 v[56:59], v[170:173], v[178:181], v[56:59]
	v_mfma_f32_16x16x32_bf16 v[44:47], v[148:151], v[186:189], v[44:47]
	v_mfma_f32_16x16x32_bf16 v[40:43], v[170:173], v[186:189], v[40:43]
	v_mfma_f32_16x16x32_bf16 v[28:31], v[148:151], v[200:203], v[28:31]
	v_mfma_f32_16x16x32_bf16 v[24:27], v[170:173], v[200:203], v[24:27]
	v_mfma_f32_16x16x32_bf16 v[12:15], v[148:151], v[208:211], v[12:15]
	v_mfma_f32_16x16x32_bf16 v[8:11], v[170:173], v[208:211], v[8:11]
	v_mfma_f32_16x16x32_bf16 v[60:63], v[166:169], v[182:185], v[60:63]
	v_mfma_f32_16x16x32_bf16 v[56:59], v[174:177], v[182:185], v[56:59]
	v_mfma_f32_16x16x32_bf16 v[44:47], v[166:169], v[196:199], v[44:47]
	v_mfma_f32_16x16x32_bf16 v[40:43], v[174:177], v[196:199], v[40:43]
	v_mfma_f32_16x16x32_bf16 v[28:31], v[166:169], v[204:207], v[28:31]
	v_mfma_f32_16x16x32_bf16 v[24:27], v[174:177], v[204:207], v[24:27]
	v_mfma_f32_16x16x32_bf16 v[12:15], v[166:169], v[212:215], v[12:15]
	v_mfma_f32_16x16x32_bf16 v[8:11], v[174:177], v[212:215], v[8:11]
	s_setprio 0
	s_barrier
	s_add_u32 s18, s18, 0x80080
	s_addc_u32 s19, s19, 0
	s_add_i32 s20, s20, s37
	v_lshl_add_u64 v[142:143], s[18:19], 0, v[128:129]
	s_mov_b32 m0, s20
	s_nop 0
	global_load_lds_dwordx4 v[142:143], off
	v_lshl_add_u64 v[142:143], s[18:19], 0, v[130:131]
	s_add_i32 m0, s20, 0x2000
	s_nop 0
	global_load_lds_dwordx4 v[142:143], off
	s_waitcnt vmcnt(6)
	s_barrier
	s_setprio 1
	v_mfma_f32_16x16x32_bf16 v[52:55], v[216:219], v[178:181], v[52:55]
	v_mfma_f32_16x16x32_bf16 v[48:51], v[224:227], v[178:181], v[48:51]
	v_mfma_f32_16x16x32_bf16 v[36:39], v[216:219], v[186:189], v[36:39]
	v_mfma_f32_16x16x32_bf16 v[32:35], v[224:227], v[186:189], v[32:35]
	v_mfma_f32_16x16x32_bf16 v[20:23], v[216:219], v[200:203], v[20:23]
	v_mfma_f32_16x16x32_bf16 v[16:19], v[224:227], v[200:203], v[16:19]
	v_mfma_f32_16x16x32_bf16 v[4:7], v[216:219], v[208:211], v[4:7]
	v_mfma_f32_16x16x32_bf16 v[0:3], v[224:227], v[208:211], v[0:3]
	v_mfma_f32_16x16x32_bf16 v[52:55], v[220:223], v[182:185], v[52:55]
	v_mfma_f32_16x16x32_bf16 v[48:51], v[228:231], v[182:185], v[48:51]
	v_mfma_f32_16x16x32_bf16 v[36:39], v[220:223], v[196:199], v[36:39]
	v_mfma_f32_16x16x32_bf16 v[32:35], v[228:231], v[196:199], v[32:35]
	v_mfma_f32_16x16x32_bf16 v[20:23], v[220:223], v[204:207], v[20:23]
	v_mfma_f32_16x16x32_bf16 v[16:19], v[228:231], v[204:207], v[16:19]
	v_mfma_f32_16x16x32_bf16 v[4:7], v[220:223], v[212:215], v[4:7]
	v_mfma_f32_16x16x32_bf16 v[0:3], v[228:231], v[212:215], v[0:3]
	s_setprio 0
	s_add_i32 s35, s35, 2
	s_add_u32 s16, s16, 0x100
	s_addc_u32 s17, s17, 0
	s_add_u32 s33, s33, 0x100
	s_addc_u32 s34, s34, 0
	s_cmp_gt_u32 s35, 29
	s_barrier
	s_cbranch_scc0 .LBB0_1090
	s_lshl_b32 s34, s14, 8
	s_add_i32 s34, s34, s59
	v_or_b32_e32 v150, s34, v147
	v_lshl_or_b32 v142, s0, 8, v162
	v_ashrrev_i32_e32 v151, 31, v150
	v_cmp_gt_i32_e64 s[18:19], s58, v150
	v_cmp_lt_i32_e64 s[16:17], s68, v150
	v_lshlrev_b64 v[148:149], 8, v[150:151]
	v_cmp_lt_i32_e64 s[14:15], s76, v142
	v_add_u32_e32 v132, 0xfffff700, v142
	v_add_u32_e32 v174, 0xfffff710, v142
	v_add_u32_e32 v172, 0xfffff701, v142
	v_add_u32_e32 v170, 0xfffff711, v142
	v_add_u32_e32 v169, 0xfffff702, v142
	v_add_u32_e32 v168, 0xfffff712, v142
	v_add_u32_e32 v167, 0xfffff703, v142
	v_add_u32_e32 v166, 0xfffff713, v142
	v_lshl_add_u64 v[152:153], v[150:151], 1, s[24:25]
	s_and_saveexec_b64 s[0:1], s[14:15]
	s_xor_b64 s[0:1], exec, s[0:1]
	s_cbranch_execz .LBB0_1095
	v_bfe_u32 v143, v124, 16, 1
	v_add3_u32 v143, v124, v143, s77
	v_mad_u64_u32 v[176:177], s[20:21], v132, s66, v[152:153]
	global_store_short_d16_hi v[176:177], v143, off
	v_bfe_u32 v143, v120, 16, 1
	v_add3_u32 v143, v120, v143, s77
	v_mad_u64_u32 v[176:177], s[20:21], v174, s66, v[152:153]
	global_store_short_d16_hi v[176:177], v143, off
	v_bfe_u32 v143, v125, 16, 1
	v_add3_u32 v143, v125, v143, s77
	v_mad_u64_u32 v[176:177], s[20:21], v172, s66, v[152:153]
	global_store_short_d16_hi v[176:177], v143, off
	v_bfe_u32 v143, v121, 16, 1
	v_add3_u32 v143, v121, v143, s77
	v_mad_u64_u32 v[176:177], s[20:21], v170, s66, v[152:153]
	global_store_short_d16_hi v[176:177], v143, off
	v_bfe_u32 v143, v126, 16, 1
	v_add3_u32 v143, v126, v143, s77
	v_mad_u64_u32 v[176:177], s[20:21], v169, s66, v[152:153]
	global_store_short_d16_hi v[176:177], v143, off
	v_bfe_u32 v143, v122, 16, 1
	v_add3_u32 v143, v122, v143, s77
	v_mad_u64_u32 v[176:177], s[20:21], v168, s66, v[152:153]
	global_store_short_d16_hi v[176:177], v143, off
	v_bfe_u32 v143, v127, 16, 1
	v_add3_u32 v143, v127, v143, s77
	v_mad_u64_u32 v[176:177], s[20:21], v167, s66, v[152:153]
	global_store_short_d16_hi v[176:177], v143, off
	v_bfe_u32 v143, v123, 16, 1
	v_add3_u32 v143, v123, v143, s77
	v_mad_u64_u32 v[176:177], s[20:21], v166, s66, v[152:153]
	global_store_short_d16_hi v[176:177], v143, off
	s_and_saveexec_b64 s[20:21], s[18:19]
	s_cbranch_execz .LBB0_1094
	v_lshl_add_u64 v[176:177], v[148:149], 2, s[44:45]
	v_lshl_add_u64 v[176:177], v[132:133], 2, v[176:177]
	global_store_dwordx4 v[176:177], v[124:127], off
	global_store_dwordx4 v[176:177], v[120:123], off offset:64

.LBB0_1346:
	ds_read_b128 v[148:151], v158
	ds_read_b128 v[152:155], v158 offset:1024
	ds_read_b128 v[162:165], v158 offset:2048
	ds_read_b128 v[166:169], v158 offset:3072
	s_add_u32 s20, s38, 0xfff80080
	s_addc_u32 s21, s39, -1
	s_cmp_eq_u32 s61, 28
	s_cselect_b32 s21, s17, s21
	s_cselect_b32 s20, s57, s20
	s_cselect_b32 s45, s15, s60
	s_cselect_b32 s44, s58, s59
	v_lshl_add_u64 v[190:191], s[38:39], 0, v[136:137]
	s_add_i32 m0, s37, 0xc000
	ds_read_b128 v[170:173], v159
	ds_read_b128 v[174:177], v159 offset:1024
	ds_read_b128 v[178:181], v159 offset:2048
	ds_read_b128 v[182:185], v159 offset:3072
	ds_read_b128 v[186:189], v159 offset:4096
	ds_read_b128 v[196:199], v159 offset:5120
	ds_read_b128 v[200:203], v159 offset:6144
	ds_read_b128 v[204:207], v159 offset:7168
	global_load_lds_dwordx4 v[190:191], off
	v_lshl_add_u64 v[190:191], s[38:39], 0, v[138:139]
	s_add_i32 m0, s37, 0xe000
	s_nop 0
	global_load_lds_dwordx4 v[190:191], off
	s_waitcnt lgkmcnt(8)
	s_barrier
	s_waitcnt lgkmcnt(0)
	s_setprio 1
	v_mfma_f32_16x16x32_bf16 v[124:127], v[148:151], v[170:173], v[124:127]
	v_mfma_f32_16x16x32_bf16 v[120:123], v[162:165], v[170:173], v[120:123]
	v_mfma_f32_16x16x32_bf16 v[108:111], v[148:151], v[178:181], v[108:111]
	v_mfma_f32_16x16x32_bf16 v[104:107], v[162:165], v[178:181], v[104:107]
	v_mfma_f32_16x16x32_bf16 v[92:95], v[148:151], v[186:189], v[92:95]
	v_mfma_f32_16x16x32_bf16 v[88:91], v[162:165], v[186:189], v[88:91]
	v_mfma_f32_16x16x32_bf16 v[76:79], v[148:151], v[200:203], v[76:79]
	v_mfma_f32_16x16x32_bf16 v[72:75], v[162:165], v[200:203], v[72:75]
	v_mfma_f32_16x16x32_bf16 v[124:127], v[152:155], v[174:177], v[124:127]
	v_mfma_f32_16x16x32_bf16 v[120:123], v[166:169], v[174:177], v[120:123]
	v_mfma_f32_16x16x32_bf16 v[108:111], v[152:155], v[182:185], v[108:111]
	v_mfma_f32_16x16x32_bf16 v[104:107], v[166:169], v[182:185], v[104:107]
	v_mfma_f32_16x16x32_bf16 v[92:95], v[152:155], v[196:199], v[92:95]
	v_mfma_f32_16x16x32_bf16 v[88:91], v[166:169], v[196:199], v[88:91]
	v_mfma_f32_16x16x32_bf16 v[76:79], v[152:155], v[204:207], v[76:79]
	v_mfma_f32_16x16x32_bf16 v[72:75], v[166:169], v[204:207], v[72:75]
	s_setprio 0
	s_barrier
	s_add_i32 s62, s53, s23
	v_lshl_add_u64 v[190:191], s[44:45], 0, v[132:133]
	s_mov_b32 m0, s62
	ds_read_b128 v[208:211], v160
	ds_read_b128 v[212:215], v160 offset:1024
	ds_read_b128 v[216:219], v160 offset:2048
	ds_read_b128 v[220:223], v160 offset:3072
	global_load_lds_dwordx4 v[190:191], off
	v_lshl_add_u64 v[224:225], s[44:45], 0, v[128:129]
	s_add_i32 m0, s62, 0x2000
	s_nop 0
	global_load_lds_dwordx4 v[224:225], off
	s_barrier
	s_waitcnt lgkmcnt(0)
	s_setprio 1
	v_mfma_f32_16x16x32_bf16 v[116:119], v[208:211], v[170:173], v[116:119]
	v_mfma_f32_16x16x32_bf16 v[112:115], v[216:219], v[170:173], v[112:115]
	v_mfma_f32_16x16x32_bf16 v[100:103], v[208:211], v[178:181], v[100:103]
	v_mfma_f32_16x16x32_bf16 v[96:99], v[216:219], v[178:181], v[96:99]
	v_mfma_f32_16x16x32_bf16 v[84:87], v[208:211], v[186:189], v[84:87]
	v_mfma_f32_16x16x32_bf16 v[80:83], v[216:219], v[186:189], v[80:83]
	v_mfma_f32_16x16x32_bf16 v[68:71], v[208:211], v[200:203], v[68:71]
	v_mfma_f32_16x16x32_bf16 v[64:67], v[216:219], v[200:203], v[64:67]
	v_mfma_f32_16x16x32_bf16 v[116:119], v[212:215], v[174:177], v[116:119]
	v_mfma_f32_16x16x32_bf16 v[112:115], v[220:223], v[174:177], v[112:115]
	v_mfma_f32_16x16x32_bf16 v[100:103], v[212:215], v[182:185], v[100:103]
	v_mfma_f32_16x16x32_bf16 v[96:99], v[220:223], v[182:185], v[96:99]
	v_mfma_f32_16x16x32_bf16 v[84:87], v[212:215], v[196:199], v[84:87]
	v_mfma_f32_16x16x32_bf16 v[80:83], v[220:223], v[196:199], v[80:83]
	v_mfma_f32_16x16x32_bf16 v[68:71], v[212:215], v[204:207], v[68:71]
	v_mfma_f32_16x16x32_bf16 v[64:67], v[220:223], v[204:207], v[64:67]
	s_setprio 0
	s_mov_b32 m0, s37
	v_lshl_add_u64 v[226:227], s[20:21], 0, v[134:135]
	s_barrier
	ds_read_b128 v[170:173], v159 offset:16384
	ds_read_b128 v[174:177], v159 offset:17408
	ds_read_b128 v[178:181], v159 offset:18432
	ds_read_b128 v[182:185], v159 offset:19456
	ds_read_b128 v[186:189], v159 offset:20480
	ds_read_b128 v[196:199], v159 offset:21504
	ds_read_b128 v[200:203], v159 offset:22528
	ds_read_b128 v[204:207], v159 offset:23552
	global_load_lds_dwordx4 v[226:227], off
	v_lshl_add_u64 v[228:229], s[20:21], 0, v[130:131]
	s_mov_b32 m0, s47
	s_nop 0
	global_load_lds_dwordx4 v[228:229], off
	s_barrier
	s_waitcnt lgkmcnt(0)
	s_setprio 1
	v_mfma_f32_16x16x32_bf16 v[60:63], v[148:151], v[170:173], v[60:63]
	v_mfma_f32_16x16x32_bf16 v[56:59], v[162:165], v[170:173], v[56:59]
	v_mfma_f32_16x16x32_bf16 v[44:47], v[148:151], v[178:181], v[44:47]
	v_mfma_f32_16x16x32_bf16 v[40:43], v[162:165], v[178:181], v[40:43]
	v_mfma_f32_16x16x32_bf16 v[28:31], v[148:151], v[186:189], v[28:31]
	v_mfma_f32_16x16x32_bf16 v[24:27], v[162:165], v[186:189], v[24:27]
	v_mfma_f32_16x16x32_bf16 v[12:15], v[148:151], v[200:203], v[12:15]
	v_mfma_f32_16x16x32_bf16 v[8:11], v[162:165], v[200:203], v[8:11]
	v_mfma_f32_16x16x32_bf16 v[60:63], v[152:155], v[174:177], v[60:63]
	v_mfma_f32_16x16x32_bf16 v[56:59], v[166:169], v[174:177], v[56:59]
	v_mfma_f32_16x16x32_bf16 v[44:47], v[152:155], v[182:185], v[44:47]
	v_mfma_f32_16x16x32_bf16 v[40:43], v[166:169], v[182:185], v[40:43]
	v_mfma_f32_16x16x32_bf16 v[28:31], v[152:155], v[196:199], v[28:31]
	v_mfma_f32_16x16x32_bf16 v[24:27], v[166:169], v[196:199], v[24:27]
	v_mfma_f32_16x16x32_bf16 v[12:15], v[152:155], v[204:207], v[12:15]
	v_mfma_f32_16x16x32_bf16 v[8:11], v[166:169], v[204:207], v[8:11]
	s_setprio 0
	s_barrier
	s_add_u32 s62, s44, 0x80000
	s_addc_u32 s63, s45, 0
	s_add_i32 s64, s55, s23
	v_lshl_add_u64 v[148:149], s[62:63], 0, v[132:133]
	s_mov_b32 m0, s64
	s_nop 0
	global_load_lds_dwordx4 v[148:149], off
	v_lshl_add_u64 v[148:149], s[62:63], 0, v[128:129]
	s_add_i32 m0, s64, 0x2000
	s_nop 0
	global_load_lds_dwordx4 v[148:149], off
	s_waitcnt vmcnt(6)
	s_barrier
	s_setprio 1
	v_mfma_f32_16x16x32_bf16 v[52:55], v[208:211], v[170:173], v[52:55]
	v_mfma_f32_16x16x32_bf16 v[48:51], v[216:219], v[170:173], v[48:51]
	v_mfma_f32_16x16x32_bf16 v[36:39], v[208:211], v[178:181], v[36:39]
	v_mfma_f32_16x16x32_bf16 v[32:35], v[216:219], v[178:181], v[32:35]
	v_mfma_f32_16x16x32_bf16 v[20:23], v[208:211], v[186:189], v[20:23]
	v_mfma_f32_16x16x32_bf16 v[16:19], v[216:219], v[186:189], v[16:19]
	v_mfma_f32_16x16x32_bf16 v[4:7], v[208:211], v[200:203], v[4:7]
	v_mfma_f32_16x16x32_bf16 v[0:3], v[216:219], v[200:203], v[0:3]
	v_mfma_f32_16x16x32_bf16 v[52:55], v[212:215], v[174:177], v[52:55]
	v_mfma_f32_16x16x32_bf16 v[48:51], v[220:223], v[174:177], v[48:51]
	v_mfma_f32_16x16x32_bf16 v[36:39], v[212:215], v[182:185], v[36:39]
	v_mfma_f32_16x16x32_bf16 v[32:35], v[220:223], v[182:185], v[32:35]
	v_mfma_f32_16x16x32_bf16 v[20:23], v[212:215], v[196:199], v[20:23]
	v_mfma_f32_16x16x32_bf16 v[16:19], v[220:223], v[196:199], v[16:19]
	v_mfma_f32_16x16x32_bf16 v[4:7], v[212:215], v[204:207], v[4:7]
	v_mfma_f32_16x16x32_bf16 v[0:3], v[220:223], v[204:207], v[0:3]
	s_setprio 0
	s_add_i32 s62, 0, 0x18000
	v_add_u32_e32 v161, s62, v147
	s_barrier
	ds_read_b128 v[148:151], v161
	ds_read_b128 v[152:155], v161 offset:1024
	ds_read_b128 v[162:165], v161 offset:2048
	ds_read_b128 v[166:169], v161 offset:3072
	s_add_u32 s20, s20, 0x80000
	s_addc_u32 s21, s21, 0
	s_mov_b32 m0, s48
	v_lshl_add_u64 v[208:209], s[20:21], 0, v[134:135]
	ds_read_b128 v[170:173], v159 offset:32768
	ds_read_b128 v[174:177], v159 offset:33792
	ds_read_b128 v[178:181], v159 offset:34816
	ds_read_b128 v[182:185], v159 offset:35840
	ds_read_b128 v[186:189], v159 offset:36864
	ds_read_b128 v[196:199], v159 offset:37888
	ds_read_b128 v[200:203], v159 offset:38912
	ds_read_b128 v[204:207], v159 offset:39936
	global_load_lds_dwordx4 v[208:209], off
	v_lshl_add_u64 v[208:209], s[20:21], 0, v[130:131]
	s_mov_b32 m0, s49
	s_nop 0
	global_load_lds_dwordx4 v[208:209], off
	s_waitcnt lgkmcnt(8)
	s_barrier
	s_waitcnt lgkmcnt(0)
	s_setprio 1
	v_mfma_f32_16x16x32_bf16 v[124:127], v[148:151], v[170:173], v[124:127]
	v_mfma_f32_16x16x32_bf16 v[120:123], v[162:165], v[170:173], v[120:123]
	v_mfma_f32_16x16x32_bf16 v[108:111], v[148:151], v[178:181], v[108:111]
	v_mfma_f32_16x16x32_bf16 v[104:107], v[162:165], v[178:181], v[104:107]
	v_mfma_f32_16x16x32_bf16 v[92:95], v[148:151], v[186:189], v[92:95]
	v_mfma_f32_16x16x32_bf16 v[88:91], v[162:165], v[186:189], v[88:91]
	v_mfma_f32_16x16x32_bf16 v[76:79], v[148:151], v[200:203], v[76:79]
	v_mfma_f32_16x16x32_bf16 v[72:75], v[162:165], v[200:203], v[72:75]
	v_mfma_f32_16x16x32_bf16 v[124:127], v[152:155], v[174:177], v[124:127]
	v_mfma_f32_16x16x32_bf16 v[120:123], v[166:169], v[174:177], v[120:123]
	v_mfma_f32_16x16x32_bf16 v[108:111], v[152:155], v[182:185], v[108:111]
	v_mfma_f32_16x16x32_bf16 v[104:107], v[166:169], v[182:185], v[104:107]
	v_mfma_f32_16x16x32_bf16 v[92:95], v[152:155], v[196:199], v[92:95]
	v_mfma_f32_16x16x32_bf16 v[88:91], v[166:169], v[196:199], v[88:91]
	v_mfma_f32_16x16x32_bf16 v[76:79], v[152:155], v[204:207], v[76:79]
	v_mfma_f32_16x16x32_bf16 v[72:75], v[166:169], v[204:207], v[72:75]
	s_setprio 0
	s_barrier
	s_add_i32 s63, 0, 0x1c000
	s_add_i32 s20, s62, s23
	v_add_u32_e32 v161, s63, v147
	v_lshl_add_u64 v[190:191], v[190:191], 0, s[10:11]
	s_mov_b32 m0, s20
	ds_read_b128 v[208:211], v161
	ds_read_b128 v[212:215], v161 offset:1024
	ds_read_b128 v[216:219], v161 offset:2048
	ds_read_b128 v[220:223], v161 offset:3072
	global_load_lds_dwordx4 v[190:191], off
	v_lshl_add_u64 v[190:191], v[224:225], 0, s[10:11]
	s_add_i32 m0, s20, 0x2000
	s_nop 0
	global_load_lds_dwordx4 v[190:191], off
	s_barrier
	s_waitcnt lgkmcnt(0)
	s_setprio 1
	v_mfma_f32_16x16x32_bf16 v[116:119], v[208:211], v[170:173], v[116:119]
	v_mfma_f32_16x16x32_bf16 v[112:115], v[216:219], v[170:173], v[112:115]
	v_mfma_f32_16x16x32_bf16 v[100:103], v[208:211], v[178:181], v[100:103]
	v_mfma_f32_16x16x32_bf16 v[96:99], v[216:219], v[178:181], v[96:99]
	v_mfma_f32_16x16x32_bf16 v[84:87], v[208:211], v[186:189], v[84:87]
	v_mfma_f32_16x16x32_bf16 v[80:83], v[216:219], v[186:189], v[80:83]
	v_mfma_f32_16x16x32_bf16 v[68:71], v[208:211], v[200:203], v[68:71]
	v_mfma_f32_16x16x32_bf16 v[64:67], v[216:219], v[200:203], v[64:67]
	v_mfma_f32_16x16x32_bf16 v[116:119], v[212:215], v[174:177], v[116:119]
	v_mfma_f32_16x16x32_bf16 v[112:115], v[220:223], v[174:177], v[112:115]
	v_mfma_f32_16x16x32_bf16 v[100:103], v[212:215], v[182:185], v[100:103]
	v_mfma_f32_16x16x32_bf16 v[96:99], v[220:223], v[182:185], v[96:99]
	v_mfma_f32_16x16x32_bf16 v[84:87], v[212:215], v[196:199], v[84:87]
	v_mfma_f32_16x16x32_bf16 v[80:83], v[220:223], v[196:199], v[80:83]
	v_mfma_f32_16x16x32_bf16 v[68:71], v[212:215], v[204:207], v[68:71]
	v_mfma_f32_16x16x32_bf16 v[64:67], v[220:223], v[204:207], v[64:67]
	s_setprio 0
	s_mov_b32 m0, s34
	v_lshl_add_u64 v[190:191], v[226:227], 0, s[10:11]
	s_barrier
	ds_read_b128 v[170:173], v159 offset:49152
	ds_read_b128 v[174:177], v159 offset:50176
	ds_read_b128 v[178:181], v159 offset:51200
	ds_read_b128 v[182:185], v159 offset:52224
	ds_read_b128 v[186:189], v159 offset:53248
	ds_read_b128 v[196:199], v159 offset:54272
	ds_read_b128 v[200:203], v159 offset:55296
	ds_read_b128 v[204:207], v159 offset:56320
	global_load_lds_dwordx4 v[190:191], off
	v_lshl_add_u64 v[190:191], v[228:229], 0, s[10:11]
	s_mov_b32 m0, s35
	s_nop 0
	global_load_lds_dwordx4 v[190:191], off
	s_barrier
	s_waitcnt lgkmcnt(0)
	s_setprio 1
	v_mfma_f32_16x16x32_bf16 v[60:63], v[148:151], v[170:173], v[60:63]
	v_mfma_f32_16x16x32_bf16 v[56:59], v[162:165], v[170:173], v[56:59]
	v_mfma_f32_16x16x32_bf16 v[44:47], v[148:151], v[178:181], v[44:47]
	v_mfma_f32_16x16x32_bf16 v[40:43], v[162:165], v[178:181], v[40:43]
	v_mfma_f32_16x16x32_bf16 v[28:31], v[148:151], v[186:189], v[28:31]
	v_mfma_f32_16x16x32_bf16 v[24:27], v[162:165], v[186:189], v[24:27]
	v_mfma_f32_16x16x32_bf16 v[12:15], v[148:151], v[200:203], v[12:15]
	v_mfma_f32_16x16x32_bf16 v[8:11], v[162:165], v[200:203], v[8:11]
	v_mfma_f32_16x16x32_bf16 v[60:63], v[152:155], v[174:177], v[60:63]
	v_mfma_f32_16x16x32_bf16 v[56:59], v[166:169], v[174:177], v[56:59]
	v_mfma_f32_16x16x32_bf16 v[44:47], v[152:155], v[182:185], v[44:47]
	v_mfma_f32_16x16x32_bf16 v[40:43], v[166:169], v[182:185], v[40:43]
	v_mfma_f32_16x16x32_bf16 v[28:31], v[152:155], v[196:199], v[28:31]
	v_mfma_f32_16x16x32_bf16 v[24:27], v[166:169], v[196:199], v[24:27]
	v_mfma_f32_16x16x32_bf16 v[12:15], v[152:155], v[204:207], v[12:15]
	v_mfma_f32_16x16x32_bf16 v[8:11], v[166:169], v[204:207], v[8:11]
	s_setprio 0
	s_barrier
	s_add_u32 s20, s44, 0x80080
	s_addc_u32 s21, s45, 0
	s_add_i32 s44, s63, s23
	v_lshl_add_u64 v[148:149], s[20:21], 0, v[132:133]
	s_mov_b32 m0, s44
	s_nop 0
	global_load_lds_dwordx4 v[148:149], off
	v_lshl_add_u64 v[148:149], s[20:21], 0, v[128:129]
	s_add_i32 m0, s44, 0x2000
	s_nop 0
	global_load_lds_dwordx4 v[148:149], off
	s_waitcnt vmcnt(6)
	s_barrier
	s_setprio 1
	v_mfma_f32_16x16x32_bf16 v[52:55], v[208:211], v[170:173], v[52:55]
	v_mfma_f32_16x16x32_bf16 v[48:51], v[216:219], v[170:173], v[48:51]
	v_mfma_f32_16x16x32_bf16 v[36:39], v[208:211], v[178:181], v[36:39]
	v_mfma_f32_16x16x32_bf16 v[32:35], v[216:219], v[178:181], v[32:35]
	v_mfma_f32_16x16x32_bf16 v[20:23], v[208:211], v[186:189], v[20:23]
	v_mfma_f32_16x16x32_bf16 v[16:19], v[216:219], v[186:189], v[16:19]
	v_mfma_f32_16x16x32_bf16 v[4:7], v[208:211], v[200:203], v[4:7]
	v_mfma_f32_16x16x32_bf16 v[0:3], v[216:219], v[200:203], v[0:3]
	v_mfma_f32_16x16x32_bf16 v[52:55], v[212:215], v[174:177], v[52:55]
	v_mfma_f32_16x16x32_bf16 v[48:51], v[220:223], v[174:177], v[48:51]
	v_mfma_f32_16x16x32_bf16 v[36:39], v[212:215], v[182:185], v[36:39]
	v_mfma_f32_16x16x32_bf16 v[32:35], v[220:223], v[182:185], v[32:35]
	v_mfma_f32_16x16x32_bf16 v[20:23], v[212:215], v[196:199], v[20:23]
	v_mfma_f32_16x16x32_bf16 v[16:19], v[220:223], v[196:199], v[16:19]
	v_mfma_f32_16x16x32_bf16 v[4:7], v[212:215], v[204:207], v[4:7]
	v_mfma_f32_16x16x32_bf16 v[0:3], v[220:223], v[204:207], v[0:3]
	s_setprio 0
	s_add_i32 s61, s61, 2
	s_add_u32 s38, s38, 0x100
	s_addc_u32 s39, s39, 0
	s_add_u32 s59, s59, 0x100
	s_addc_u32 s60, s60, 0
	s_cmp_gt_u32 s61, 29
	s_cbranch_scc0 .Lepi_nl_c_out
	s_cmp_lg_u32 s51, 64
	s_cbranch_scc1 .Lepi_nl_c_out
	s_lshl_b32 s15, s36, 8
	s_add_i32 s15, s15, s51
	v_or_b32_e32 v154, s15, v145
	s_add_i32 s17, s15, 0xffffe000
	v_lshl_or_b32 v150, s33, 8, v157
	s_lshr_b32 s17, s17, 12
	v_lshlrev_b32_e32 v148, 12, v154
	s_add_i32 s17, s17, 1
	s_cmp_gt_i32 s15, s56
	s_cselect_b32 s17, s17, 0
	s_mul_i32 s17, s17, s54
	v_lshl_add_u32 v148, v150, 1, v148
	s_add_u32 s20, s8, s17
	s_addc_u32 s21, s9, 0
	v_lshlrev_b32_e32 v149, 2, v150
	s_nop 0
	global_load_dwordx4 v[196:199], v149, s[20:21]
	global_load_dwordx4 v[200:203], v149, s[20:21] offset:16
	global_load_dwordx4 v[204:207], v149, s[20:21] offset:512
	global_load_dwordx4 v[208:211], v149, s[20:21] offset:528
	global_load_dwordx4 v[212:215], v148, s[74:75]
	global_load_dwordx4 v[216:219], v148, s[74:75] offset:256
	v_add_u32_e32 v151, 0x10000, v148
	global_load_dwordx4 v[220:223], v151, s[74:75]
	global_load_dwordx4 v[224:227], v151, s[74:75] offset:256
	v_add_u32_e32 v151, 0x20000, v148
	global_load_dwordx4 v[164:167], v151, s[74:75]
	global_load_dwordx4 v[168:171], v151, s[74:75] offset:256
	v_add_u32_e32 v151, 0x30000, v148
	global_load_dwordx4 v[172:175], v151, s[74:75]
	global_load_dwordx4 v[176:179], v151, s[74:75] offset:256
	s_waitcnt vmcnt(0)
	v_lshlrev_b32_e32 v180, 16, v212
	v_and_b32_e32 v181, 0xffff0000, v212
	v_lshlrev_b32_e32 v182, 16, v213
	v_and_b32_e32 v183, 0xffff0000, v213
	v_lshlrev_b32_e32 v184, 16, v214
	v_and_b32_e32 v185, 0xffff0000, v214
	v_lshlrev_b32_e32 v186, 16, v215
	v_and_b32_e32 v187, 0xffff0000, v215
	v_pk_fma_f32 v[124:125], v[124:125], v[196:197], v[180:181]
	v_pk_fma_f32 v[126:127], v[126:127], v[198:199], v[182:183]
	v_pk_fma_f32 v[120:121], v[120:121], v[200:201], v[184:185]
	v_pk_fma_f32 v[122:123], v[122:123], v[202:203], v[186:187]
	v_cvt_pk_bf16_f32 v123, v122, v123
	v_cvt_pk_bf16_f32 v122, v120, v121
	v_cvt_pk_bf16_f32 v121, v126, v127
	v_cvt_pk_bf16_f32 v120, v124, v125
	global_store_dwordx4 v148, v[120:123], s[74:75]
	v_lshlrev_b32_e32 v180, 16, v216
	v_and_b32_e32 v181, 0xffff0000, v216
	v_lshlrev_b32_e32 v182, 16, v217
	v_and_b32_e32 v183, 0xffff0000, v217
	v_lshlrev_b32_e32 v184, 16, v218
	v_and_b32_e32 v185, 0xffff0000, v218
	v_lshlrev_b32_e32 v186, 16, v219
	v_and_b32_e32 v187, 0xffff0000, v219
	v_pk_fma_f32 v[116:117], v[116:117], v[204:205], v[180:181]
	v_pk_fma_f32 v[118:119], v[118:119], v[206:207], v[182:183]
	v_pk_fma_f32 v[112:113], v[112:113], v[208:209], v[184:185]
	v_pk_fma_f32 v[114:115], v[114:115], v[210:211], v[186:187]
	v_cvt_pk_bf16_f32 v115, v114, v115
	v_cvt_pk_bf16_f32 v114, v112, v113
	v_cvt_pk_bf16_f32 v113, v118, v119
	v_cvt_pk_bf16_f32 v112, v116, v117
	global_store_dwordx4 v148, v[112:115], s[74:75] offset:256
	v_lshlrev_b32_e32 v180, 16, v220
	v_and_b32_e32 v181, 0xffff0000, v220
	v_lshlrev_b32_e32 v182, 16, v221
	v_and_b32_e32 v183, 0xffff0000, v221
	v_lshlrev_b32_e32 v184, 16, v222
	v_and_b32_e32 v185, 0xffff0000, v222
	v_lshlrev_b32_e32 v186, 16, v223
	v_and_b32_e32 v187, 0xffff0000, v223
	v_pk_fma_f32 v[108:109], v[108:109], v[196:197], v[180:181]
	v_pk_fma_f32 v[110:111], v[110:111], v[198:199], v[182:183]
	v_pk_fma_f32 v[104:105], v[104:105], v[200:201], v[184:185]
	v_pk_fma_f32 v[106:107], v[106:107], v[202:203], v[186:187]
	v_cvt_pk_bf16_f32 v107, v106, v107
	v_cvt_pk_bf16_f32 v106, v104, v105
	v_cvt_pk_bf16_f32 v105, v110, v111
	v_cvt_pk_bf16_f32 v104, v108, v109
	v_add_u32_e32 v151, 0x10000, v148
	global_store_dwordx4 v151, v[104:107], s[74:75]
	v_lshlrev_b32_e32 v180, 16, v224
	v_and_b32_e32 v181, 0xffff0000, v224
	v_lshlrev_b32_e32 v182, 16, v225
	v_and_b32_e32 v183, 0xffff0000, v225
	v_lshlrev_b32_e32 v184, 16, v226
	v_and_b32_e32 v185, 0xffff0000, v226
	v_lshlrev_b32_e32 v186, 16, v227
	v_and_b32_e32 v187, 0xffff0000, v227
	v_pk_fma_f32 v[100:101], v[100:101], v[204:205], v[180:181]
	v_pk_fma_f32 v[102:103], v[102:103], v[206:207], v[182:183]
	v_pk_fma_f32 v[96:97], v[96:97], v[208:209], v[184:185]
	v_pk_fma_f32 v[98:99], v[98:99], v[210:211], v[186:187]
	v_cvt_pk_bf16_f32 v99, v98, v99
	v_cvt_pk_bf16_f32 v98, v96, v97
	v_cvt_pk_bf16_f32 v97, v102, v103
	v_cvt_pk_bf16_f32 v96, v100, v101
	v_add_u32_e32 v151, 0x10000, v148
	global_store_dwordx4 v151, v[96:99], s[74:75] offset:256
	v_add_u32_e32 v151, 0x80000, v148
	global_load_dwordx4 v[212:215], v151, s[74:75]
	global_load_dwordx4 v[216:219], v151, s[74:75] offset:256
	v_add_u32_e32 v151, 0x90000, v148
	global_load_dwordx4 v[220:223], v151, s[74:75]
	global_load_dwordx4 v[224:227], v151, s[74:75] offset:256
	v_lshlrev_b32_e32 v180, 16, v164
	v_and_b32_e32 v181, 0xffff0000, v164
	v_lshlrev_b32_e32 v182, 16, v165
	v_and_b32_e32 v183, 0xffff0000, v165
	v_lshlrev_b32_e32 v184, 16, v166
	v_and_b32_e32 v185, 0xffff0000, v166
	v_lshlrev_b32_e32 v186, 16, v167
	v_and_b32_e32 v187, 0xffff0000, v167
	v_pk_fma_f32 v[92:93], v[92:93], v[196:197], v[180:181]
	v_pk_fma_f32 v[94:95], v[94:95], v[198:199], v[182:183]
	v_pk_fma_f32 v[88:89], v[88:89], v[200:201], v[184:185]
	v_pk_fma_f32 v[90:91], v[90:91], v[202:203], v[186:187]
	v_cvt_pk_bf16_f32 v91, v90, v91
	v_cvt_pk_bf16_f32 v90, v88, v89
	v_cvt_pk_bf16_f32 v89, v94, v95
	v_cvt_pk_bf16_f32 v88, v92, v93
	v_add_u32_e32 v151, 0x20000, v148
	global_store_dwordx4 v151, v[88:91], s[74:75]
	v_lshlrev_b32_e32 v180, 16, v168
	v_and_b32_e32 v181, 0xffff0000, v168
	v_lshlrev_b32_e32 v182, 16, v169
	v_and_b32_e32 v183, 0xffff0000, v169
	v_lshlrev_b32_e32 v184, 16, v170
	v_and_b32_e32 v185, 0xffff0000, v170
	v_lshlrev_b32_e32 v186, 16, v171
	v_and_b32_e32 v187, 0xffff0000, v171
	v_pk_fma_f32 v[84:85], v[84:85], v[204:205], v[180:181]
	v_pk_fma_f32 v[86:87], v[86:87], v[206:207], v[182:183]
	v_pk_fma_f32 v[80:81], v[80:81], v[208:209], v[184:185]
	v_pk_fma_f32 v[82:83], v[82:83], v[210:211], v[186:187]
	v_cvt_pk_bf16_f32 v83, v82, v83
	v_cvt_pk_bf16_f32 v82, v80, v81
	v_cvt_pk_bf16_f32 v81, v86, v87
	v_cvt_pk_bf16_f32 v80, v84, v85
	v_add_u32_e32 v151, 0x20000, v148
	global_store_dwordx4 v151, v[80:83], s[74:75] offset:256
	v_lshlrev_b32_e32 v180, 16, v172
	v_and_b32_e32 v181, 0xffff0000, v172
	v_lshlrev_b32_e32 v182, 16, v173
	v_and_b32_e32 v183, 0xffff0000, v173
	v_lshlrev_b32_e32 v184, 16, v174
	v_and_b32_e32 v185, 0xffff0000, v174
	v_lshlrev_b32_e32 v186, 16, v175
	v_and_b32_e32 v187, 0xffff0000, v175
	v_pk_fma_f32 v[76:77], v[76:77], v[196:197], v[180:181]
	v_pk_fma_f32 v[78:79], v[78:79], v[198:199], v[182:183]
	v_pk_fma_f32 v[72:73], v[72:73], v[200:201], v[184:185]
	v_pk_fma_f32 v[74:75], v[74:75], v[202:203], v[186:187]
	v_cvt_pk_bf16_f32 v75, v74, v75
	v_cvt_pk_bf16_f32 v74, v72, v73
	v_cvt_pk_bf16_f32 v73, v78, v79
	v_cvt_pk_bf16_f32 v72, v76, v77
	v_add_u32_e32 v151, 0x30000, v148
	global_store_dwordx4 v151, v[72:75], s[74:75]
	v_lshlrev_b32_e32 v180, 16, v176
	v_and_b32_e32 v181, 0xffff0000, v176
	v_lshlrev_b32_e32 v182, 16, v177
	v_and_b32_e32 v183, 0xffff0000, v177
	v_lshlrev_b32_e32 v184, 16, v178
	v_and_b32_e32 v185, 0xffff0000, v178
	v_lshlrev_b32_e32 v186, 16, v179
	v_and_b32_e32 v187, 0xffff0000, v179
	v_pk_fma_f32 v[68:69], v[68:69], v[204:205], v[180:181]
	v_pk_fma_f32 v[70:71], v[70:71], v[206:207], v[182:183]
	v_pk_fma_f32 v[64:65], v[64:65], v[208:209], v[184:185]
	v_pk_fma_f32 v[66:67], v[66:67], v[210:211], v[186:187]
	v_cvt_pk_bf16_f32 v67, v66, v67
	v_cvt_pk_bf16_f32 v66, v64, v65
	v_cvt_pk_bf16_f32 v65, v70, v71
	v_cvt_pk_bf16_f32 v64, v68, v69
	v_add_u32_e32 v151, 0x30000, v148
	global_store_dwordx4 v151, v[64:67], s[74:75] offset:256
	v_add_u32_e32 v151, 0xa0000, v148
	global_load_dwordx4 v[164:167], v151, s[74:75]
	global_load_dwordx4 v[168:171], v151, s[74:75] offset:256
	v_add_u32_e32 v151, 0xb0000, v148
	global_load_dwordx4 v[172:175], v151, s[74:75]
	global_load_dwordx4 v[176:179], v151, s[74:75] offset:256
	s_waitcnt vmcnt(0)
	v_lshlrev_b32_e32 v180, 16, v212
	v_and_b32_e32 v181, 0xffff0000, v212
	v_lshlrev_b32_e32 v182, 16, v213
	v_and_b32_e32 v183, 0xffff0000, v213
	v_lshlrev_b32_e32 v184, 16, v214
	v_and_b32_e32 v185, 0xffff0000, v214
	v_lshlrev_b32_e32 v186, 16, v215
	v_and_b32_e32 v187, 0xffff0000, v215
	v_pk_fma_f32 v[60:61], v[60:61], v[196:197], v[180:181]
	v_pk_fma_f32 v[62:63], v[62:63], v[198:199], v[182:183]
	v_pk_fma_f32 v[56:57], v[56:57], v[200:201], v[184:185]
	v_pk_fma_f32 v[58:59], v[58:59], v[202:203], v[186:187]
	v_cvt_pk_bf16_f32 v59, v58, v59
	v_cvt_pk_bf16_f32 v58, v56, v57
	v_cvt_pk_bf16_f32 v57, v62, v63
	v_cvt_pk_bf16_f32 v56, v60, v61
	v_add_u32_e32 v151, 0x80000, v148
	global_store_dwordx4 v151, v[56:59], s[74:75]
	v_lshlrev_b32_e32 v180, 16, v216
	v_and_b32_e32 v181, 0xffff0000, v216
	v_lshlrev_b32_e32 v182, 16, v217
	v_and_b32_e32 v183, 0xffff0000, v217
	v_lshlrev_b32_e32 v184, 16, v218
	v_and_b32_e32 v185, 0xffff0000, v218
	v_lshlrev_b32_e32 v186, 16, v219
	v_and_b32_e32 v187, 0xffff0000, v219
	v_pk_fma_f32 v[52:53], v[52:53], v[204:205], v[180:181]
	v_pk_fma_f32 v[54:55], v[54:55], v[206:207], v[182:183]
	v_pk_fma_f32 v[48:49], v[48:49], v[208:209], v[184:185]
	v_pk_fma_f32 v[50:51], v[50:51], v[210:211], v[186:187]
	v_cvt_pk_bf16_f32 v51, v50, v51
	v_cvt_pk_bf16_f32 v50, v48, v49
	v_cvt_pk_bf16_f32 v49, v54, v55
	v_cvt_pk_bf16_f32 v48, v52, v53
	v_add_u32_e32 v151, 0x80000, v148
	global_store_dwordx4 v151, v[48:51], s[74:75] offset:256
	v_lshlrev_b32_e32 v180, 16, v220
	v_and_b32_e32 v181, 0xffff0000, v220
	v_lshlrev_b32_e32 v182, 16, v221
	v_and_b32_e32 v183, 0xffff0000, v221
	v_lshlrev_b32_e32 v184, 16, v222
	v_and_b32_e32 v185, 0xffff0000, v222
	v_lshlrev_b32_e32 v186, 16, v223
	v_and_b32_e32 v187, 0xffff0000, v223
	v_pk_fma_f32 v[44:45], v[44:45], v[196:197], v[180:181]
	v_pk_fma_f32 v[46:47], v[46:47], v[198:199], v[182:183]
	v_pk_fma_f32 v[40:41], v[40:41], v[200:201], v[184:185]
	v_pk_fma_f32 v[42:43], v[42:43], v[202:203], v[186:187]
	v_cvt_pk_bf16_f32 v43, v42, v43
	v_cvt_pk_bf16_f32 v42, v40, v41
	v_cvt_pk_bf16_f32 v41, v46, v47
	v_cvt_pk_bf16_f32 v40, v44, v45
	v_add_u32_e32 v151, 0x90000, v148
	global_store_dwordx4 v151, v[40:43], s[74:75]
	v_lshlrev_b32_e32 v180, 16, v224
	v_and_b32_e32 v181, 0xffff0000, v224
	v_lshlrev_b32_e32 v182, 16, v225
	v_and_b32_e32 v183, 0xffff0000, v225
	v_lshlrev_b32_e32 v184, 16, v226
	v_and_b32_e32 v185, 0xffff0000, v226
	v_lshlrev_b32_e32 v186, 16, v227
	v_and_b32_e32 v187, 0xffff0000, v227
	v_pk_fma_f32 v[36:37], v[36:37], v[204:205], v[180:181]
	v_pk_fma_f32 v[38:39], v[38:39], v[206:207], v[182:183]
	v_pk_fma_f32 v[32:33], v[32:33], v[208:209], v[184:185]
	v_pk_fma_f32 v[34:35], v[34:35], v[210:211], v[186:187]
	v_cvt_pk_bf16_f32 v35, v34, v35
	v_cvt_pk_bf16_f32 v34, v32, v33
	v_cvt_pk_bf16_f32 v33, v38, v39
	v_cvt_pk_bf16_f32 v32, v36, v37
	v_add_u32_e32 v151, 0x90000, v148
	global_store_dwordx4 v151, v[32:35], s[74:75] offset:256
	v_lshlrev_b32_e32 v180, 16, v164
	v_and_b32_e32 v181, 0xffff0000, v164
	v_lshlrev_b32_e32 v182, 16, v165
	v_and_b32_e32 v183, 0xffff0000, v165
	v_lshlrev_b32_e32 v184, 16, v166
	v_and_b32_e32 v185, 0xffff0000, v166
	v_lshlrev_b32_e32 v186, 16, v167
	v_and_b32_e32 v187, 0xffff0000, v167
	v_pk_fma_f32 v[28:29], v[28:29], v[196:197], v[180:181]
	v_pk_fma_f32 v[30:31], v[30:31], v[198:199], v[182:183]
	v_pk_fma_f32 v[24:25], v[24:25], v[200:201], v[184:185]
	v_pk_fma_f32 v[26:27], v[26:27], v[202:203], v[186:187]
	v_cvt_pk_bf16_f32 v27, v26, v27
	v_cvt_pk_bf16_f32 v26, v24, v25
	v_cvt_pk_bf16_f32 v25, v30, v31
	v_cvt_pk_bf16_f32 v24, v28, v29
	v_add_u32_e32 v151, 0xa0000, v148
	global_store_dwordx4 v151, v[24:27], s[74:75]
	v_lshlrev_b32_e32 v180, 16, v168
	v_and_b32_e32 v181, 0xffff0000, v168
	v_lshlrev_b32_e32 v182, 16, v169
	v_and_b32_e32 v183, 0xffff0000, v169
	v_lshlrev_b32_e32 v184, 16, v170
	v_and_b32_e32 v185, 0xffff0000, v170
	v_lshlrev_b32_e32 v186, 16, v171
	v_and_b32_e32 v187, 0xffff0000, v171
	v_pk_fma_f32 v[20:21], v[20:21], v[204:205], v[180:181]
	v_pk_fma_f32 v[22:23], v[22:23], v[206:207], v[182:183]
	v_pk_fma_f32 v[16:17], v[16:17], v[208:209], v[184:185]
	v_pk_fma_f32 v[18:19], v[18:19], v[210:211], v[186:187]
	v_cvt_pk_bf16_f32 v19, v18, v19
	v_cvt_pk_bf16_f32 v18, v16, v17
	v_cvt_pk_bf16_f32 v17, v22, v23
	v_cvt_pk_bf16_f32 v16, v20, v21
	v_add_u32_e32 v151, 0xa0000, v148
	global_store_dwordx4 v151, v[16:19], s[74:75] offset:256
	v_lshlrev_b32_e32 v180, 16, v172
	v_and_b32_e32 v181, 0xffff0000, v172
	v_lshlrev_b32_e32 v182, 16, v173
	v_and_b32_e32 v183, 0xffff0000, v173
	v_lshlrev_b32_e32 v184, 16, v174
	v_and_b32_e32 v185, 0xffff0000, v174
	v_lshlrev_b32_e32 v186, 16, v175
	v_and_b32_e32 v187, 0xffff0000, v175
	v_pk_fma_f32 v[12:13], v[12:13], v[196:197], v[180:181]
	v_pk_fma_f32 v[14:15], v[14:15], v[198:199], v[182:183]
	v_pk_fma_f32 v[8:9], v[8:9], v[200:201], v[184:185]
	v_pk_fma_f32 v[10:11], v[10:11], v[202:203], v[186:187]
	v_cvt_pk_bf16_f32 v11, v10, v11
	v_cvt_pk_bf16_f32 v10, v8, v9
	v_cvt_pk_bf16_f32 v9, v14, v15
	v_cvt_pk_bf16_f32 v8, v12, v13
	v_add_u32_e32 v151, 0xb0000, v148
	global_store_dwordx4 v151, v[8:11], s[74:75]
	v_lshlrev_b32_e32 v180, 16, v176
	v_and_b32_e32 v181, 0xffff0000, v176
	v_lshlrev_b32_e32 v182, 16, v177
	v_and_b32_e32 v183, 0xffff0000, v177
	v_lshlrev_b32_e32 v184, 16, v178
	v_and_b32_e32 v185, 0xffff0000, v178
	v_lshlrev_b32_e32 v186, 16, v179
	v_and_b32_e32 v187, 0xffff0000, v179
	v_pk_fma_f32 v[4:5], v[4:5], v[204:205], v[180:181]
	v_pk_fma_f32 v[6:7], v[6:7], v[206:207], v[182:183]
	v_pk_fma_f32 v[0:1], v[0:1], v[208:209], v[184:185]
	v_pk_fma_f32 v[2:3], v[2:3], v[210:211], v[186:187]
	v_cvt_pk_bf16_f32 v3, v2, v3
	v_cvt_pk_bf16_f32 v2, v0, v1
	v_cvt_pk_bf16_f32 v1, v6, v7
	v_cvt_pk_bf16_f32 v0, v4, v5
	v_add_u32_e32 v151, 0xb0000, v148
	global_store_dwordx4 v151, v[0:3], s[74:75] offset:256

.LBB0_1402:
	ds_read_b128 v[154:157], v151
	ds_read_b128 v[158:161], v151 offset:1024
	ds_read_b128 v[162:165], v151 offset:2048
	ds_read_b128 v[166:169], v151 offset:3072
	s_add_u32 s20, s26, 0xfff80080
	s_addc_u32 s21, s27, -1
	s_cmp_eq_u32 s52, 28
	s_cselect_b32 s21, s15, s21
	s_cselect_b32 s20, s48, s20
	s_cselect_b32 s37, s11, s51
	s_cselect_b32 s36, s49, s50
	v_lshl_add_u64 v[148:149], s[26:27], 0, v[136:137]
	s_add_i32 m0, s25, 0xc000
	ds_read_b128 v[170:173], v152
	ds_read_b128 v[174:177], v152 offset:1024
	ds_read_b128 v[178:181], v152 offset:2048
	ds_read_b128 v[182:185], v152 offset:3072
	ds_read_b128 v[186:189], v152 offset:4096
	ds_read_b128 v[196:199], v152 offset:5120
	ds_read_b128 v[200:203], v152 offset:6144
	ds_read_b128 v[204:207], v152 offset:7168
	global_load_lds_dwordx4 v[148:149], off
	v_lshl_add_u64 v[148:149], s[26:27], 0, v[138:139]
	s_add_i32 m0, s25, 0xe000
	s_nop 0
	global_load_lds_dwordx4 v[148:149], off
	s_waitcnt lgkmcnt(8)
	s_barrier
	s_waitcnt lgkmcnt(0)
	s_setprio 1
	v_mfma_f32_16x16x32_bf16 v[124:127], v[154:157], v[170:173], v[124:127]
	v_mfma_f32_16x16x32_bf16 v[120:123], v[162:165], v[170:173], v[120:123]
	v_mfma_f32_16x16x32_bf16 v[108:111], v[154:157], v[178:181], v[108:111]
	v_mfma_f32_16x16x32_bf16 v[104:107], v[162:165], v[178:181], v[104:107]
	v_mfma_f32_16x16x32_bf16 v[92:95], v[154:157], v[186:189], v[92:95]
	v_mfma_f32_16x16x32_bf16 v[88:91], v[162:165], v[186:189], v[88:91]
	v_mfma_f32_16x16x32_bf16 v[76:79], v[154:157], v[200:203], v[76:79]
	v_mfma_f32_16x16x32_bf16 v[72:75], v[162:165], v[200:203], v[72:75]
	v_mfma_f32_16x16x32_bf16 v[124:127], v[158:161], v[174:177], v[124:127]
	v_mfma_f32_16x16x32_bf16 v[120:123], v[166:169], v[174:177], v[120:123]
	v_mfma_f32_16x16x32_bf16 v[108:111], v[158:161], v[182:185], v[108:111]
	v_mfma_f32_16x16x32_bf16 v[104:107], v[166:169], v[182:185], v[104:107]
	v_mfma_f32_16x16x32_bf16 v[92:95], v[158:161], v[196:199], v[92:95]
	v_mfma_f32_16x16x32_bf16 v[88:91], v[166:169], v[196:199], v[88:91]
	v_mfma_f32_16x16x32_bf16 v[76:79], v[158:161], v[204:207], v[76:79]
	v_mfma_f32_16x16x32_bf16 v[72:75], v[166:169], v[204:207], v[72:75]
	s_setprio 0
	s_barrier
	s_add_i32 s53, s46, s23
	v_lshl_add_u64 v[148:149], s[36:37], 0, v[132:133]
	s_mov_b32 m0, s53
	ds_read_b128 v[208:211], v153
	ds_read_b128 v[212:215], v153 offset:1024
	ds_read_b128 v[216:219], v153 offset:2048
	ds_read_b128 v[220:223], v153 offset:3072
	global_load_lds_dwordx4 v[148:149], off
	v_lshl_add_u64 v[190:191], s[36:37], 0, v[128:129]
	s_add_i32 m0, s53, 0x2000
	s_nop 0
	global_load_lds_dwordx4 v[190:191], off
	s_barrier
	s_waitcnt lgkmcnt(0)
	s_setprio 1
	v_mfma_f32_16x16x32_bf16 v[116:119], v[208:211], v[170:173], v[116:119]
	v_mfma_f32_16x16x32_bf16 v[112:115], v[216:219], v[170:173], v[112:115]
	v_mfma_f32_16x16x32_bf16 v[100:103], v[208:211], v[178:181], v[100:103]
	v_mfma_f32_16x16x32_bf16 v[96:99], v[216:219], v[178:181], v[96:99]
	v_mfma_f32_16x16x32_bf16 v[84:87], v[208:211], v[186:189], v[84:87]
	v_mfma_f32_16x16x32_bf16 v[80:83], v[216:219], v[186:189], v[80:83]
	v_mfma_f32_16x16x32_bf16 v[68:71], v[208:211], v[200:203], v[68:71]
	v_mfma_f32_16x16x32_bf16 v[64:67], v[216:219], v[200:203], v[64:67]
	v_mfma_f32_16x16x32_bf16 v[116:119], v[212:215], v[174:177], v[116:119]
	v_mfma_f32_16x16x32_bf16 v[112:115], v[220:223], v[174:177], v[112:115]
	v_mfma_f32_16x16x32_bf16 v[100:103], v[212:215], v[182:185], v[100:103]
	v_mfma_f32_16x16x32_bf16 v[96:99], v[220:223], v[182:185], v[96:99]
	v_mfma_f32_16x16x32_bf16 v[84:87], v[212:215], v[196:199], v[84:87]
	v_mfma_f32_16x16x32_bf16 v[80:83], v[220:223], v[196:199], v[80:83]
	v_mfma_f32_16x16x32_bf16 v[68:71], v[212:215], v[204:207], v[68:71]
	v_mfma_f32_16x16x32_bf16 v[64:67], v[220:223], v[204:207], v[64:67]
	s_setprio 0
	s_mov_b32 m0, s25
	v_lshl_add_u64 v[224:225], s[20:21], 0, v[134:135]
	s_barrier
	ds_read_b128 v[170:173], v152 offset:16384
	ds_read_b128 v[174:177], v152 offset:17408
	ds_read_b128 v[178:181], v152 offset:18432
	ds_read_b128 v[182:185], v152 offset:19456
	ds_read_b128 v[186:189], v152 offset:20480
	ds_read_b128 v[196:199], v152 offset:21504
	ds_read_b128 v[200:203], v152 offset:22528
	ds_read_b128 v[204:207], v152 offset:23552
	global_load_lds_dwordx4 v[224:225], off
	v_lshl_add_u64 v[226:227], s[20:21], 0, v[130:131]
	s_mov_b32 m0, s35
	s_nop 0
	global_load_lds_dwordx4 v[226:227], off
	s_barrier
	s_waitcnt lgkmcnt(0)
	s_setprio 1
	v_mfma_f32_16x16x32_bf16 v[60:63], v[154:157], v[170:173], v[60:63]
	v_mfma_f32_16x16x32_bf16 v[56:59], v[162:165], v[170:173], v[56:59]
	v_mfma_f32_16x16x32_bf16 v[44:47], v[154:157], v[178:181], v[44:47]
	v_mfma_f32_16x16x32_bf16 v[40:43], v[162:165], v[178:181], v[40:43]
	v_mfma_f32_16x16x32_bf16 v[28:31], v[154:157], v[186:189], v[28:31]
	v_mfma_f32_16x16x32_bf16 v[24:27], v[162:165], v[186:189], v[24:27]
	v_mfma_f32_16x16x32_bf16 v[12:15], v[154:157], v[200:203], v[12:15]
	v_mfma_f32_16x16x32_bf16 v[8:11], v[162:165], v[200:203], v[8:11]
	v_mfma_f32_16x16x32_bf16 v[60:63], v[158:161], v[174:177], v[60:63]
	v_mfma_f32_16x16x32_bf16 v[56:59], v[166:169], v[174:177], v[56:59]
	v_mfma_f32_16x16x32_bf16 v[44:47], v[158:161], v[182:185], v[44:47]
	v_mfma_f32_16x16x32_bf16 v[40:43], v[166:169], v[182:185], v[40:43]
	v_mfma_f32_16x16x32_bf16 v[28:31], v[158:161], v[196:199], v[28:31]
	v_mfma_f32_16x16x32_bf16 v[24:27], v[166:169], v[196:199], v[24:27]
	v_mfma_f32_16x16x32_bf16 v[12:15], v[158:161], v[204:207], v[12:15]
	v_mfma_f32_16x16x32_bf16 v[8:11], v[166:169], v[204:207], v[8:11]
	s_setprio 0
	s_barrier
	s_add_u32 s54, s36, 0x80000
	s_addc_u32 s55, s37, 0
	s_add_i32 s53, s47, s23
	v_lshl_add_u64 v[154:155], s[54:55], 0, v[132:133]
	s_mov_b32 m0, s53
	s_nop 0
	global_load_lds_dwordx4 v[154:155], off
	v_lshl_add_u64 v[154:155], s[54:55], 0, v[128:129]
	s_add_i32 m0, s53, 0x2000
	s_nop 0
	global_load_lds_dwordx4 v[154:155], off
	s_waitcnt vmcnt(6)
	s_barrier
	s_setprio 1
	v_mfma_f32_16x16x32_bf16 v[52:55], v[208:211], v[170:173], v[52:55]
	v_mfma_f32_16x16x32_bf16 v[48:51], v[216:219], v[170:173], v[48:51]
	v_mfma_f32_16x16x32_bf16 v[36:39], v[208:211], v[178:181], v[36:39]
	v_mfma_f32_16x16x32_bf16 v[32:35], v[216:219], v[178:181], v[32:35]
	v_mfma_f32_16x16x32_bf16 v[20:23], v[208:211], v[186:189], v[20:23]
	v_mfma_f32_16x16x32_bf16 v[16:19], v[216:219], v[186:189], v[16:19]
	v_mfma_f32_16x16x32_bf16 v[4:7], v[208:211], v[200:203], v[4:7]
	v_mfma_f32_16x16x32_bf16 v[0:3], v[216:219], v[200:203], v[0:3]
	v_mfma_f32_16x16x32_bf16 v[52:55], v[212:215], v[174:177], v[52:55]
	v_mfma_f32_16x16x32_bf16 v[48:51], v[220:223], v[174:177], v[48:51]
	v_mfma_f32_16x16x32_bf16 v[36:39], v[212:215], v[182:185], v[36:39]
	v_mfma_f32_16x16x32_bf16 v[32:35], v[220:223], v[182:185], v[32:35]
	v_mfma_f32_16x16x32_bf16 v[20:23], v[212:215], v[196:199], v[20:23]
	v_mfma_f32_16x16x32_bf16 v[16:19], v[220:223], v[196:199], v[16:19]
	v_mfma_f32_16x16x32_bf16 v[4:7], v[212:215], v[204:207], v[4:7]
	v_mfma_f32_16x16x32_bf16 v[0:3], v[220:223], v[204:207], v[0:3]
	s_setprio 0
	s_add_i32 s53, 0, 0x18000
	v_add_u32_e32 v166, s53, v147
	s_barrier
	ds_read_b128 v[154:157], v166
	ds_read_b128 v[158:161], v166 offset:1024
	ds_read_b128 v[162:165], v166 offset:2048
	ds_read_b128 v[166:169], v166 offset:3072
	s_add_u32 s20, s20, 0x80000
	s_addc_u32 s21, s21, 0
	s_mov_b32 m0, s38
	v_lshl_add_u64 v[208:209], s[20:21], 0, v[134:135]
	ds_read_b128 v[170:173], v152 offset:32768
	ds_read_b128 v[174:177], v152 offset:33792
	ds_read_b128 v[178:181], v152 offset:34816
	ds_read_b128 v[182:185], v152 offset:35840
	ds_read_b128 v[186:189], v152 offset:36864
	ds_read_b128 v[196:199], v152 offset:37888
	ds_read_b128 v[200:203], v152 offset:38912
	ds_read_b128 v[204:207], v152 offset:39936
	global_load_lds_dwordx4 v[208:209], off
	v_lshl_add_u64 v[208:209], s[20:21], 0, v[130:131]
	s_mov_b32 m0, s39
	s_nop 0
	global_load_lds_dwordx4 v[208:209], off
	s_waitcnt lgkmcnt(8)
	s_barrier
	s_waitcnt lgkmcnt(0)
	s_setprio 1
	v_mfma_f32_16x16x32_bf16 v[124:127], v[154:157], v[170:173], v[124:127]
	v_mfma_f32_16x16x32_bf16 v[120:123], v[162:165], v[170:173], v[120:123]
	v_mfma_f32_16x16x32_bf16 v[108:111], v[154:157], v[178:181], v[108:111]
	v_mfma_f32_16x16x32_bf16 v[104:107], v[162:165], v[178:181], v[104:107]
	v_mfma_f32_16x16x32_bf16 v[92:95], v[154:157], v[186:189], v[92:95]
	v_mfma_f32_16x16x32_bf16 v[88:91], v[162:165], v[186:189], v[88:91]
	v_mfma_f32_16x16x32_bf16 v[76:79], v[154:157], v[200:203], v[76:79]
	v_mfma_f32_16x16x32_bf16 v[72:75], v[162:165], v[200:203], v[72:75]
	v_mfma_f32_16x16x32_bf16 v[124:127], v[158:161], v[174:177], v[124:127]
	v_mfma_f32_16x16x32_bf16 v[120:123], v[166:169], v[174:177], v[120:123]
	v_mfma_f32_16x16x32_bf16 v[108:111], v[158:161], v[182:185], v[108:111]
	v_mfma_f32_16x16x32_bf16 v[104:107], v[166:169], v[182:185], v[104:107]
	v_mfma_f32_16x16x32_bf16 v[92:95], v[158:161], v[196:199], v[92:95]
	v_mfma_f32_16x16x32_bf16 v[88:91], v[166:169], v[196:199], v[88:91]
	v_mfma_f32_16x16x32_bf16 v[76:79], v[158:161], v[204:207], v[76:79]
	v_mfma_f32_16x16x32_bf16 v[72:75], v[166:169], v[204:207], v[72:75]
	s_setprio 0
	s_barrier
	s_add_i32 s54, 0, 0x1c000
	s_add_i32 s20, s53, s23
	v_add_u32_e32 v193, s54, v147
	v_lshl_add_u64 v[148:149], v[148:149], 0, s[8:9]
	s_mov_b32 m0, s20
	ds_read_b128 v[208:211], v193
	ds_read_b128 v[212:215], v193 offset:1024
	ds_read_b128 v[216:219], v193 offset:2048
	ds_read_b128 v[220:223], v193 offset:3072
	global_load_lds_dwordx4 v[148:149], off
	v_lshl_add_u64 v[148:149], v[190:191], 0, s[8:9]
	s_add_i32 m0, s20, 0x2000
	s_nop 0
	global_load_lds_dwordx4 v[148:149], off
	s_barrier
	s_waitcnt lgkmcnt(0)
	s_setprio 1
	v_mfma_f32_16x16x32_bf16 v[116:119], v[208:211], v[170:173], v[116:119]
	v_mfma_f32_16x16x32_bf16 v[112:115], v[216:219], v[170:173], v[112:115]
	v_mfma_f32_16x16x32_bf16 v[100:103], v[208:211], v[178:181], v[100:103]
	v_mfma_f32_16x16x32_bf16 v[96:99], v[216:219], v[178:181], v[96:99]
	v_mfma_f32_16x16x32_bf16 v[84:87], v[208:211], v[186:189], v[84:87]
	v_mfma_f32_16x16x32_bf16 v[80:83], v[216:219], v[186:189], v[80:83]
	v_mfma_f32_16x16x32_bf16 v[68:71], v[208:211], v[200:203], v[68:71]
	v_mfma_f32_16x16x32_bf16 v[64:67], v[216:219], v[200:203], v[64:67]
	v_mfma_f32_16x16x32_bf16 v[116:119], v[212:215], v[174:177], v[116:119]
	v_mfma_f32_16x16x32_bf16 v[112:115], v[220:223], v[174:177], v[112:115]
	v_mfma_f32_16x16x32_bf16 v[100:103], v[212:215], v[182:185], v[100:103]
	v_mfma_f32_16x16x32_bf16 v[96:99], v[220:223], v[182:185], v[96:99]
	v_mfma_f32_16x16x32_bf16 v[84:87], v[212:215], v[196:199], v[84:87]
	v_mfma_f32_16x16x32_bf16 v[80:83], v[220:223], v[196:199], v[80:83]
	v_mfma_f32_16x16x32_bf16 v[68:71], v[212:215], v[204:207], v[68:71]
	v_mfma_f32_16x16x32_bf16 v[64:67], v[220:223], v[204:207], v[64:67]
	s_setprio 0
	s_mov_b32 m0, s41
	v_lshl_add_u64 v[148:149], v[224:225], 0, s[8:9]
	s_barrier
	ds_read_b128 v[170:173], v152 offset:49152
	ds_read_b128 v[174:177], v152 offset:50176
	ds_read_b128 v[178:181], v152 offset:51200
	ds_read_b128 v[182:185], v152 offset:52224
	ds_read_b128 v[186:189], v152 offset:53248
	ds_read_b128 v[196:199], v152 offset:54272
	ds_read_b128 v[200:203], v152 offset:55296
	ds_read_b128 v[204:207], v152 offset:56320
	global_load_lds_dwordx4 v[148:149], off
	v_lshl_add_u64 v[148:149], v[226:227], 0, s[8:9]
	s_mov_b32 m0, s44
	s_nop 0
	global_load_lds_dwordx4 v[148:149], off
	s_barrier
	s_waitcnt lgkmcnt(0)
	s_setprio 1
	v_mfma_f32_16x16x32_bf16 v[60:63], v[154:157], v[170:173], v[60:63]
	v_mfma_f32_16x16x32_bf16 v[56:59], v[162:165], v[170:173], v[56:59]
	v_mfma_f32_16x16x32_bf16 v[44:47], v[154:157], v[178:181], v[44:47]
	v_mfma_f32_16x16x32_bf16 v[40:43], v[162:165], v[178:181], v[40:43]
	v_mfma_f32_16x16x32_bf16 v[28:31], v[154:157], v[186:189], v[28:31]
	v_mfma_f32_16x16x32_bf16 v[24:27], v[162:165], v[186:189], v[24:27]
	v_mfma_f32_16x16x32_bf16 v[12:15], v[154:157], v[200:203], v[12:15]
	v_mfma_f32_16x16x32_bf16 v[8:11], v[162:165], v[200:203], v[8:11]
	v_mfma_f32_16x16x32_bf16 v[60:63], v[158:161], v[174:177], v[60:63]
	v_mfma_f32_16x16x32_bf16 v[56:59], v[166:169], v[174:177], v[56:59]
	v_mfma_f32_16x16x32_bf16 v[44:47], v[158:161], v[182:185], v[44:47]
	v_mfma_f32_16x16x32_bf16 v[40:43], v[166:169], v[182:185], v[40:43]
	v_mfma_f32_16x16x32_bf16 v[28:31], v[158:161], v[196:199], v[28:31]
	v_mfma_f32_16x16x32_bf16 v[24:27], v[166:169], v[196:199], v[24:27]
	v_mfma_f32_16x16x32_bf16 v[12:15], v[158:161], v[204:207], v[12:15]
	v_mfma_f32_16x16x32_bf16 v[8:11], v[166:169], v[204:207], v[8:11]
	s_setprio 0
	s_barrier
	s_add_u32 s20, s36, 0x80080
	s_addc_u32 s21, s37, 0
	s_add_i32 s36, s54, s23
	v_lshl_add_u64 v[148:149], s[20:21], 0, v[132:133]
	s_mov_b32 m0, s36
	s_nop 0
	global_load_lds_dwordx4 v[148:149], off
	v_lshl_add_u64 v[148:149], s[20:21], 0, v[128:129]
	s_add_i32 m0, s36, 0x2000
	s_nop 0
	global_load_lds_dwordx4 v[148:149], off
	s_waitcnt vmcnt(6)
	s_barrier
	s_setprio 1
	v_mfma_f32_16x16x32_bf16 v[52:55], v[208:211], v[170:173], v[52:55]
	v_mfma_f32_16x16x32_bf16 v[48:51], v[216:219], v[170:173], v[48:51]
	v_mfma_f32_16x16x32_bf16 v[36:39], v[208:211], v[178:181], v[36:39]
	v_mfma_f32_16x16x32_bf16 v[32:35], v[216:219], v[178:181], v[32:35]
	v_mfma_f32_16x16x32_bf16 v[20:23], v[208:211], v[186:189], v[20:23]
	v_mfma_f32_16x16x32_bf16 v[16:19], v[216:219], v[186:189], v[16:19]
	v_mfma_f32_16x16x32_bf16 v[4:7], v[208:211], v[200:203], v[4:7]
	v_mfma_f32_16x16x32_bf16 v[0:3], v[216:219], v[200:203], v[0:3]
	v_mfma_f32_16x16x32_bf16 v[52:55], v[212:215], v[174:177], v[52:55]
	v_mfma_f32_16x16x32_bf16 v[48:51], v[220:223], v[174:177], v[48:51]
	v_mfma_f32_16x16x32_bf16 v[36:39], v[212:215], v[182:185], v[36:39]
	v_mfma_f32_16x16x32_bf16 v[32:35], v[220:223], v[182:185], v[32:35]
	v_mfma_f32_16x16x32_bf16 v[20:23], v[212:215], v[196:199], v[20:23]
	v_mfma_f32_16x16x32_bf16 v[16:19], v[220:223], v[196:199], v[16:19]
	v_mfma_f32_16x16x32_bf16 v[4:7], v[212:215], v[204:207], v[4:7]
	v_mfma_f32_16x16x32_bf16 v[0:3], v[220:223], v[204:207], v[0:3]
	s_setprio 0
	s_add_i32 s52, s52, 2
	s_add_u32 s26, s26, 0x100
	s_addc_u32 s27, s27, 0
	s_add_u32 s50, s50, 0x100
	s_addc_u32 s51, s51, 0
	s_cmp_gt_u32 s52, 29
	s_cbranch_scc0 .Ldup_nl_mlpin1
	s_cmpk_gt_u32 s12, 0xff
	s_cbranch_scc0 .Ldup_nl_mlpin1
	v_lshl_add_u32 v148, s24, 8, v145
	v_max_f32_e32 v124, v124, v124
	v_max_f32_e32 v120, v120, v120
	v_ashrrev_i32_e32 v149, 31, v148
	v_max_f32_e32 v124, 0, v124
	v_max_f32_e32 v120, 0, v120
	v_lshlrev_b64 v[156:157], 14, v[148:149]
	v_mul_f32_e32 v149, v124, v124
	v_mul_f32_e32 v124, v120, v120
	v_max_f32_e32 v120, v125, v125
	v_max_f32_e32 v121, v121, v121
	v_max_f32_e32 v120, 0, v120
	v_max_f32_e32 v121, 0, v121
	v_mul_f32_e32 v158, v120, v120
	v_mul_f32_e32 v159, v121, v121
	v_max_f32_e32 v120, v126, v126
	v_max_f32_e32 v121, v122, v122
	v_max_f32_e32 v120, 0, v120
	v_max_f32_e32 v121, 0, v121
	v_lshl_or_b32 v154, s33, 8, v150
	v_mul_f32_e32 v160, v120, v120
	v_mul_f32_e32 v125, v121, v121
	v_max_f32_e32 v120, v127, v127
	v_max_f32_e32 v121, v123, v123
	v_max_f32_e32 v116, v116, v116
	v_max_f32_e32 v112, v112, v112
	v_max_f32_e32 v117, v117, v117
	v_max_f32_e32 v113, v113, v113
	v_max_f32_e32 v118, v118, v118
	v_max_f32_e32 v114, v114, v114
	v_max_f32_e32 v119, v119, v119
	v_max_f32_e32 v115, v115, v115
	v_ashrrev_i32_e32 v155, 31, v154
	v_max_f32_e32 v120, 0, v120
	v_max_f32_e32 v121, 0, v121
	v_max_f32_e32 v116, 0, v116
	v_max_f32_e32 v112, 0, v112
	v_max_f32_e32 v117, 0, v117
	v_max_f32_e32 v113, 0, v113
	v_max_f32_e32 v118, 0, v118
	v_max_f32_e32 v114, 0, v114
	v_max_f32_e32 v119, 0, v119
	v_max_f32_e32 v115, 0, v115
	v_mul_f32_e32 v161, v120, v120
	v_mul_f32_e32 v162, v121, v121
	v_lshl_add_u64 v[122:123], s[28:29], 0, v[156:157]
	v_lshlrev_b64 v[120:121], 1, v[154:155]
	v_mul_f32_e32 v116, v116, v116
	v_mul_f32_e32 v112, v112, v112
	v_mul_f32_e32 v117, v117, v117
	v_mul_f32_e32 v113, v113, v113
	v_mul_f32_e32 v118, v118, v118
	v_mul_f32_e32 v114, v114, v114
	v_mul_f32_e32 v119, v119, v119
	v_mul_f32_e32 v115, v115, v115
	v_max_f32_e32 v104, v104, v104
	v_lshl_add_u64 v[126:127], v[122:123], 0, v[120:121]
	v_cvt_pk_bf16_f32 v115, v114, v115
	v_cvt_pk_bf16_f32 v114, v112, v113
	v_cvt_pk_bf16_f32 v113, v118, v119
	v_cvt_pk_bf16_f32 v112, v116, v117
	v_max_f32_e32 v104, 0, v104
	global_store_dwordx4 v[126:127], v[112:115], off offset:256
	v_max_f32_e32 v105, v105, v105
	v_max_f32_e32 v105, 0, v105
	v_mul_f32_e32 v115, v104, v104
	v_max_f32_e32 v104, v109, v109
	v_max_f32_e32 v104, 0, v104
	v_mul_f32_e32 v116, v104, v104
	v_mul_f32_e32 v117, v105, v105
	v_max_f32_e32 v104, v110, v110
	v_max_f32_e32 v105, v106, v106
	v_or_b32_e32 v112, 16, v148
	v_max_f32_e32 v104, 0, v104
	v_max_f32_e32 v105, 0, v105
	v_ashrrev_i32_e32 v113, 31, v112
	v_mul_f32_e32 v110, v104, v104
	v_mul_f32_e32 v106, v105, v105
	v_max_f32_e32 v104, v111, v111
	v_max_f32_e32 v105, v107, v107
	v_max_f32_e32 v100, v100, v100
	v_max_f32_e32 v96, v96, v96
	v_max_f32_e32 v101, v101, v101
	v_max_f32_e32 v97, v97, v97
	v_max_f32_e32 v102, v102, v102
	v_max_f32_e32 v98, v98, v98
	v_max_f32_e32 v103, v103, v103
	v_max_f32_e32 v99, v99, v99
	v_lshlrev_b64 v[112:113], 14, v[112:113]
	v_max_f32_e32 v108, v108, v108
	v_max_f32_e32 v104, 0, v104
	v_max_f32_e32 v105, 0, v105
	v_max_f32_e32 v100, 0, v100
	v_max_f32_e32 v96, 0, v96
	v_max_f32_e32 v101, 0, v101
	v_max_f32_e32 v97, 0, v97
	v_max_f32_e32 v102, 0, v102
	v_max_f32_e32 v98, 0, v98
	v_max_f32_e32 v103, 0, v103
	v_max_f32_e32 v99, 0, v99
	v_max_f32_e32 v108, 0, v108
	v_mul_f32_e32 v111, v104, v104
	v_mul_f32_e32 v107, v105, v105
	v_lshl_add_u64 v[104:105], s[28:29], 0, v[112:113]
	v_mul_f32_e32 v100, v100, v100
	v_mul_f32_e32 v96, v96, v96
	v_mul_f32_e32 v101, v101, v101
	v_mul_f32_e32 v97, v97, v97
	v_mul_f32_e32 v102, v102, v102
	v_mul_f32_e32 v98, v98, v98
	v_mul_f32_e32 v103, v103, v103
	v_mul_f32_e32 v99, v99, v99
	v_max_f32_e32 v88, v88, v88
	v_mul_f32_e32 v114, v108, v108
	v_lshl_add_u64 v[108:109], v[104:105], 0, v[120:121]
	v_cvt_pk_bf16_f32 v99, v98, v99
	v_cvt_pk_bf16_f32 v98, v96, v97
	v_cvt_pk_bf16_f32 v97, v102, v103
	v_cvt_pk_bf16_f32 v96, v100, v101
	v_max_f32_e32 v88, 0, v88
	global_store_dwordx4 v[108:109], v[96:99], off offset:256
	v_max_f32_e32 v89, v89, v89
	v_max_f32_e32 v89, 0, v89
	v_mul_f32_e32 v99, v88, v88
	v_max_f32_e32 v88, v93, v93
	v_max_f32_e32 v88, 0, v88
	v_mul_f32_e32 v100, v88, v88
	v_mul_f32_e32 v101, v89, v89
	v_max_f32_e32 v88, v94, v94
	v_max_f32_e32 v89, v90, v90
	v_or_b32_e32 v96, 32, v148
	v_max_f32_e32 v88, 0, v88
	v_max_f32_e32 v89, 0, v89
	v_ashrrev_i32_e32 v97, 31, v96
	v_mul_f32_e32 v94, v88, v88
	v_mul_f32_e32 v90, v89, v89
	v_max_f32_e32 v88, v95, v95
	v_max_f32_e32 v89, v91, v91
	v_max_f32_e32 v84, v84, v84
	v_max_f32_e32 v80, v80, v80
	v_max_f32_e32 v85, v85, v85
	v_max_f32_e32 v81, v81, v81
	v_max_f32_e32 v86, v86, v86
	v_max_f32_e32 v82, v82, v82
	v_max_f32_e32 v87, v87, v87
	v_max_f32_e32 v83, v83, v83
	v_lshlrev_b64 v[96:97], 14, v[96:97]
	v_max_f32_e32 v92, v92, v92
	v_max_f32_e32 v88, 0, v88
	v_max_f32_e32 v89, 0, v89
	v_max_f32_e32 v84, 0, v84
	v_max_f32_e32 v80, 0, v80
	v_max_f32_e32 v85, 0, v85
	v_max_f32_e32 v81, 0, v81
	v_max_f32_e32 v86, 0, v86
	v_max_f32_e32 v82, 0, v82
	v_max_f32_e32 v87, 0, v87
	v_max_f32_e32 v83, 0, v83
	v_max_f32_e32 v92, 0, v92
	v_mul_f32_e32 v95, v88, v88
	v_mul_f32_e32 v91, v89, v89
	v_lshl_add_u64 v[88:89], s[28:29], 0, v[96:97]
	v_mul_f32_e32 v84, v84, v84
	v_mul_f32_e32 v80, v80, v80
	v_mul_f32_e32 v85, v85, v85
	v_mul_f32_e32 v81, v81, v81
	v_mul_f32_e32 v86, v86, v86
	v_mul_f32_e32 v82, v82, v82
	v_mul_f32_e32 v87, v87, v87
	v_mul_f32_e32 v83, v83, v83
	v_max_f32_e32 v72, v72, v72
	v_mul_f32_e32 v98, v92, v92
	v_lshl_add_u64 v[92:93], v[88:89], 0, v[120:121]
	v_cvt_pk_bf16_f32 v83, v82, v83
	v_cvt_pk_bf16_f32 v82, v80, v81
	v_cvt_pk_bf16_f32 v81, v86, v87
	v_cvt_pk_bf16_f32 v80, v84, v85
	v_max_f32_e32 v72, 0, v72
	global_store_dwordx4 v[92:93], v[80:83], off offset:256
	v_max_f32_e32 v73, v73, v73
	v_max_f32_e32 v73, 0, v73
	v_mul_f32_e32 v83, v72, v72
	v_max_f32_e32 v72, v77, v77
	v_max_f32_e32 v72, 0, v72
	v_mul_f32_e32 v84, v72, v72
	v_mul_f32_e32 v85, v73, v73
	v_max_f32_e32 v72, v78, v78
	v_max_f32_e32 v73, v74, v74
	v_or_b32_e32 v80, 48, v148
	v_max_f32_e32 v72, 0, v72
	v_max_f32_e32 v73, 0, v73
	v_ashrrev_i32_e32 v81, 31, v80
	v_mul_f32_e32 v78, v72, v72
	v_mul_f32_e32 v74, v73, v73
	v_max_f32_e32 v72, v79, v79
	v_max_f32_e32 v73, v75, v75
	v_max_f32_e32 v68, v68, v68
	v_max_f32_e32 v64, v64, v64
	v_max_f32_e32 v69, v69, v69
	v_max_f32_e32 v65, v65, v65
	v_max_f32_e32 v70, v70, v70
	v_max_f32_e32 v66, v66, v66
	v_max_f32_e32 v71, v71, v71
	v_max_f32_e32 v67, v67, v67
	v_lshlrev_b64 v[80:81], 14, v[80:81]
	v_max_f32_e32 v76, v76, v76
	v_max_f32_e32 v72, 0, v72
	v_max_f32_e32 v73, 0, v73
	v_max_f32_e32 v68, 0, v68
	v_max_f32_e32 v64, 0, v64
	v_max_f32_e32 v69, 0, v69
	v_max_f32_e32 v65, 0, v65
	v_max_f32_e32 v70, 0, v70
	v_max_f32_e32 v66, 0, v66
	v_max_f32_e32 v71, 0, v71
	v_max_f32_e32 v67, 0, v67
	v_max_f32_e32 v76, 0, v76
	v_mul_f32_e32 v79, v72, v72
	v_mul_f32_e32 v75, v73, v73
	v_lshl_add_u64 v[72:73], s[28:29], 0, v[80:81]
	v_mul_f32_e32 v68, v68, v68
	v_mul_f32_e32 v64, v64, v64
	v_mul_f32_e32 v69, v69, v69
	v_mul_f32_e32 v65, v65, v65
	v_mul_f32_e32 v70, v70, v70
	v_mul_f32_e32 v66, v66, v66
	v_mul_f32_e32 v71, v71, v71
	v_mul_f32_e32 v67, v67, v67
	v_max_f32_e32 v56, v56, v56
	v_mul_f32_e32 v82, v76, v76
	v_lshl_add_u64 v[76:77], v[72:73], 0, v[120:121]
	v_cvt_pk_bf16_f32 v67, v66, v67
	v_cvt_pk_bf16_f32 v66, v64, v65
	v_cvt_pk_bf16_f32 v65, v70, v71
	v_cvt_pk_bf16_f32 v64, v68, v69
	v_max_f32_e32 v56, 0, v56
	global_store_dwordx4 v[76:77], v[64:67], off offset:256
	v_max_f32_e32 v57, v57, v57
	v_max_f32_e32 v57, 0, v57
	v_mul_f32_e32 v67, v56, v56
	v_max_f32_e32 v56, v61, v61
	v_max_f32_e32 v56, 0, v56
	v_mul_f32_e32 v68, v56, v56
	v_mul_f32_e32 v69, v57, v57
	v_max_f32_e32 v56, v62, v62
	v_max_f32_e32 v57, v58, v58
	v_add_u32_e32 v64, 0x80, v148
	v_max_f32_e32 v56, 0, v56
	v_max_f32_e32 v57, 0, v57
	v_ashrrev_i32_e32 v65, 31, v64
	v_mul_f32_e32 v62, v56, v56
	v_mul_f32_e32 v58, v57, v57
	v_max_f32_e32 v56, v63, v63
	v_max_f32_e32 v57, v59, v59
	v_max_f32_e32 v52, v52, v52
	v_max_f32_e32 v48, v48, v48
	v_max_f32_e32 v53, v53, v53
	v_max_f32_e32 v49, v49, v49
	v_max_f32_e32 v54, v54, v54
	v_max_f32_e32 v50, v50, v50
	v_max_f32_e32 v55, v55, v55
	v_max_f32_e32 v51, v51, v51
	v_lshlrev_b64 v[64:65], 14, v[64:65]
	v_max_f32_e32 v60, v60, v60
	v_max_f32_e32 v56, 0, v56
	v_max_f32_e32 v57, 0, v57
	v_max_f32_e32 v52, 0, v52
	v_max_f32_e32 v48, 0, v48
	v_max_f32_e32 v53, 0, v53
	v_max_f32_e32 v49, 0, v49
	v_max_f32_e32 v54, 0, v54
	v_max_f32_e32 v50, 0, v50
	v_max_f32_e32 v55, 0, v55
	v_max_f32_e32 v51, 0, v51
	v_max_f32_e32 v60, 0, v60
	v_mul_f32_e32 v63, v56, v56
	v_mul_f32_e32 v59, v57, v57
	v_lshl_add_u64 v[56:57], s[28:29], 0, v[64:65]
	v_mul_f32_e32 v52, v52, v52
	v_mul_f32_e32 v48, v48, v48
	v_mul_f32_e32 v53, v53, v53
	v_mul_f32_e32 v49, v49, v49
	v_mul_f32_e32 v54, v54, v54
	v_mul_f32_e32 v50, v50, v50
	v_mul_f32_e32 v55, v55, v55
	v_mul_f32_e32 v51, v51, v51
	v_max_f32_e32 v40, v40, v40
	v_mul_f32_e32 v66, v60, v60
	v_lshl_add_u64 v[60:61], v[56:57], 0, v[120:121]
	v_cvt_pk_bf16_f32 v51, v50, v51
	v_cvt_pk_bf16_f32 v50, v48, v49
	v_cvt_pk_bf16_f32 v49, v54, v55
	v_cvt_pk_bf16_f32 v48, v52, v53
	v_max_f32_e32 v40, 0, v40
	global_store_dwordx4 v[60:61], v[48:51], off offset:256
	v_max_f32_e32 v41, v41, v41
	v_max_f32_e32 v41, 0, v41
	v_mul_f32_e32 v51, v40, v40
	v_max_f32_e32 v40, v45, v45
	v_max_f32_e32 v40, 0, v40
	v_mul_f32_e32 v52, v40, v40
	v_mul_f32_e32 v53, v41, v41
	v_max_f32_e32 v40, v46, v46
	v_max_f32_e32 v41, v42, v42
	v_add_u32_e32 v48, 0x90, v148
	v_max_f32_e32 v40, 0, v40
	v_max_f32_e32 v41, 0, v41
	v_ashrrev_i32_e32 v49, 31, v48
	v_mul_f32_e32 v46, v40, v40
	v_mul_f32_e32 v42, v41, v41
	v_max_f32_e32 v40, v47, v47
	v_max_f32_e32 v41, v43, v43
	v_max_f32_e32 v36, v36, v36
	v_max_f32_e32 v32, v32, v32
	v_max_f32_e32 v37, v37, v37
	v_max_f32_e32 v33, v33, v33
	v_max_f32_e32 v38, v38, v38
	v_max_f32_e32 v34, v34, v34
	v_max_f32_e32 v39, v39, v39
	v_max_f32_e32 v35, v35, v35
	v_lshlrev_b64 v[48:49], 14, v[48:49]
	v_max_f32_e32 v44, v44, v44
	v_max_f32_e32 v40, 0, v40
	v_max_f32_e32 v41, 0, v41
	v_max_f32_e32 v36, 0, v36
	v_max_f32_e32 v32, 0, v32
	v_max_f32_e32 v37, 0, v37
	v_max_f32_e32 v33, 0, v33
	v_max_f32_e32 v38, 0, v38
	v_max_f32_e32 v34, 0, v34
	v_max_f32_e32 v39, 0, v39
	v_max_f32_e32 v35, 0, v35
	v_max_f32_e32 v44, 0, v44
	v_mul_f32_e32 v47, v40, v40
	v_mul_f32_e32 v43, v41, v41
	v_lshl_add_u64 v[40:41], s[28:29], 0, v[48:49]
	v_mul_f32_e32 v36, v36, v36
	v_mul_f32_e32 v32, v32, v32
	v_mul_f32_e32 v37, v37, v37
	v_mul_f32_e32 v33, v33, v33
	v_mul_f32_e32 v38, v38, v38
	v_mul_f32_e32 v34, v34, v34
	v_mul_f32_e32 v39, v39, v39
	v_mul_f32_e32 v35, v35, v35
	v_max_f32_e32 v24, v24, v24
	v_mul_f32_e32 v50, v44, v44
	v_lshl_add_u64 v[44:45], v[40:41], 0, v[120:121]
	v_cvt_pk_bf16_f32 v35, v34, v35
	v_cvt_pk_bf16_f32 v34, v32, v33
	v_cvt_pk_bf16_f32 v33, v38, v39
	v_cvt_pk_bf16_f32 v32, v36, v37
	v_max_f32_e32 v24, 0, v24
	global_store_dwordx4 v[44:45], v[32:35], off offset:256
	v_max_f32_e32 v25, v25, v25
	v_max_f32_e32 v25, 0, v25
	v_mul_f32_e32 v35, v24, v24
	v_max_f32_e32 v24, v29, v29
	v_max_f32_e32 v24, 0, v24
	v_mul_f32_e32 v36, v24, v24
	v_mul_f32_e32 v37, v25, v25
	v_max_f32_e32 v24, v30, v30
	v_max_f32_e32 v25, v26, v26
	v_add_u32_e32 v32, 0xa0, v148
	v_max_f32_e32 v24, 0, v24
	v_max_f32_e32 v25, 0, v25
	v_ashrrev_i32_e32 v33, 31, v32
	v_mul_f32_e32 v30, v24, v24
	v_mul_f32_e32 v26, v25, v25
	v_max_f32_e32 v24, v31, v31
	v_max_f32_e32 v25, v27, v27
	v_max_f32_e32 v20, v20, v20
	v_max_f32_e32 v16, v16, v16
	v_max_f32_e32 v21, v21, v21
	v_max_f32_e32 v17, v17, v17
	v_max_f32_e32 v22, v22, v22
	v_max_f32_e32 v18, v18, v18
	v_max_f32_e32 v23, v23, v23
	v_max_f32_e32 v19, v19, v19
	v_lshlrev_b64 v[32:33], 14, v[32:33]
	v_max_f32_e32 v28, v28, v28
	v_max_f32_e32 v24, 0, v24
	v_max_f32_e32 v25, 0, v25
	v_max_f32_e32 v20, 0, v20
	v_max_f32_e32 v16, 0, v16
	v_max_f32_e32 v21, 0, v21
	v_max_f32_e32 v17, 0, v17
	v_max_f32_e32 v22, 0, v22
	v_max_f32_e32 v18, 0, v18
	v_max_f32_e32 v23, 0, v23
	v_max_f32_e32 v19, 0, v19
	v_max_f32_e32 v28, 0, v28
	v_mul_f32_e32 v31, v24, v24
	v_mul_f32_e32 v27, v25, v25
	v_lshl_add_u64 v[24:25], s[28:29], 0, v[32:33]
	v_mul_f32_e32 v20, v20, v20
	v_mul_f32_e32 v16, v16, v16
	v_mul_f32_e32 v21, v21, v21
	v_mul_f32_e32 v17, v17, v17
	v_mul_f32_e32 v22, v22, v22
	v_mul_f32_e32 v18, v18, v18
	v_mul_f32_e32 v23, v23, v23
	v_mul_f32_e32 v19, v19, v19
	v_max_f32_e32 v8, v8, v8
	v_mul_f32_e32 v34, v28, v28
	v_lshl_add_u64 v[28:29], v[24:25], 0, v[120:121]
	v_cvt_pk_bf16_f32 v19, v18, v19
	v_cvt_pk_bf16_f32 v18, v16, v17
	v_cvt_pk_bf16_f32 v17, v22, v23
	v_cvt_pk_bf16_f32 v16, v20, v21
	v_max_f32_e32 v8, 0, v8
	global_store_dwordx4 v[28:29], v[16:19], off offset:256
	v_max_f32_e32 v9, v9, v9
	v_max_f32_e32 v9, 0, v9
	v_mul_f32_e32 v19, v8, v8
	v_max_f32_e32 v8, v13, v13
	v_max_f32_e32 v8, 0, v8
	v_mul_f32_e32 v20, v8, v8
	v_mul_f32_e32 v21, v9, v9
	v_max_f32_e32 v8, v14, v14
	v_max_f32_e32 v9, v10, v10
	v_add_u32_e32 v16, 0xb0, v148
	v_max_f32_e32 v8, 0, v8
	v_max_f32_e32 v9, 0, v9
	v_ashrrev_i32_e32 v17, 31, v16
	v_max_f32_e32 v12, v12, v12
	v_mul_f32_e32 v14, v8, v8
	v_mul_f32_e32 v10, v9, v9
	v_max_f32_e32 v8, v15, v15
	v_max_f32_e32 v9, v11, v11
	v_max_f32_e32 v4, v4, v4
	v_max_f32_e32 v0, v0, v0
	v_max_f32_e32 v5, v5, v5
	v_max_f32_e32 v1, v1, v1
	v_max_f32_e32 v6, v6, v6
	v_max_f32_e32 v2, v2, v2
	v_max_f32_e32 v7, v7, v7
	v_max_f32_e32 v3, v3, v3
	v_lshlrev_b64 v[16:17], 14, v[16:17]
	v_max_f32_e32 v12, 0, v12
	v_max_f32_e32 v8, 0, v8
	v_max_f32_e32 v9, 0, v9
	v_max_f32_e32 v4, 0, v4
	v_max_f32_e32 v0, 0, v0
	v_max_f32_e32 v5, 0, v5
	v_max_f32_e32 v1, 0, v1
	v_max_f32_e32 v6, 0, v6
	v_max_f32_e32 v2, 0, v2
	v_max_f32_e32 v7, 0, v7
	v_max_f32_e32 v3, 0, v3
	v_mul_f32_e32 v18, v12, v12
	v_mul_f32_e32 v15, v8, v8
	v_mul_f32_e32 v11, v9, v9
	v_lshl_add_u64 v[8:9], s[28:29], 0, v[16:17]
	v_mul_f32_e32 v4, v4, v4
	v_mul_f32_e32 v0, v0, v0
	v_mul_f32_e32 v5, v5, v5
	v_mul_f32_e32 v1, v1, v1
	v_mul_f32_e32 v6, v6, v6
	v_mul_f32_e32 v2, v2, v2
	v_mul_f32_e32 v7, v7, v7
	v_mul_f32_e32 v3, v3, v3
	v_cvt_pk_bf16_f32 v125, v125, v162
	v_cvt_pk_bf16_f32 v124, v124, v159
	v_cvt_pk_bf16_f32 v123, v160, v161
	v_cvt_pk_bf16_f32 v122, v149, v158
	v_cvt_pk_bf16_f32 v107, v106, v107
	v_cvt_pk_bf16_f32 v106, v115, v117
	v_cvt_pk_bf16_f32 v105, v110, v111
	v_cvt_pk_bf16_f32 v104, v114, v116
	v_cvt_pk_bf16_f32 v91, v90, v91
	v_cvt_pk_bf16_f32 v90, v99, v101
	v_cvt_pk_bf16_f32 v89, v94, v95
	v_cvt_pk_bf16_f32 v88, v98, v100
	v_cvt_pk_bf16_f32 v75, v74, v75
	v_cvt_pk_bf16_f32 v74, v83, v85
	v_cvt_pk_bf16_f32 v73, v78, v79
	v_cvt_pk_bf16_f32 v72, v82, v84
	v_cvt_pk_bf16_f32 v59, v58, v59
	v_cvt_pk_bf16_f32 v58, v67, v69
	v_cvt_pk_bf16_f32 v57, v62, v63
	v_cvt_pk_bf16_f32 v56, v66, v68
	v_cvt_pk_bf16_f32 v43, v42, v43
	v_cvt_pk_bf16_f32 v42, v51, v53
	v_cvt_pk_bf16_f32 v41, v46, v47
	v_cvt_pk_bf16_f32 v40, v50, v52
	v_cvt_pk_bf16_f32 v27, v26, v27
	v_cvt_pk_bf16_f32 v26, v35, v37
	v_cvt_pk_bf16_f32 v25, v30, v31
	v_cvt_pk_bf16_f32 v24, v34, v36
	v_lshl_add_u64 v[12:13], v[8:9], 0, v[120:121]
	v_cvt_pk_bf16_f32 v11, v10, v11
	v_cvt_pk_bf16_f32 v10, v19, v21
	v_cvt_pk_bf16_f32 v9, v14, v15
	v_cvt_pk_bf16_f32 v8, v18, v20
	v_cvt_pk_bf16_f32 v3, v2, v3
	v_cvt_pk_bf16_f32 v2, v0, v1
	v_cvt_pk_bf16_f32 v1, v6, v7
	v_cvt_pk_bf16_f32 v0, v4, v5
	global_store_dwordx4 v[126:127], v[122:125], off
	global_store_dwordx4 v[108:109], v[104:107], off
	global_store_dwordx4 v[92:93], v[88:91], off
	global_store_dwordx4 v[76:77], v[72:75], off
	global_store_dwordx4 v[60:61], v[56:59], off
	global_store_dwordx4 v[44:45], v[40:43], off
	global_store_dwordx4 v[28:29], v[24:27], off
	global_store_dwordx4 v[12:13], v[8:11], off
	global_store_dwordx4 v[12:13], v[0:3], off offset:256

.LBB0_1433:
	ds_read_b128 v[148:151], v158
	ds_read_b128 v[152:155], v158 offset:1024
	ds_read_b128 v[162:165], v158 offset:2048
	ds_read_b128 v[166:169], v158 offset:3072
	s_add_u32 s20, s26, 0xffe00080
	s_addc_u32 s21, s27, -1
	s_cmpk_eq_i32 s53, 0x7c
	s_cselect_b32 s21, s15, s21
	s_cselect_b32 s20, s49, s20
	s_cselect_b32 s31, s11, s52
	s_cselect_b32 s30, s50, s51
	v_lshl_add_u64 v[204:205], s[26:27], 0, v[136:137]
	s_add_i32 m0, s25, 0xc000
	ds_read_b128 v[170:173], v159
	ds_read_b128 v[174:177], v159 offset:1024
	ds_read_b128 v[178:181], v159 offset:2048
	ds_read_b128 v[182:185], v159 offset:3072
	ds_read_b128 v[186:189], v159 offset:4096
	ds_read_b128 v[190:193], v159 offset:5120
	ds_read_b128 v[196:199], v159 offset:6144
	ds_read_b128 v[200:203], v159 offset:7168
	global_load_lds_dwordx4 v[204:205], off
	v_lshl_add_u64 v[204:205], s[26:27], 0, v[138:139]
	s_add_i32 m0, s25, 0xe000
	s_nop 0
	global_load_lds_dwordx4 v[204:205], off
	s_waitcnt lgkmcnt(8)
	s_barrier
	s_waitcnt lgkmcnt(0)
	s_setprio 1
	v_mfma_f32_16x16x32_bf16 v[124:127], v[148:151], v[170:173], v[124:127]
	v_mfma_f32_16x16x32_bf16 v[120:123], v[162:165], v[170:173], v[120:123]
	v_mfma_f32_16x16x32_bf16 v[108:111], v[148:151], v[178:181], v[108:111]
	v_mfma_f32_16x16x32_bf16 v[104:107], v[162:165], v[178:181], v[104:107]
	v_mfma_f32_16x16x32_bf16 v[92:95], v[148:151], v[186:189], v[92:95]
	v_mfma_f32_16x16x32_bf16 v[88:91], v[162:165], v[186:189], v[88:91]
	v_mfma_f32_16x16x32_bf16 v[76:79], v[148:151], v[196:199], v[76:79]
	v_mfma_f32_16x16x32_bf16 v[72:75], v[162:165], v[196:199], v[72:75]
	v_mfma_f32_16x16x32_bf16 v[124:127], v[152:155], v[174:177], v[124:127]
	v_mfma_f32_16x16x32_bf16 v[120:123], v[166:169], v[174:177], v[120:123]
	v_mfma_f32_16x16x32_bf16 v[108:111], v[152:155], v[182:185], v[108:111]
	v_mfma_f32_16x16x32_bf16 v[104:107], v[166:169], v[182:185], v[104:107]
	v_mfma_f32_16x16x32_bf16 v[92:95], v[152:155], v[190:193], v[92:95]
	v_mfma_f32_16x16x32_bf16 v[88:91], v[166:169], v[190:193], v[88:91]
	v_mfma_f32_16x16x32_bf16 v[76:79], v[152:155], v[200:203], v[76:79]
	v_mfma_f32_16x16x32_bf16 v[72:75], v[166:169], v[200:203], v[72:75]
	s_setprio 0
	s_barrier
	s_add_i32 s54, s45, s23
	v_lshl_add_u64 v[220:221], s[30:31], 0, v[132:133]
	s_mov_b32 m0, s54
	ds_read_b128 v[204:207], v160
	ds_read_b128 v[208:211], v160 offset:1024
	ds_read_b128 v[212:215], v160 offset:2048
	ds_read_b128 v[216:219], v160 offset:3072
	global_load_lds_dwordx4 v[220:221], off
	v_lshl_add_u64 v[222:223], s[30:31], 0, v[128:129]
	s_add_i32 m0, s54, 0x2000
	s_nop 0
	global_load_lds_dwordx4 v[222:223], off
	s_barrier
	s_waitcnt lgkmcnt(0)
	s_setprio 1
	v_mfma_f32_16x16x32_bf16 v[116:119], v[204:207], v[170:173], v[116:119]
	v_mfma_f32_16x16x32_bf16 v[112:115], v[212:215], v[170:173], v[112:115]
	v_mfma_f32_16x16x32_bf16 v[100:103], v[204:207], v[178:181], v[100:103]
	v_mfma_f32_16x16x32_bf16 v[96:99], v[212:215], v[178:181], v[96:99]
	v_mfma_f32_16x16x32_bf16 v[84:87], v[204:207], v[186:189], v[84:87]
	v_mfma_f32_16x16x32_bf16 v[80:83], v[212:215], v[186:189], v[80:83]
	v_mfma_f32_16x16x32_bf16 v[68:71], v[204:207], v[196:199], v[68:71]
	v_mfma_f32_16x16x32_bf16 v[64:67], v[212:215], v[196:199], v[64:67]
	v_mfma_f32_16x16x32_bf16 v[116:119], v[208:211], v[174:177], v[116:119]
	v_mfma_f32_16x16x32_bf16 v[112:115], v[216:219], v[174:177], v[112:115]
	v_mfma_f32_16x16x32_bf16 v[100:103], v[208:211], v[182:185], v[100:103]
	v_mfma_f32_16x16x32_bf16 v[96:99], v[216:219], v[182:185], v[96:99]
	v_mfma_f32_16x16x32_bf16 v[84:87], v[208:211], v[190:193], v[84:87]
	v_mfma_f32_16x16x32_bf16 v[80:83], v[216:219], v[190:193], v[80:83]
	v_mfma_f32_16x16x32_bf16 v[68:71], v[208:211], v[200:203], v[68:71]
	v_mfma_f32_16x16x32_bf16 v[64:67], v[216:219], v[200:203], v[64:67]
	s_setprio 0
	s_mov_b32 m0, s25
	v_lshl_add_u64 v[224:225], s[20:21], 0, v[134:135]
	s_barrier
	ds_read_b128 v[170:173], v159 offset:16384
	ds_read_b128 v[174:177], v159 offset:17408
	ds_read_b128 v[178:181], v159 offset:18432
	ds_read_b128 v[182:185], v159 offset:19456
	ds_read_b128 v[186:189], v159 offset:20480
	ds_read_b128 v[190:193], v159 offset:21504
	ds_read_b128 v[196:199], v159 offset:22528
	ds_read_b128 v[200:203], v159 offset:23552
	global_load_lds_dwordx4 v[224:225], off
	v_lshl_add_u64 v[226:227], s[20:21], 0, v[130:131]
	s_mov_b32 m0, s37
	s_nop 0
	global_load_lds_dwordx4 v[226:227], off
	s_barrier
	s_waitcnt lgkmcnt(0)
	s_setprio 1
	v_mfma_f32_16x16x32_bf16 v[60:63], v[148:151], v[170:173], v[60:63]
	v_mfma_f32_16x16x32_bf16 v[56:59], v[162:165], v[170:173], v[56:59]
	v_mfma_f32_16x16x32_bf16 v[44:47], v[148:151], v[178:181], v[44:47]
	v_mfma_f32_16x16x32_bf16 v[40:43], v[162:165], v[178:181], v[40:43]
	v_mfma_f32_16x16x32_bf16 v[28:31], v[148:151], v[186:189], v[28:31]
	v_mfma_f32_16x16x32_bf16 v[24:27], v[162:165], v[186:189], v[24:27]
	v_mfma_f32_16x16x32_bf16 v[12:15], v[148:151], v[196:199], v[12:15]
	v_mfma_f32_16x16x32_bf16 v[8:11], v[162:165], v[196:199], v[8:11]
	v_mfma_f32_16x16x32_bf16 v[60:63], v[152:155], v[174:177], v[60:63]
	v_mfma_f32_16x16x32_bf16 v[56:59], v[166:169], v[174:177], v[56:59]
	v_mfma_f32_16x16x32_bf16 v[44:47], v[152:155], v[182:185], v[44:47]
	v_mfma_f32_16x16x32_bf16 v[40:43], v[166:169], v[182:185], v[40:43]
	v_mfma_f32_16x16x32_bf16 v[28:31], v[152:155], v[190:193], v[28:31]
	v_mfma_f32_16x16x32_bf16 v[24:27], v[166:169], v[190:193], v[24:27]
	v_mfma_f32_16x16x32_bf16 v[12:15], v[152:155], v[200:203], v[12:15]
	v_mfma_f32_16x16x32_bf16 v[8:11], v[166:169], v[200:203], v[8:11]
	s_setprio 0
	s_barrier
	s_add_u32 s54, s30, 0x200000
	s_addc_u32 s55, s31, 0
	s_add_i32 s56, s47, s23
	v_lshl_add_u64 v[148:149], s[54:55], 0, v[132:133]
	s_mov_b32 m0, s56
	s_nop 0
	global_load_lds_dwordx4 v[148:149], off
	v_lshl_add_u64 v[148:149], s[54:55], 0, v[128:129]
	s_add_i32 m0, s56, 0x2000
	s_nop 0
	global_load_lds_dwordx4 v[148:149], off
	s_waitcnt vmcnt(6)
	s_barrier
	s_setprio 1
	v_mfma_f32_16x16x32_bf16 v[52:55], v[204:207], v[170:173], v[52:55]
	v_mfma_f32_16x16x32_bf16 v[48:51], v[212:215], v[170:173], v[48:51]
	v_mfma_f32_16x16x32_bf16 v[36:39], v[204:207], v[178:181], v[36:39]
	v_mfma_f32_16x16x32_bf16 v[32:35], v[212:215], v[178:181], v[32:35]
	v_mfma_f32_16x16x32_bf16 v[20:23], v[204:207], v[186:189], v[20:23]
	v_mfma_f32_16x16x32_bf16 v[16:19], v[212:215], v[186:189], v[16:19]
	v_mfma_f32_16x16x32_bf16 v[4:7], v[204:207], v[196:199], v[4:7]
	v_mfma_f32_16x16x32_bf16 v[0:3], v[212:215], v[196:199], v[0:3]
	v_mfma_f32_16x16x32_bf16 v[52:55], v[208:211], v[174:177], v[52:55]
	v_mfma_f32_16x16x32_bf16 v[48:51], v[216:219], v[174:177], v[48:51]
	v_mfma_f32_16x16x32_bf16 v[36:39], v[208:211], v[182:185], v[36:39]
	v_mfma_f32_16x16x32_bf16 v[32:35], v[216:219], v[182:185], v[32:35]
	v_mfma_f32_16x16x32_bf16 v[20:23], v[208:211], v[190:193], v[20:23]
	v_mfma_f32_16x16x32_bf16 v[16:19], v[216:219], v[190:193], v[16:19]
	v_mfma_f32_16x16x32_bf16 v[4:7], v[208:211], v[200:203], v[4:7]
	v_mfma_f32_16x16x32_bf16 v[0:3], v[216:219], v[200:203], v[0:3]
	s_setprio 0
	s_add_i32 s54, 0, 0x18000
	v_add_u32_e32 v161, s54, v147
	s_barrier
	ds_read_b128 v[148:151], v161
	ds_read_b128 v[152:155], v161 offset:1024
	ds_read_b128 v[162:165], v161 offset:2048
	ds_read_b128 v[166:169], v161 offset:3072
	s_add_u32 s20, s20, 0x200000
	s_addc_u32 s21, s21, 0
	s_mov_b32 m0, s38
	v_lshl_add_u64 v[204:205], s[20:21], 0, v[134:135]
	ds_read_b128 v[170:173], v159 offset:32768
	ds_read_b128 v[174:177], v159 offset:33792
	ds_read_b128 v[178:181], v159 offset:34816
	ds_read_b128 v[182:185], v159 offset:35840
	ds_read_b128 v[186:189], v159 offset:36864
	ds_read_b128 v[190:193], v159 offset:37888
	ds_read_b128 v[196:199], v159 offset:38912
	ds_read_b128 v[200:203], v159 offset:39936
	global_load_lds_dwordx4 v[204:205], off
	v_lshl_add_u64 v[204:205], s[20:21], 0, v[130:131]
	s_mov_b32 m0, s39
	s_nop 0
	global_load_lds_dwordx4 v[204:205], off
	s_waitcnt lgkmcnt(8)
	s_barrier
	s_waitcnt lgkmcnt(0)
	s_setprio 1
	v_mfma_f32_16x16x32_bf16 v[124:127], v[148:151], v[170:173], v[124:127]
	v_mfma_f32_16x16x32_bf16 v[120:123], v[162:165], v[170:173], v[120:123]
	v_mfma_f32_16x16x32_bf16 v[108:111], v[148:151], v[178:181], v[108:111]
	v_mfma_f32_16x16x32_bf16 v[104:107], v[162:165], v[178:181], v[104:107]
	v_mfma_f32_16x16x32_bf16 v[92:95], v[148:151], v[186:189], v[92:95]
	v_mfma_f32_16x16x32_bf16 v[88:91], v[162:165], v[186:189], v[88:91]
	v_mfma_f32_16x16x32_bf16 v[76:79], v[148:151], v[196:199], v[76:79]
	v_mfma_f32_16x16x32_bf16 v[72:75], v[162:165], v[196:199], v[72:75]
	v_mfma_f32_16x16x32_bf16 v[124:127], v[152:155], v[174:177], v[124:127]
	v_mfma_f32_16x16x32_bf16 v[120:123], v[166:169], v[174:177], v[120:123]
	v_mfma_f32_16x16x32_bf16 v[108:111], v[152:155], v[182:185], v[108:111]
	v_mfma_f32_16x16x32_bf16 v[104:107], v[166:169], v[182:185], v[104:107]
	v_mfma_f32_16x16x32_bf16 v[92:95], v[152:155], v[190:193], v[92:95]
	v_mfma_f32_16x16x32_bf16 v[88:91], v[166:169], v[190:193], v[88:91]
	v_mfma_f32_16x16x32_bf16 v[76:79], v[152:155], v[200:203], v[76:79]
	v_mfma_f32_16x16x32_bf16 v[72:75], v[166:169], v[200:203], v[72:75]
	s_setprio 0
	s_barrier
	s_add_i32 s55, 0, 0x1c000
	s_add_i32 s20, s54, s23
	v_add_u32_e32 v161, s55, v147
	v_lshl_add_u64 v[220:221], v[220:221], 0, s[8:9]
	s_mov_b32 m0, s20
	ds_read_b128 v[204:207], v161
	ds_read_b128 v[208:211], v161 offset:1024
	ds_read_b128 v[212:215], v161 offset:2048
	ds_read_b128 v[216:219], v161 offset:3072
	global_load_lds_dwordx4 v[220:221], off
	v_lshl_add_u64 v[220:221], v[222:223], 0, s[8:9]
	s_add_i32 m0, s20, 0x2000
	s_nop 0
	global_load_lds_dwordx4 v[220:221], off
	s_barrier
	s_waitcnt lgkmcnt(0)
	s_setprio 1
	v_mfma_f32_16x16x32_bf16 v[116:119], v[204:207], v[170:173], v[116:119]
	v_mfma_f32_16x16x32_bf16 v[112:115], v[212:215], v[170:173], v[112:115]
	v_mfma_f32_16x16x32_bf16 v[100:103], v[204:207], v[178:181], v[100:103]
	v_mfma_f32_16x16x32_bf16 v[96:99], v[212:215], v[178:181], v[96:99]
	v_mfma_f32_16x16x32_bf16 v[84:87], v[204:207], v[186:189], v[84:87]
	v_mfma_f32_16x16x32_bf16 v[80:83], v[212:215], v[186:189], v[80:83]
	v_mfma_f32_16x16x32_bf16 v[68:71], v[204:207], v[196:199], v[68:71]
	v_mfma_f32_16x16x32_bf16 v[64:67], v[212:215], v[196:199], v[64:67]
	v_mfma_f32_16x16x32_bf16 v[116:119], v[208:211], v[174:177], v[116:119]
	v_mfma_f32_16x16x32_bf16 v[112:115], v[216:219], v[174:177], v[112:115]
	v_mfma_f32_16x16x32_bf16 v[100:103], v[208:211], v[182:185], v[100:103]
	v_mfma_f32_16x16x32_bf16 v[96:99], v[216:219], v[182:185], v[96:99]
	v_mfma_f32_16x16x32_bf16 v[84:87], v[208:211], v[190:193], v[84:87]
	v_mfma_f32_16x16x32_bf16 v[80:83], v[216:219], v[190:193], v[80:83]
	v_mfma_f32_16x16x32_bf16 v[68:71], v[208:211], v[200:203], v[68:71]
	v_mfma_f32_16x16x32_bf16 v[64:67], v[216:219], v[200:203], v[64:67]
	s_setprio 0
	s_mov_b32 m0, s35
	v_lshl_add_u64 v[220:221], v[224:225], 0, s[8:9]
	s_barrier
	ds_read_b128 v[170:173], v159 offset:49152
	ds_read_b128 v[174:177], v159 offset:50176
	ds_read_b128 v[178:181], v159 offset:51200
	ds_read_b128 v[182:185], v159 offset:52224
	ds_read_b128 v[186:189], v159 offset:53248
	ds_read_b128 v[190:193], v159 offset:54272
	ds_read_b128 v[196:199], v159 offset:55296
	ds_read_b128 v[200:203], v159 offset:56320
	global_load_lds_dwordx4 v[220:221], off
	v_lshl_add_u64 v[220:221], v[226:227], 0, s[8:9]
	s_mov_b32 m0, s41
	s_nop 0
	global_load_lds_dwordx4 v[220:221], off
	s_barrier
	s_waitcnt lgkmcnt(0)
	s_setprio 1
	v_mfma_f32_16x16x32_bf16 v[60:63], v[148:151], v[170:173], v[60:63]
	v_mfma_f32_16x16x32_bf16 v[56:59], v[162:165], v[170:173], v[56:59]
	v_mfma_f32_16x16x32_bf16 v[44:47], v[148:151], v[178:181], v[44:47]
	v_mfma_f32_16x16x32_bf16 v[40:43], v[162:165], v[178:181], v[40:43]
	v_mfma_f32_16x16x32_bf16 v[28:31], v[148:151], v[186:189], v[28:31]
	v_mfma_f32_16x16x32_bf16 v[24:27], v[162:165], v[186:189], v[24:27]
	v_mfma_f32_16x16x32_bf16 v[12:15], v[148:151], v[196:199], v[12:15]
	v_mfma_f32_16x16x32_bf16 v[8:11], v[162:165], v[196:199], v[8:11]
	v_mfma_f32_16x16x32_bf16 v[60:63], v[152:155], v[174:177], v[60:63]
	v_mfma_f32_16x16x32_bf16 v[56:59], v[166:169], v[174:177], v[56:59]
	v_mfma_f32_16x16x32_bf16 v[44:47], v[152:155], v[182:185], v[44:47]
	v_mfma_f32_16x16x32_bf16 v[40:43], v[166:169], v[182:185], v[40:43]
	v_mfma_f32_16x16x32_bf16 v[28:31], v[152:155], v[190:193], v[28:31]
	v_mfma_f32_16x16x32_bf16 v[24:27], v[166:169], v[190:193], v[24:27]
	v_mfma_f32_16x16x32_bf16 v[12:15], v[152:155], v[200:203], v[12:15]
	v_mfma_f32_16x16x32_bf16 v[8:11], v[166:169], v[200:203], v[8:11]
	s_setprio 0
	s_barrier
	s_add_u32 s20, s30, 0x200080
	s_addc_u32 s21, s31, 0
	s_add_i32 s30, s55, s23
	v_lshl_add_u64 v[148:149], s[20:21], 0, v[132:133]
	s_mov_b32 m0, s30
	s_nop 0
	global_load_lds_dwordx4 v[148:149], off
	v_lshl_add_u64 v[148:149], s[20:21], 0, v[128:129]
	s_add_i32 m0, s30, 0x2000
	s_nop 0
	global_load_lds_dwordx4 v[148:149], off
	s_waitcnt vmcnt(6)
	s_barrier
	s_setprio 1
	v_mfma_f32_16x16x32_bf16 v[52:55], v[204:207], v[170:173], v[52:55]
	v_mfma_f32_16x16x32_bf16 v[48:51], v[212:215], v[170:173], v[48:51]
	v_mfma_f32_16x16x32_bf16 v[36:39], v[204:207], v[178:181], v[36:39]
	v_mfma_f32_16x16x32_bf16 v[32:35], v[212:215], v[178:181], v[32:35]
	v_mfma_f32_16x16x32_bf16 v[20:23], v[204:207], v[186:189], v[20:23]
	v_mfma_f32_16x16x32_bf16 v[16:19], v[212:215], v[186:189], v[16:19]
	v_mfma_f32_16x16x32_bf16 v[4:7], v[204:207], v[196:199], v[4:7]
	v_mfma_f32_16x16x32_bf16 v[0:3], v[212:215], v[196:199], v[0:3]
	v_mfma_f32_16x16x32_bf16 v[52:55], v[208:211], v[174:177], v[52:55]
	v_mfma_f32_16x16x32_bf16 v[48:51], v[216:219], v[174:177], v[48:51]
	v_mfma_f32_16x16x32_bf16 v[36:39], v[208:211], v[182:185], v[36:39]
	v_mfma_f32_16x16x32_bf16 v[32:35], v[216:219], v[182:185], v[32:35]
	v_mfma_f32_16x16x32_bf16 v[20:23], v[208:211], v[190:193], v[20:23]
	v_mfma_f32_16x16x32_bf16 v[16:19], v[216:219], v[190:193], v[16:19]
	v_mfma_f32_16x16x32_bf16 v[4:7], v[208:211], v[200:203], v[4:7]
	v_mfma_f32_16x16x32_bf16 v[0:3], v[216:219], v[200:203], v[0:3]
	s_setprio 0
	s_add_i32 s53, s53, 2
	s_add_u32 s26, s26, 0x100
	s_addc_u32 s27, s27, 0
	s_add_u32 s51, s51, 0x100
	s_addc_u32 s52, s52, 0
	s_cmpk_gt_u32 s53, 0x7d
	s_cbranch_scc0 .Lepi_nl_mlpout1
	s_cmp_lg_u32 s34, 64
	s_cbranch_scc1 .Lepi_nl_mlpout1
	s_lshl_b32 s11, s24, 8
	s_add_i32 s11, s11, s34
	v_or_b32_e32 v154, s11, v145
	s_add_i32 s15, s11, 0xffffe000
	v_lshl_or_b32 v150, s33, 8, v157
	s_lshr_b32 s15, s15, 12
	v_lshlrev_b32_e32 v148, 12, v154
	s_add_i32 s15, s15, 1
	s_cmp_gt_i32 s11, s48
	s_cselect_b32 s15, s15, 0
	s_mul_i32 s15, s15, s46
	v_lshl_add_u32 v148, v150, 1, v148
	s_add_u32 s20, s6, s15
	s_addc_u32 s21, s7, 0
	v_lshlrev_b32_e32 v149, 2, v150
	s_nop 0
	global_load_dwordx4 v[196:199], v149, s[20:21]
	global_load_dwordx4 v[200:203], v149, s[20:21] offset:16
	global_load_dwordx4 v[204:207], v149, s[20:21] offset:512
	global_load_dwordx4 v[208:211], v149, s[20:21] offset:528
	global_load_dwordx4 v[212:215], v148, s[74:75]
	global_load_dwordx4 v[216:219], v148, s[74:75] offset:256
	v_add_u32_e32 v151, 0x10000, v148
	global_load_dwordx4 v[220:223], v151, s[74:75]
	global_load_dwordx4 v[224:227], v151, s[74:75] offset:256
	v_add_u32_e32 v151, 0x20000, v148
	global_load_dwordx4 v[164:167], v151, s[74:75]
	global_load_dwordx4 v[168:171], v151, s[74:75] offset:256
	v_add_u32_e32 v151, 0x30000, v148
	global_load_dwordx4 v[172:175], v151, s[74:75]
	global_load_dwordx4 v[176:179], v151, s[74:75] offset:256
	s_waitcnt vmcnt(0)
	v_lshlrev_b32_e32 v180, 16, v212
	v_and_b32_e32 v181, 0xffff0000, v212
	v_lshlrev_b32_e32 v182, 16, v213
	v_and_b32_e32 v183, 0xffff0000, v213
	v_lshlrev_b32_e32 v184, 16, v214
	v_and_b32_e32 v185, 0xffff0000, v214
	v_lshlrev_b32_e32 v186, 16, v215
	v_and_b32_e32 v187, 0xffff0000, v215
	v_pk_fma_f32 v[124:125], v[124:125], v[196:197], v[180:181]
	v_pk_fma_f32 v[126:127], v[126:127], v[198:199], v[182:183]
	v_pk_fma_f32 v[120:121], v[120:121], v[200:201], v[184:185]
	v_pk_fma_f32 v[122:123], v[122:123], v[202:203], v[186:187]
	v_cvt_pk_bf16_f32 v123, v122, v123
	v_cvt_pk_bf16_f32 v122, v120, v121
	v_cvt_pk_bf16_f32 v121, v126, v127
	v_cvt_pk_bf16_f32 v120, v124, v125
	global_store_dwordx4 v148, v[120:123], s[42:43]
	v_lshlrev_b32_e32 v180, 16, v216
	v_and_b32_e32 v181, 0xffff0000, v216
	v_lshlrev_b32_e32 v182, 16, v217
	v_and_b32_e32 v183, 0xffff0000, v217
	v_lshlrev_b32_e32 v184, 16, v218
	v_and_b32_e32 v185, 0xffff0000, v218
	v_lshlrev_b32_e32 v186, 16, v219
	v_and_b32_e32 v187, 0xffff0000, v219
	v_pk_fma_f32 v[116:117], v[116:117], v[204:205], v[180:181]
	v_pk_fma_f32 v[118:119], v[118:119], v[206:207], v[182:183]
	v_pk_fma_f32 v[112:113], v[112:113], v[208:209], v[184:185]
	v_pk_fma_f32 v[114:115], v[114:115], v[210:211], v[186:187]
	v_cvt_pk_bf16_f32 v115, v114, v115
	v_cvt_pk_bf16_f32 v114, v112, v113
	v_cvt_pk_bf16_f32 v113, v118, v119
	v_cvt_pk_bf16_f32 v112, v116, v117
	global_store_dwordx4 v148, v[112:115], s[42:43] offset:256
	v_lshlrev_b32_e32 v180, 16, v220
	v_and_b32_e32 v181, 0xffff0000, v220
	v_lshlrev_b32_e32 v182, 16, v221
	v_and_b32_e32 v183, 0xffff0000, v221
	v_lshlrev_b32_e32 v184, 16, v222
	v_and_b32_e32 v185, 0xffff0000, v222
	v_lshlrev_b32_e32 v186, 16, v223
	v_and_b32_e32 v187, 0xffff0000, v223
	v_pk_fma_f32 v[108:109], v[108:109], v[196:197], v[180:181]
	v_pk_fma_f32 v[110:111], v[110:111], v[198:199], v[182:183]
	v_pk_fma_f32 v[104:105], v[104:105], v[200:201], v[184:185]
	v_pk_fma_f32 v[106:107], v[106:107], v[202:203], v[186:187]
	v_cvt_pk_bf16_f32 v107, v106, v107
	v_cvt_pk_bf16_f32 v106, v104, v105
	v_cvt_pk_bf16_f32 v105, v110, v111
	v_cvt_pk_bf16_f32 v104, v108, v109
	v_add_u32_e32 v151, 0x10000, v148
	global_store_dwordx4 v151, v[104:107], s[42:43]
	v_lshlrev_b32_e32 v180, 16, v224
	v_and_b32_e32 v181, 0xffff0000, v224
	v_lshlrev_b32_e32 v182, 16, v225
	v_and_b32_e32 v183, 0xffff0000, v225
	v_lshlrev_b32_e32 v184, 16, v226
	v_and_b32_e32 v185, 0xffff0000, v226
	v_lshlrev_b32_e32 v186, 16, v227
	v_and_b32_e32 v187, 0xffff0000, v227
	v_pk_fma_f32 v[100:101], v[100:101], v[204:205], v[180:181]
	v_pk_fma_f32 v[102:103], v[102:103], v[206:207], v[182:183]
	v_pk_fma_f32 v[96:97], v[96:97], v[208:209], v[184:185]
	v_pk_fma_f32 v[98:99], v[98:99], v[210:211], v[186:187]
	v_cvt_pk_bf16_f32 v99, v98, v99
	v_cvt_pk_bf16_f32 v98, v96, v97
	v_cvt_pk_bf16_f32 v97, v102, v103
	v_cvt_pk_bf16_f32 v96, v100, v101
	v_add_u32_e32 v151, 0x10000, v148
	global_store_dwordx4 v151, v[96:99], s[42:43] offset:256
	v_add_u32_e32 v151, 0x80000, v148
	global_load_dwordx4 v[212:215], v151, s[74:75]
	global_load_dwordx4 v[216:219], v151, s[74:75] offset:256
	v_add_u32_e32 v151, 0x90000, v148
	global_load_dwordx4 v[220:223], v151, s[74:75]
	global_load_dwordx4 v[224:227], v151, s[74:75] offset:256
	v_lshlrev_b32_e32 v180, 16, v164
	v_and_b32_e32 v181, 0xffff0000, v164
	v_lshlrev_b32_e32 v182, 16, v165
	v_and_b32_e32 v183, 0xffff0000, v165
	v_lshlrev_b32_e32 v184, 16, v166
	v_and_b32_e32 v185, 0xffff0000, v166
	v_lshlrev_b32_e32 v186, 16, v167
	v_and_b32_e32 v187, 0xffff0000, v167
	v_pk_fma_f32 v[92:93], v[92:93], v[196:197], v[180:181]
	v_pk_fma_f32 v[94:95], v[94:95], v[198:199], v[182:183]
	v_pk_fma_f32 v[88:89], v[88:89], v[200:201], v[184:185]
	v_pk_fma_f32 v[90:91], v[90:91], v[202:203], v[186:187]
	v_cvt_pk_bf16_f32 v91, v90, v91
	v_cvt_pk_bf16_f32 v90, v88, v89
	v_cvt_pk_bf16_f32 v89, v94, v95
	v_cvt_pk_bf16_f32 v88, v92, v93
	v_add_u32_e32 v151, 0x20000, v148
	global_store_dwordx4 v151, v[88:91], s[42:43]
	v_lshlrev_b32_e32 v180, 16, v168
	v_and_b32_e32 v181, 0xffff0000, v168
	v_lshlrev_b32_e32 v182, 16, v169
	v_and_b32_e32 v183, 0xffff0000, v169
	v_lshlrev_b32_e32 v184, 16, v170
	v_and_b32_e32 v185, 0xffff0000, v170
	v_lshlrev_b32_e32 v186, 16, v171
	v_and_b32_e32 v187, 0xffff0000, v171
	v_pk_fma_f32 v[84:85], v[84:85], v[204:205], v[180:181]
	v_pk_fma_f32 v[86:87], v[86:87], v[206:207], v[182:183]
	v_pk_fma_f32 v[80:81], v[80:81], v[208:209], v[184:185]
	v_pk_fma_f32 v[82:83], v[82:83], v[210:211], v[186:187]
	v_cvt_pk_bf16_f32 v83, v82, v83
	v_cvt_pk_bf16_f32 v82, v80, v81
	v_cvt_pk_bf16_f32 v81, v86, v87
	v_cvt_pk_bf16_f32 v80, v84, v85
	v_add_u32_e32 v151, 0x20000, v148
	global_store_dwordx4 v151, v[80:83], s[42:43] offset:256
	v_lshlrev_b32_e32 v180, 16, v172
	v_and_b32_e32 v181, 0xffff0000, v172
	v_lshlrev_b32_e32 v182, 16, v173
	v_and_b32_e32 v183, 0xffff0000, v173
	v_lshlrev_b32_e32 v184, 16, v174
	v_and_b32_e32 v185, 0xffff0000, v174
	v_lshlrev_b32_e32 v186, 16, v175
	v_and_b32_e32 v187, 0xffff0000, v175
	v_pk_fma_f32 v[76:77], v[76:77], v[196:197], v[180:181]
	v_pk_fma_f32 v[78:79], v[78:79], v[198:199], v[182:183]
	v_pk_fma_f32 v[72:73], v[72:73], v[200:201], v[184:185]
	v_pk_fma_f32 v[74:75], v[74:75], v[202:203], v[186:187]
	v_cvt_pk_bf16_f32 v75, v74, v75
	v_cvt_pk_bf16_f32 v74, v72, v73
	v_cvt_pk_bf16_f32 v73, v78, v79
	v_cvt_pk_bf16_f32 v72, v76, v77
	v_add_u32_e32 v151, 0x30000, v148
	global_store_dwordx4 v151, v[72:75], s[42:43]
	v_lshlrev_b32_e32 v180, 16, v176
	v_and_b32_e32 v181, 0xffff0000, v176
	v_lshlrev_b32_e32 v182, 16, v177
	v_and_b32_e32 v183, 0xffff0000, v177
	v_lshlrev_b32_e32 v184, 16, v178
	v_and_b32_e32 v185, 0xffff0000, v178
	v_lshlrev_b32_e32 v186, 16, v179
	v_and_b32_e32 v187, 0xffff0000, v179
	v_pk_fma_f32 v[68:69], v[68:69], v[204:205], v[180:181]
	v_pk_fma_f32 v[70:71], v[70:71], v[206:207], v[182:183]
	v_pk_fma_f32 v[64:65], v[64:65], v[208:209], v[184:185]
	v_pk_fma_f32 v[66:67], v[66:67], v[210:211], v[186:187]
	v_cvt_pk_bf16_f32 v67, v66, v67
	v_cvt_pk_bf16_f32 v66, v64, v65
	v_cvt_pk_bf16_f32 v65, v70, v71
	v_cvt_pk_bf16_f32 v64, v68, v69
	v_add_u32_e32 v151, 0x30000, v148
	global_store_dwordx4 v151, v[64:67], s[42:43] offset:256
	v_add_u32_e32 v151, 0xa0000, v148
	global_load_dwordx4 v[164:167], v151, s[74:75]
	global_load_dwordx4 v[168:171], v151, s[74:75] offset:256
	v_add_u32_e32 v151, 0xb0000, v148
	global_load_dwordx4 v[172:175], v151, s[74:75]
	global_load_dwordx4 v[176:179], v151, s[74:75] offset:256
	s_waitcnt vmcnt(0)
	v_lshlrev_b32_e32 v180, 16, v212
	v_and_b32_e32 v181, 0xffff0000, v212
	v_lshlrev_b32_e32 v182, 16, v213
	v_and_b32_e32 v183, 0xffff0000, v213
	v_lshlrev_b32_e32 v184, 16, v214
	v_and_b32_e32 v185, 0xffff0000, v214
	v_lshlrev_b32_e32 v186, 16, v215
	v_and_b32_e32 v187, 0xffff0000, v215
	v_pk_fma_f32 v[60:61], v[60:61], v[196:197], v[180:181]
	v_pk_fma_f32 v[62:63], v[62:63], v[198:199], v[182:183]
	v_pk_fma_f32 v[56:57], v[56:57], v[200:201], v[184:185]
	v_pk_fma_f32 v[58:59], v[58:59], v[202:203], v[186:187]
	v_cvt_pk_bf16_f32 v59, v58, v59
	v_cvt_pk_bf16_f32 v58, v56, v57
	v_cvt_pk_bf16_f32 v57, v62, v63
	v_cvt_pk_bf16_f32 v56, v60, v61
	v_add_u32_e32 v151, 0x80000, v148
	global_store_dwordx4 v151, v[56:59], s[42:43]
	v_lshlrev_b32_e32 v180, 16, v216
	v_and_b32_e32 v181, 0xffff0000, v216
	v_lshlrev_b32_e32 v182, 16, v217
	v_and_b32_e32 v183, 0xffff0000, v217
	v_lshlrev_b32_e32 v184, 16, v218
	v_and_b32_e32 v185, 0xffff0000, v218
	v_lshlrev_b32_e32 v186, 16, v219
	v_and_b32_e32 v187, 0xffff0000, v219
	v_pk_fma_f32 v[52:53], v[52:53], v[204:205], v[180:181]
	v_pk_fma_f32 v[54:55], v[54:55], v[206:207], v[182:183]
	v_pk_fma_f32 v[48:49], v[48:49], v[208:209], v[184:185]
	v_pk_fma_f32 v[50:51], v[50:51], v[210:211], v[186:187]
	v_cvt_pk_bf16_f32 v51, v50, v51
	v_cvt_pk_bf16_f32 v50, v48, v49
	v_cvt_pk_bf16_f32 v49, v54, v55
	v_cvt_pk_bf16_f32 v48, v52, v53
	v_add_u32_e32 v151, 0x80000, v148
	global_store_dwordx4 v151, v[48:51], s[42:43] offset:256
	v_lshlrev_b32_e32 v180, 16, v220
	v_and_b32_e32 v181, 0xffff0000, v220
	v_lshlrev_b32_e32 v182, 16, v221
	v_and_b32_e32 v183, 0xffff0000, v221
	v_lshlrev_b32_e32 v184, 16, v222
	v_and_b32_e32 v185, 0xffff0000, v222
	v_lshlrev_b32_e32 v186, 16, v223
	v_and_b32_e32 v187, 0xffff0000, v223
	v_pk_fma_f32 v[44:45], v[44:45], v[196:197], v[180:181]
	v_pk_fma_f32 v[46:47], v[46:47], v[198:199], v[182:183]
	v_pk_fma_f32 v[40:41], v[40:41], v[200:201], v[184:185]
	v_pk_fma_f32 v[42:43], v[42:43], v[202:203], v[186:187]
	v_cvt_pk_bf16_f32 v43, v42, v43
	v_cvt_pk_bf16_f32 v42, v40, v41
	v_cvt_pk_bf16_f32 v41, v46, v47
	v_cvt_pk_bf16_f32 v40, v44, v45
	v_add_u32_e32 v151, 0x90000, v148
	global_store_dwordx4 v151, v[40:43], s[42:43]
	v_lshlrev_b32_e32 v180, 16, v224
	v_and_b32_e32 v181, 0xffff0000, v224
	v_lshlrev_b32_e32 v182, 16, v225
	v_and_b32_e32 v183, 0xffff0000, v225
	v_lshlrev_b32_e32 v184, 16, v226
	v_and_b32_e32 v185, 0xffff0000, v226
	v_lshlrev_b32_e32 v186, 16, v227
	v_and_b32_e32 v187, 0xffff0000, v227
	v_pk_fma_f32 v[36:37], v[36:37], v[204:205], v[180:181]
	v_pk_fma_f32 v[38:39], v[38:39], v[206:207], v[182:183]
	v_pk_fma_f32 v[32:33], v[32:33], v[208:209], v[184:185]
	v_pk_fma_f32 v[34:35], v[34:35], v[210:211], v[186:187]
	v_cvt_pk_bf16_f32 v35, v34, v35
	v_cvt_pk_bf16_f32 v34, v32, v33
	v_cvt_pk_bf16_f32 v33, v38, v39
	v_cvt_pk_bf16_f32 v32, v36, v37
	v_add_u32_e32 v151, 0x90000, v148
	global_store_dwordx4 v151, v[32:35], s[42:43] offset:256
	v_lshlrev_b32_e32 v180, 16, v164
	v_and_b32_e32 v181, 0xffff0000, v164
	v_lshlrev_b32_e32 v182, 16, v165
	v_and_b32_e32 v183, 0xffff0000, v165
	v_lshlrev_b32_e32 v184, 16, v166
	v_and_b32_e32 v185, 0xffff0000, v166
	v_lshlrev_b32_e32 v186, 16, v167
	v_and_b32_e32 v187, 0xffff0000, v167
	v_pk_fma_f32 v[28:29], v[28:29], v[196:197], v[180:181]
	v_pk_fma_f32 v[30:31], v[30:31], v[198:199], v[182:183]
	v_pk_fma_f32 v[24:25], v[24:25], v[200:201], v[184:185]
	v_pk_fma_f32 v[26:27], v[26:27], v[202:203], v[186:187]
	v_cvt_pk_bf16_f32 v27, v26, v27
	v_cvt_pk_bf16_f32 v26, v24, v25
	v_cvt_pk_bf16_f32 v25, v30, v31
	v_cvt_pk_bf16_f32 v24, v28, v29
	v_add_u32_e32 v151, 0xa0000, v148
	global_store_dwordx4 v151, v[24:27], s[42:43]
	v_lshlrev_b32_e32 v180, 16, v168
	v_and_b32_e32 v181, 0xffff0000, v168
	v_lshlrev_b32_e32 v182, 16, v169
	v_and_b32_e32 v183, 0xffff0000, v169
	v_lshlrev_b32_e32 v184, 16, v170
	v_and_b32_e32 v185, 0xffff0000, v170
	v_lshlrev_b32_e32 v186, 16, v171
	v_and_b32_e32 v187, 0xffff0000, v171
	v_pk_fma_f32 v[20:21], v[20:21], v[204:205], v[180:181]
	v_pk_fma_f32 v[22:23], v[22:23], v[206:207], v[182:183]
	v_pk_fma_f32 v[16:17], v[16:17], v[208:209], v[184:185]
	v_pk_fma_f32 v[18:19], v[18:19], v[210:211], v[186:187]
	v_cvt_pk_bf16_f32 v19, v18, v19
	v_cvt_pk_bf16_f32 v18, v16, v17
	v_cvt_pk_bf16_f32 v17, v22, v23
	v_cvt_pk_bf16_f32 v16, v20, v21
	v_add_u32_e32 v151, 0xa0000, v148
	global_store_dwordx4 v151, v[16:19], s[42:43] offset:256
	v_lshlrev_b32_e32 v180, 16, v172
	v_and_b32_e32 v181, 0xffff0000, v172
	v_lshlrev_b32_e32 v182, 16, v173
	v_and_b32_e32 v183, 0xffff0000, v173
	v_lshlrev_b32_e32 v184, 16, v174
	v_and_b32_e32 v185, 0xffff0000, v174
	v_lshlrev_b32_e32 v186, 16, v175
	v_and_b32_e32 v187, 0xffff0000, v175
	v_pk_fma_f32 v[12:13], v[12:13], v[196:197], v[180:181]
	v_pk_fma_f32 v[14:15], v[14:15], v[198:199], v[182:183]
	v_pk_fma_f32 v[8:9], v[8:9], v[200:201], v[184:185]
	v_pk_fma_f32 v[10:11], v[10:11], v[202:203], v[186:187]
	v_cvt_pk_bf16_f32 v11, v10, v11
	v_cvt_pk_bf16_f32 v10, v8, v9
	v_cvt_pk_bf16_f32 v9, v14, v15
	v_cvt_pk_bf16_f32 v8, v12, v13
	v_add_u32_e32 v151, 0xb0000, v148
	global_store_dwordx4 v151, v[8:11], s[42:43]
	v_lshlrev_b32_e32 v180, 16, v176
	v_and_b32_e32 v181, 0xffff0000, v176
	v_lshlrev_b32_e32 v182, 16, v177
	v_and_b32_e32 v183, 0xffff0000, v177
	v_lshlrev_b32_e32 v184, 16, v178
	v_and_b32_e32 v185, 0xffff0000, v178
	v_lshlrev_b32_e32 v186, 16, v179
	v_and_b32_e32 v187, 0xffff0000, v179
	v_pk_fma_f32 v[4:5], v[4:5], v[204:205], v[180:181]
	v_pk_fma_f32 v[6:7], v[6:7], v[206:207], v[182:183]
	v_pk_fma_f32 v[0:1], v[0:1], v[208:209], v[184:185]
	v_pk_fma_f32 v[2:3], v[2:3], v[210:211], v[186:187]
	v_cvt_pk_bf16_f32 v3, v2, v3
	v_cvt_pk_bf16_f32 v2, v0, v1
	v_cvt_pk_bf16_f32 v1, v6, v7
	v_cvt_pk_bf16_f32 v0, v4, v5
	v_add_u32_e32 v151, 0xb0000, v148
	global_store_dwordx4 v151, v[0:3], s[42:43] offset:256
